# v09 + placeholder s_nops removed wherever no gfx950 wait-state rule needs them (hazard-checked)
# baseline (speedup 1.0000x reference)
.LBB0_529:
	s_or_b64 exec, exec, s[4:5]
	s_and_b32 s1, s51, 0x300
	v_or_b32_sdwa v24, v25, s1 dst_sel:DWORD dst_unused:UNUSED_PAD src0_sel:BYTE_0 src1_sel:DWORD
	v_readlane_b32 s4, v252, 49
	v_lshlrev_b32_e32 v2, 2, v24
	v_mov_b32_e32 v3, v34
	v_readlane_b32 s5, v252, 50
	s_ashr_i32 s1, s0, 31
	s_lshl_b64 s[48:49], s[0:1], 11
	v_lshl_add_u64 v[20:21], s[4:5], 0, v[2:3]
	v_add_co_u32_e32 v6, vcc, 0x1000, v20
	s_nop 0
	global_load_dword v4, v2, s[4:5]
	v_addc_co_u32_e32 v7, vcc, 0, v21, vcc
	v_add_co_u32_e32 v8, vcc, 0x2000, v20
	global_load_dword v6, v[6:7], off
	s_nop 0
	v_addc_co_u32_e32 v9, vcc, 0, v21, vcc
	v_add_co_u32_e32 v10, vcc, 0x3000, v20
	global_load_dword v8, v[8:9], off
	s_nop 0
	v_addc_co_u32_e32 v11, vcc, 0, v21, vcc
	v_add_co_u32_e32 v12, vcc, 0x4000, v20
	global_load_dword v10, v[10:11], off
	s_nop 0
	v_addc_co_u32_e32 v13, vcc, 0, v21, vcc
	global_load_dword v5, v[12:13], off
	v_add_co_u32_e32 v12, vcc, 0x5000, v20
	v_readlane_b32 s4, v252, 51
	s_nop 0
	v_addc_co_u32_e32 v13, vcc, 0, v21, vcc
	global_load_dword v7, v[12:13], off
	v_add_co_u32_e32 v12, vcc, 0x6000, v20
	v_readlane_b32 s0, v252, 35
	s_nop 0
	v_addc_co_u32_e32 v13, vcc, 0, v21, vcc
	global_load_dword v9, v[12:13], off
	v_add_co_u32_e32 v12, vcc, 0x7000, v20
	v_readlane_b32 s5, v252, 52
	s_nop 0
	v_addc_co_u32_e32 v13, vcc, 0, v21, vcc
	global_load_dword v11, v[12:13], off
	v_add_co_u32_e32 v12, vcc, 0x8000, v20
	s_add_u32 s0, s0, s48
	s_nop 0
	v_addc_co_u32_e32 v13, vcc, 0, v21, vcc
	v_add_co_u32_e32 v14, vcc, 0x9000, v20
	global_load_dword v12, v[12:13], off
	s_nop 0
	v_addc_co_u32_e32 v15, vcc, 0, v21, vcc
	v_add_co_u32_e32 v16, vcc, 0xa000, v20
	global_load_dword v14, v[14:15], off
	s_nop 0
	v_addc_co_u32_e32 v17, vcc, 0, v21, vcc
	v_add_co_u32_e32 v18, vcc, 0xb000, v20
	global_load_dword v16, v[16:17], off
	s_nop 0
	v_addc_co_u32_e32 v19, vcc, 0, v21, vcc
	v_add_co_u32_e32 v22, vcc, 0xc000, v20
	global_load_dword v18, v[18:19], off
	s_nop 0
	v_addc_co_u32_e32 v23, vcc, 0, v21, vcc
	global_load_dword v13, v[22:23], off
	v_add_co_u32_e32 v22, vcc, 0xd000, v20
	v_readlane_b32 s1, v252, 36
	s_nop 0
	v_addc_co_u32_e32 v23, vcc, 0, v21, vcc
	global_load_dword v15, v[22:23], off
	v_add_co_u32_e32 v22, vcc, 0xe000, v20
	global_load_dword v26, v2, s[4:5]
	s_nop 0
	v_addc_co_u32_e32 v23, vcc, 0, v21, vcc
	v_add_co_u32_e32 v20, vcc, 0xf000, v20
	s_addc_u32 s1, s1, s49
	s_nop 0
	v_addc_co_u32_e32 v21, vcc, 0, v21, vcc
	v_lshlrev_b32_e32 v2, 1, v24
	global_load_dword v17, v[22:23], off
	global_load_dword v19, v[20:21], off
	v_lshl_add_u64 v[20:21], s[0:1], 0, v[2:3]
	v_readlane_b32 s0, v252, 39
	s_add_u32 s0, s0, s48
	v_readlane_b32 s1, v252, 41
	s_addc_u32 s1, s1, s49
	s_nop 0
	v_lshl_add_u64 v[22:23], s[0:1], 0, v[2:3]
	s_ashr_i32 s0, s55, 3
	s_and_b32 s38, s0, 0xffffffe0
	s_cmp_lt_i32 s38, s73
	s_cselect_b64 s[2:3], -1, 0
	v_writelane_b32 v255, s2, 45
	s_and_b64 s[4:5], s[2:3], exec
	s_cselect_b32 s4, s38, 0
	s_ashr_i32 s5, s4, 31
	v_writelane_b32 v255, s3, 46
	s_lshl_b64 s[2:3], s[4:5], 11
	s_or_b32 s72, s38, 1
	v_writelane_b32 v255, s2, 49
	s_cmp_lt_i32 s72, s73
	s_nop 0
	v_writelane_b32 v255, s3, 50
	s_cselect_b64 s[2:3], -1, 0
	v_writelane_b32 v255, s2, 3
	s_and_b64 s[4:5], s[2:3], exec
	s_cselect_b32 s4, s72, 0
	s_ashr_i32 s5, s4, 31
	v_writelane_b32 v255, s3, 4
	s_lshl_b64 s[2:3], s[4:5], 11
	s_or_b32 s40, s38, 2
	v_writelane_b32 v252, s2, 55
	s_cmp_lt_i32 s40, s73
	s_mov_b32 s58, s40
	v_writelane_b32 v252, s3, 56
	s_cselect_b64 s[2:3], -1, 0
	v_writelane_b32 v254, s2, 21
	s_and_b64 s[4:5], s[2:3], exec
	s_cselect_b32 s4, s40, 0
	s_ashr_i32 s5, s4, 31
	v_writelane_b32 v254, s3, 22
	s_lshl_b64 s[2:3], s[4:5], 11
	s_or_b32 s18, s38, 3
	s_cmp_lt_i32 s18, s73
	s_cselect_b64 s[14:15], -1, 0
	s_and_b64 s[4:5], s[14:15], exec
	s_cselect_b32 s4, s18, 0
	v_writelane_b32 v252, s2, 53
	s_ashr_i32 s5, s4, 31
	s_or_b32 s52, s38, 4
	v_writelane_b32 v252, s3, 54
	s_lshl_b64 s[2:3], s[4:5], 11
	v_writelane_b32 v252, s2, 57
	s_cmp_lt_i32 s52, s73
	s_nop 0
	v_writelane_b32 v252, s3, 58
	s_cselect_b64 s[2:3], -1, 0
	v_writelane_b32 v254, s2, 15
	s_and_b64 s[4:5], s[2:3], exec
	s_cselect_b32 s4, s52, 0
	s_ashr_i32 s5, s4, 31
	v_writelane_b32 v254, s3, 16
	s_lshl_b64 s[2:3], s[4:5], 11
	s_or_b32 s56, s38, 5
	s_cmp_lt_i32 s56, s73
	s_cselect_b64 s[10:11], -1, 0
	s_and_b64 s[4:5], s[10:11], exec
	s_cselect_b32 s4, s56, 0
	v_writelane_b32 v252, s2, 59
	s_ashr_i32 s5, s4, 31
	s_or_b32 s20, s38, 6
	v_writelane_b32 v252, s3, 60
	s_lshl_b64 s[2:3], s[4:5], 11
	s_cmp_lt_i32 s20, s73
	s_cselect_b64 s[12:13], -1, 0
	s_and_b64 s[4:5], s[12:13], exec
	s_cselect_b32 s4, s20, 0
	v_writelane_b32 v252, s2, 61
	s_ashr_i32 s5, s4, 31
	s_or_b32 s60, s38, 7
	v_writelane_b32 v252, s3, 62
	s_lshl_b64 s[2:3], s[4:5], 11
	s_cmp_lt_i32 s60, s73
	s_cselect_b64 s[22:23], -1, 0
	s_and_b64 s[4:5], s[22:23], exec
	s_cselect_b32 s4, s60, 0
	v_writelane_b32 v252, s2, 63
	s_ashr_i32 s5, s4, 31
	s_or_b32 s62, s38, 8
	v_writelane_b32 v255, s3, 0
	s_lshl_b64 s[2:3], s[4:5], 11
	v_writelane_b32 v255, s2, 5
	s_cmp_lt_i32 s62, s73
	v_writelane_b32 v252, s58, 33
	v_writelane_b32 v255, s3, 6
	s_cselect_b64 s[2:3], -1, 0
	v_writelane_b32 v255, s2, 23
	s_and_b64 s[4:5], s[2:3], exec
	s_cselect_b32 s4, s62, 0
	s_ashr_i32 s5, s4, 31
	v_writelane_b32 v255, s3, 24
	s_lshl_b64 s[2:3], s[4:5], 11
	s_or_b32 s64, s38, 9
	v_writelane_b32 v255, s2, 7
	s_cmp_lt_i32 s64, s73
	v_writelane_b32 v252, s59, 34
	v_writelane_b32 v255, s3, 8
	s_cselect_b64 s[2:3], -1, 0
	v_writelane_b32 v255, s2, 17
	s_and_b64 s[4:5], s[2:3], exec
	s_cselect_b32 s4, s64, 0
	s_ashr_i32 s5, s4, 31
	v_writelane_b32 v255, s3, 18
	s_lshl_b64 s[2:3], s[4:5], 11
	s_or_b32 s66, s38, 10
	v_writelane_b32 v255, s2, 11
	s_cmp_lt_i32 s66, s73
	s_mov_b32 s58, s18
	v_writelane_b32 v255, s3, 12
	s_cselect_b64 s[2:3], -1, 0
	v_writelane_b32 v255, s2, 27
	s_and_b64 s[4:5], s[2:3], exec
	s_cselect_b32 s4, s66, 0
	s_ashr_i32 s5, s4, 31
	v_writelane_b32 v255, s3, 28
	s_lshl_b64 s[2:3], s[4:5], 11
	s_or_b32 s68, s38, 11
	v_writelane_b32 v255, s2, 15
	s_cmp_lt_i32 s68, s73
	v_writelane_b32 v252, s58, 31
	v_writelane_b32 v255, s3, 16
	s_cselect_b64 s[2:3], -1, 0
	v_writelane_b32 v253, s2, 32
	s_and_b64 s[4:5], s[2:3], exec
	s_cselect_b32 s4, s68, 0
	s_ashr_i32 s5, s4, 31
	v_writelane_b32 v253, s3, 33
	s_lshl_b64 s[2:3], s[4:5], 11
	s_or_b32 s70, s38, 12
	s_cmp_lt_i32 s70, s73
	s_cselect_b64 s[28:29], -1, 0
	s_and_b64 s[4:5], s[28:29], exec
	s_cselect_b32 s4, s70, 0
	v_writelane_b32 v255, s2, 19
	s_ashr_i32 s5, s4, 31
	s_or_b32 s24, s38, 13
	v_writelane_b32 v255, s3, 20
	s_lshl_b64 s[2:3], s[4:5], 11
	v_writelane_b32 v255, s2, 21
	s_cmp_lt_i32 s24, s73
	v_writelane_b32 v252, s59, 32
	v_writelane_b32 v255, s3, 22
	s_cselect_b64 s[2:3], -1, 0
	v_writelane_b32 v255, s2, 1
	s_and_b64 s[4:5], s[2:3], exec
	s_cselect_b32 s4, s24, 0
	s_ashr_i32 s5, s4, 31
	v_writelane_b32 v255, s3, 2
	s_lshl_b64 s[2:3], s[4:5], 11
	s_or_b32 s44, s38, 14
	s_cmp_lt_i32 s44, s73
	s_cselect_b64 s[26:27], -1, 0
	s_and_b64 s[4:5], s[26:27], exec
	s_cselect_b32 s4, s44, 0
	v_writelane_b32 v255, s2, 25
	s_ashr_i32 s5, s4, 31
	s_or_b32 s74, s38, 15
	v_writelane_b32 v255, s3, 26
	s_lshl_b64 s[2:3], s[4:5], 11
	s_cmp_lt_i32 s74, s73
	s_cselect_b64 s[46:47], -1, 0
	s_and_b64 s[4:5], s[46:47], exec
	s_cselect_b32 s4, s74, 0
	v_writelane_b32 v255, s2, 29
	s_ashr_i32 s5, s4, 31
	s_or_b32 s76, s38, 16
	v_writelane_b32 v255, s3, 30
	s_lshl_b64 s[2:3], s[4:5], 11
	s_cmp_lt_i32 s76, s73
	s_cselect_b64 s[42:43], -1, 0
	s_and_b64 s[4:5], s[42:43], exec
	s_cselect_b32 s4, s76, 0
	v_writelane_b32 v255, s2, 31
	s_ashr_i32 s5, s4, 31
	s_or_b32 s78, s38, 17
	v_writelane_b32 v255, s3, 32
	s_lshl_b64 s[2:3], s[4:5], 11
	v_writelane_b32 v255, s2, 33
	s_cmp_lt_i32 s78, s73
	s_mov_b32 s58, s52
	v_writelane_b32 v255, s3, 34
	s_cselect_b64 s[2:3], -1, 0
	v_writelane_b32 v253, s2, 28
	s_and_b64 s[4:5], s[2:3], exec
	s_cselect_b32 s4, s78, 0
	s_ashr_i32 s5, s4, 31
	v_writelane_b32 v253, s3, 29
	s_lshl_b64 s[2:3], s[4:5], 11
	s_or_b32 s80, s38, 18
	s_cmp_lt_i32 s80, s73
	s_cselect_b64 vcc, -1, 0
	s_and_b64 s[4:5], vcc, exec
	s_cselect_b32 s4, s80, 0
	v_writelane_b32 v255, s2, 35
	s_ashr_i32 s5, s4, 31
	s_or_b32 s82, s38, 19
	v_writelane_b32 v255, s3, 36
	s_lshl_b64 s[2:3], s[4:5], 11
	s_cmp_lt_i32 s82, s73
	s_cselect_b64 s[36:37], -1, 0
	s_and_b64 s[4:5], s[36:37], exec
	s_cselect_b32 s4, s82, 0
	v_writelane_b32 v255, s2, 39
	s_ashr_i32 s5, s4, 31
	s_or_b32 s94, s38, 20
	v_writelane_b32 v255, s3, 40
	s_lshl_b64 s[2:3], s[4:5], 11
	s_cmp_lt_i32 s94, s73
	s_cselect_b64 s[34:35], -1, 0
	s_and_b64 s[4:5], s[34:35], exec
	s_cselect_b32 s4, s94, 0
	v_writelane_b32 v255, s2, 43
	s_ashr_i32 s5, s4, 31
	s_or_b32 s92, s38, 21
	v_writelane_b32 v255, s3, 44
	s_lshl_b64 s[2:3], s[4:5], 11
	s_cmp_lt_i32 s92, s73
	s_cselect_b64 s[30:31], -1, 0
	s_and_b64 s[4:5], s[30:31], exec
	s_cselect_b32 s4, s92, 0
	v_writelane_b32 v255, s2, 47
	s_ashr_i32 s5, s4, 31
	s_or_b32 s90, s38, 22
	v_writelane_b32 v255, s3, 48
	s_lshl_b64 s[2:3], s[4:5], 11
	v_writelane_b32 v255, s2, 51
	s_cmp_lt_i32 s90, s73
	s_nop 0
	v_writelane_b32 v255, s3, 52
	s_cselect_b64 s[2:3], -1, 0
	v_writelane_b32 v255, s2, 53
	s_and_b64 s[4:5], s[2:3], exec
	s_cselect_b32 s4, s90, 0
	s_ashr_i32 s5, s4, 31
	v_writelane_b32 v255, s3, 54
	s_lshl_b64 s[2:3], s[4:5], 11
	s_or_b32 s88, s38, 23
	v_writelane_b32 v255, s2, 55
	s_cmp_lt_i32 s88, s73
	s_nop 0
	v_writelane_b32 v255, s3, 56
	s_cselect_b64 s[2:3], -1, 0
	v_writelane_b32 v254, s2, 5
	s_and_b64 s[4:5], s[2:3], exec
	s_cselect_b32 s4, s88, 0
	s_ashr_i32 s5, s4, 31
	v_writelane_b32 v254, s3, 6
	s_lshl_b64 s[2:3], s[4:5], 11
	s_or_b32 s86, s38, 24
	v_writelane_b32 v255, s2, 59
	s_cmp_lt_i32 s86, s73
	s_nop 0
	v_writelane_b32 v255, s3, 60
	s_cselect_b64 s[2:3], -1, 0
	v_writelane_b32 v255, s2, 41
	s_and_b64 s[4:5], s[2:3], exec
	s_cselect_b32 s4, s86, 0
	s_ashr_i32 s5, s4, 31
	v_writelane_b32 v255, s3, 42
	s_lshl_b64 s[2:3], s[4:5], 11
	s_or_b32 s84, s38, 25
	v_writelane_b32 v254, s2, 9
	s_cmp_lt_i32 s84, s73
	s_nop 0
	v_writelane_b32 v254, s3, 10
	s_cselect_b64 s[2:3], -1, 0
	v_writelane_b32 v255, s2, 57
	s_and_b64 s[4:5], s[2:3], exec
	s_cselect_b32 s4, s84, 0
	s_ashr_i32 s5, s4, 31
	v_writelane_b32 v255, s3, 58
	s_lshl_b64 s[2:3], s[4:5], 11
	s_or_b32 s96, s38, 26
	v_writelane_b32 v255, s2, 63
	s_cmp_lt_i32 s96, s73
	s_nop 0
	v_writelane_b32 v254, s3, 0
	s_cselect_b64 s[2:3], -1, 0
	v_writelane_b32 v255, s2, 37
	s_and_b64 s[4:5], s[2:3], exec
	s_cselect_b32 s4, s96, 0
	s_ashr_i32 s5, s4, 31
	v_writelane_b32 v255, s3, 38
	s_lshl_b64 s[2:3], s[4:5], 11
	s_or_b32 s54, s38, 27
	v_writelane_b32 v254, s2, 1
	s_cmp_lt_i32 s54, s73
	s_nop 0
	v_writelane_b32 v254, s3, 2
	s_cselect_b64 s[2:3], -1, 0
	v_writelane_b32 v255, s2, 61
	s_and_b64 s[4:5], s[2:3], exec
	s_cselect_b32 s4, s54, 0
	s_ashr_i32 s5, s4, 31
	v_writelane_b32 v255, s3, 62
	s_lshl_b64 s[2:3], s[4:5], 11
	s_or_b32 s8, s38, 28
	v_writelane_b32 v254, s2, 3
	s_cmp_lt_i32 s8, s73
	s_nop 0
	v_writelane_b32 v254, s3, 4
	s_cselect_b64 s[2:3], -1, 0
	v_writelane_b32 v253, s2, 30
	s_and_b64 s[4:5], s[2:3], exec
	s_cselect_b32 s4, s8, 0
	s_ashr_i32 s5, s4, 31
	v_writelane_b32 v253, s3, 31
	s_lshl_b64 s[2:3], s[4:5], 11
	s_or_b32 s6, s38, 29
	v_writelane_b32 v254, s2, 7
	s_cmp_lt_i32 s6, s73
	s_nop 0
	v_writelane_b32 v254, s3, 8
	s_cselect_b64 s[2:3], -1, 0
	v_writelane_b32 v254, s2, 13
	s_and_b64 s[4:5], s[2:3], exec
	s_cselect_b32 s4, s6, 0
	s_ashr_i32 s5, s4, 31
	v_writelane_b32 v254, s3, 14
	s_lshl_b64 s[2:3], s[4:5], 11
	s_or_b32 s50, s38, 30
	v_writelane_b32 v254, s2, 11
	s_cmp_lt_i32 s50, s73
	s_nop 0
	v_writelane_b32 v254, s3, 12
	s_cselect_b64 s[2:3], -1, 0
	v_writelane_b32 v254, s2, 17
	s_and_b64 s[4:5], s[2:3], exec
	s_cselect_b32 s4, s50, 0
	v_writelane_b32 v254, s3, 18
	s_ashr_i32 s5, s4, 31
	s_lshl_b64 s[4:5], s[4:5], 11
	s_or_b32 s2, s0, 31
	v_writelane_b32 v254, s58, 25
	s_cmp_lt_i32 s2, s73
	s_cselect_b64 s[0:1], -1, 0
	v_writelane_b32 v254, s59, 26
	s_mov_b32 s58, s56
	v_writelane_b32 v254, s58, 27
	v_writelane_b32 v253, s0, 10
	s_nop 0
	v_writelane_b32 v254, s59, 28
	s_mov_b32 s58, s20
	v_writelane_b32 v253, s1, 11
	s_and_b64 s[0:1], s[0:1], exec
	v_writelane_b32 v254, s58, 31
	s_cselect_b32 s0, s2, 0
	s_lshl_b32 s71, s70, 6
	v_writelane_b32 v254, s59, 32
	s_lshl_b32 s59, s20, 6
	s_add_i32 s59, s59, 0
	s_mov_b32 s58, s60
	v_writelane_b32 v254, s58, 29
	s_add_i32 s9, s71, 0
	s_lshl_b32 s71, s24, 6
	v_writelane_b32 v254, s59, 30
	s_mov_b32 s58, s62
	v_writelane_b32 v254, s58, 33
	v_writelane_b32 v255, s9, 13
	s_add_i32 s9, s71, 0
	v_writelane_b32 v254, s59, 34
	s_mov_b32 s58, s64
	v_writelane_b32 v254, s58, 35
	s_lshl_b32 s71, s44, 6
	v_writelane_b32 v255, s9, 9
	v_writelane_b32 v254, s59, 36
	s_mov_b32 s58, s66
	v_writelane_b32 v254, s58, 37
	s_add_i32 s9, s71, 0
	s_lshl_b32 s71, s74, 6
	v_writelane_b32 v254, s59, 38
	s_mov_b32 s58, s68
	v_writelane_b32 v254, s58, 39
	s_ashr_i32 s1, s0, 31
	s_lshl_b64 s[0:1], s[0:1], 11
	v_writelane_b32 v254, s59, 40
	s_mov_b32 s58, s70
	v_writelane_b32 v254, s58, 41
	s_lshl_b32 s17, s38, 6
	s_add_i32 s7, s17, 0
	v_writelane_b32 v254, s59, 42
	s_mov_b32 s58, s24
	v_writelane_b32 v254, s58, 43
	s_lshl_b32 s17, s72, 6
	s_add_i32 s79, s17, 0
	v_writelane_b32 v254, s59, 44
	s_mov_b32 s58, s44
	v_writelane_b32 v254, s58, 45
	s_lshl_b32 s17, s40, 6
	s_add_i32 s3, s17, 0
	v_writelane_b32 v254, s59, 46
	v_writelane_b32 v254, s9, 49
	s_mov_b32 s58, s74
	v_writelane_b32 v254, s58, 47
	s_add_i32 s9, s71, 0
	s_lshl_b32 s71, s76, 6
	v_writelane_b32 v254, s59, 48
	v_writelane_b32 v254, s9, 52
	s_mov_b32 s58, s76
	v_writelane_b32 v254, s58, 50
	s_add_i32 s9, s71, 0
	s_lshl_b32 s71, s78, 6
	v_writelane_b32 v254, s59, 51
	v_writelane_b32 v254, s9, 55
	s_mov_b32 s58, s78
	v_writelane_b32 v254, s58, 53
	s_add_i32 s9, s71, 0
	s_lshl_b32 s71, s80, 6
	v_writelane_b32 v254, s59, 54
	v_writelane_b32 v254, s9, 58
	s_mov_b32 s58, s80
	v_writelane_b32 v254, s58, 56
	s_add_i32 s9, s71, 0
	s_lshl_b32 s71, s82, 6
	v_writelane_b32 v254, s59, 57
	v_writelane_b32 v254, s9, 61
	s_mov_b32 s58, s82
	v_writelane_b32 v254, s58, 59
	s_add_i32 s9, s71, 0
	s_lshl_b32 s71, s94, 6
	v_writelane_b32 v254, s59, 60
	s_mov_b32 s58, s94
	v_writelane_b32 v253, s9, 0
	v_writelane_b32 v254, s58, 62
	s_add_i32 s9, s71, 0
	v_writelane_b32 v253, s9, 3
	v_writelane_b32 v254, s59, 63
	s_mov_b32 s58, s92
	v_writelane_b32 v253, s58, 1
	s_lshl_b32 s71, s92, 6
	s_add_i32 s9, s71, 0
	v_writelane_b32 v253, s59, 2
	v_writelane_b32 v253, s9, 6
	s_mov_b32 s58, s90
	v_writelane_b32 v253, s58, 4
	s_lshl_b32 s71, s90, 6
	s_add_i32 s97, s71, 0
	v_writelane_b32 v253, s59, 5
	s_mov_b32 s58, s88
	v_writelane_b32 v253, s58, 8
	s_lshl_b32 s71, s88, 6
	s_add_i32 s95, s71, 0
	v_writelane_b32 v253, s59, 9
	s_mov_b32 s58, s86
	v_writelane_b32 v253, s58, 12
	s_lshl_b32 s71, s86, 6
	s_add_i32 s94, s71, 0
	v_writelane_b32 v253, s59, 13
	s_mov_b32 s58, s84
	v_writelane_b32 v253, s58, 14
	s_lshl_b32 s71, s84, 6
	s_add_i32 s93, s71, 0
	v_writelane_b32 v253, s59, 15
	s_mov_b32 s58, s96
	v_writelane_b32 v253, s58, 16
	s_lshl_b32 s71, s96, 6
	s_add_i32 s92, s71, 0
	v_writelane_b32 v253, s59, 17
	s_mov_b32 s58, s54
	s_lshl_b32 s71, s54, 6
	v_writelane_b32 v253, s58, 18
	s_add_i32 s9, s71, 0
	v_writelane_b32 v254, s9, 19
	v_writelane_b32 v253, s59, 19
	s_mov_b32 s58, s8
	s_lshl_b32 s71, s8, 6
	v_readlane_b32 s8, v255, 49
	v_readlane_b32 s9, v255, 50
	v_readlane_b32 s90, v255, 45
	v_readlane_b32 s91, v255, 46
	v_lshl_add_u64 v[28:29], v[20:21], 0, s[8:9]
	global_load_ushort v86, v[28:29], off
	v_lshl_add_u64 v[28:29], v[22:23], 0, s[8:9]
	v_readlane_b32 s8, v252, 55
	v_readlane_b32 s9, v252, 56
	global_load_ushort v1, v[28:29], off
	v_writelane_b32 v253, s58, 20
	v_lshl_add_u64 v[28:29], v[20:21], 0, s[8:9]
	global_load_ushort v84, v[28:29], off
	v_lshl_add_u64 v[28:29], v[22:23], 0, s[8:9]
	v_readlane_b32 s8, v252, 53
	v_readlane_b32 s9, v252, 54
	s_waitcnt vmcnt(0)
	global_load_ushort v88, v[28:29], off
	v_writelane_b32 v253, s59, 21
	v_lshl_add_u64 v[28:29], v[20:21], 0, s[8:9]
	global_load_ushort v82, v[28:29], off
	v_lshl_add_u64 v[28:29], v[22:23], 0, s[8:9]
	v_readlane_b32 s8, v252, 57
	v_readlane_b32 s9, v252, 58
	global_load_ushort v87, v[28:29], off
	s_add_i32 s96, s71, 0
	v_lshl_add_u64 v[28:29], v[20:21], 0, s[8:9]
	global_load_ushort v80, v[28:29], off
	v_lshl_add_u64 v[28:29], v[22:23], 0, s[8:9]
	v_readlane_b32 s8, v252, 59
	v_readlane_b32 s9, v252, 60
	global_load_ushort v85, v[28:29], off
	s_mov_b32 s58, s6
	v_lshl_add_u64 v[28:29], v[20:21], 0, s[8:9]
	global_load_ushort v79, v[28:29], off
	v_lshl_add_u64 v[28:29], v[22:23], 0, s[8:9]
	v_readlane_b32 s8, v252, 61
	v_readlane_b32 s9, v252, 62
	global_load_ushort v83, v[28:29], off
	s_lshl_b32 s71, s6, 6
	v_lshl_add_u64 v[28:29], v[20:21], 0, s[8:9]
	global_load_ushort v77, v[28:29], off
	v_lshl_add_u64 v[28:29], v[22:23], 0, s[8:9]
	v_readlane_b32 s8, v252, 63
	v_readlane_b32 s9, v255, 0
	global_load_ushort v81, v[28:29], off
	s_mov_b32 s6, 0xbfb8aa3b
	v_lshl_add_u64 v[28:29], v[20:21], 0, s[8:9]
	global_load_ushort v75, v[28:29], off
	v_lshl_add_u64 v[28:29], v[22:23], 0, s[8:9]
	v_readlane_b32 s8, v255, 5
	v_readlane_b32 s9, v255, 6
	global_load_ushort v78, v[28:29], off
	s_lshl_b32 s17, s18, 6
	v_lshl_add_u64 v[28:29], v[20:21], 0, s[8:9]
	global_load_ushort v73, v[28:29], off
	v_lshl_add_u64 v[28:29], v[22:23], 0, s[8:9]
	v_readlane_b32 s8, v255, 7
	v_readlane_b32 s9, v255, 8
	global_load_ushort v76, v[28:29], off
	s_add_i32 s17, s17, 0
	v_lshl_add_u64 v[28:29], v[20:21], 0, s[8:9]
	global_load_ushort v69, v[28:29], off
	v_lshl_add_u64 v[28:29], v[22:23], 0, s[8:9]
	v_readlane_b32 s8, v255, 11
	v_readlane_b32 s9, v255, 12
	global_load_ushort v74, v[28:29], off
	s_lshl_b32 s53, s52, 6
	v_lshl_add_u64 v[28:29], v[20:21], 0, s[8:9]
	global_load_ushort v70, v[28:29], off
	v_lshl_add_u64 v[28:29], v[22:23], 0, s[8:9]
	v_readlane_b32 s8, v255, 15
	v_readlane_b32 s9, v255, 16
	global_load_ushort v72, v[28:29], off
	s_add_i32 s53, s53, 0
	v_lshl_add_u64 v[28:29], v[20:21], 0, s[8:9]
	global_load_ushort v67, v[28:29], off
	v_lshl_add_u64 v[28:29], v[22:23], 0, s[8:9]
	v_readlane_b32 s8, v255, 19
	v_readlane_b32 s9, v255, 20
	global_load_ushort v71, v[28:29], off
	s_lshl_b32 s57, s56, 6
	v_lshl_add_u64 v[28:29], v[20:21], 0, s[8:9]
	global_load_ushort v65, v[28:29], off
	v_lshl_add_u64 v[28:29], v[22:23], 0, s[8:9]
	v_readlane_b32 s8, v255, 21
	v_readlane_b32 s9, v255, 22
	global_load_ushort v68, v[28:29], off
	s_add_i32 s57, s57, 0
	v_lshl_add_u64 v[28:29], v[20:21], 0, s[8:9]
	global_load_ushort v63, v[28:29], off
	v_lshl_add_u64 v[28:29], v[22:23], 0, s[8:9]
	v_readlane_b32 s8, v255, 25
	v_readlane_b32 s9, v255, 26
	global_load_ushort v66, v[28:29], off
	s_waitcnt vmcnt(0) lgkmcnt(0)
	v_lshlrev_b32_e32 v1, 16, v1
	v_lshl_add_u64 v[28:29], v[20:21], 0, s[8:9]
	global_load_ushort v61, v[28:29], off
	v_lshl_add_u64 v[28:29], v[22:23], 0, s[8:9]
	v_readlane_b32 s8, v255, 29
	v_readlane_b32 s9, v255, 30
	global_load_ushort v64, v[28:29], off
	v_cndmask_b32_e64 v89, 0, v1, s[90:91]
	v_lshl_add_u64 v[28:29], v[20:21], 0, s[8:9]
	global_load_ushort v59, v[28:29], off
	v_lshl_add_u64 v[28:29], v[22:23], 0, s[8:9]
	v_readlane_b32 s8, v255, 31
	v_readlane_b32 s9, v255, 32
	global_load_ushort v62, v[28:29], off
	v_mov_b32_e32 v1, s7
	v_lshl_add_u64 v[28:29], v[20:21], 0, s[8:9]
	global_load_ushort v57, v[28:29], off
	v_lshl_add_u64 v[28:29], v[22:23], 0, s[8:9]
	v_readlane_b32 s8, v255, 33
	v_readlane_b32 s9, v255, 34
	global_load_ushort v60, v[28:29], off
	s_mov_b32 s7, 0x800000
	v_lshl_add_u64 v[28:29], v[20:21], 0, s[8:9]
	global_load_ushort v43, v[28:29], off
	v_lshl_add_u64 v[28:29], v[22:23], 0, s[8:9]
	v_readlane_b32 s8, v255, 35
	v_readlane_b32 s9, v255, 36
	global_load_ushort v58, v[28:29], off
	v_writelane_b32 v253, s58, 22
	v_lshl_add_u64 v[28:29], v[20:21], 0, s[8:9]
	global_load_ushort v35, v[28:29], off
	v_lshl_add_u64 v[28:29], v[22:23], 0, s[8:9]
	v_readlane_b32 s8, v255, 39
	v_readlane_b32 s9, v255, 40
	global_load_ushort v50, v[28:29], off
	v_writelane_b32 v253, s59, 23
	v_lshl_add_u64 v[28:29], v[20:21], 0, s[8:9]
	global_load_ushort v36, v[28:29], off
	v_lshl_add_u64 v[28:29], v[22:23], 0, s[8:9]
	v_readlane_b32 s8, v255, 43
	v_readlane_b32 s9, v255, 44
	global_load_ushort v51, v[28:29], off
	s_mov_b32 s58, s50
	v_lshl_add_u64 v[28:29], v[20:21], 0, s[8:9]
	global_load_ushort v37, v[28:29], off
	v_lshl_add_u64 v[28:29], v[22:23], 0, s[8:9]
	v_readlane_b32 s8, v255, 47
	v_readlane_b32 s9, v255, 48
	global_load_ushort v52, v[28:29], off
	v_writelane_b32 v253, s58, 24
	v_lshl_add_u64 v[28:29], v[20:21], 0, s[8:9]
	global_load_ushort v38, v[28:29], off
	v_lshl_add_u64 v[28:29], v[22:23], 0, s[8:9]
	v_readlane_b32 s8, v255, 51
	v_readlane_b32 s9, v255, 52
	global_load_ushort v53, v[28:29], off
	v_writelane_b32 v253, s59, 25
	v_lshl_add_u64 v[28:29], v[20:21], 0, s[8:9]
	global_load_ushort v39, v[28:29], off
	v_lshl_add_u64 v[28:29], v[22:23], 0, s[8:9]
	v_readlane_b32 s8, v255, 55
	v_readlane_b32 s9, v255, 56
	global_load_ushort v54, v[28:29], off
	s_mov_b32 s58, s2
	v_lshl_add_u64 v[28:29], v[20:21], 0, s[8:9]
	global_load_ushort v40, v[28:29], off
	v_lshl_add_u64 v[28:29], v[22:23], 0, s[8:9]
	v_readlane_b32 s8, v255, 59
	v_readlane_b32 s9, v255, 60
	global_load_ushort v55, v[28:29], off
	v_writelane_b32 v253, s58, 26
	v_lshl_add_u64 v[28:29], v[20:21], 0, s[8:9]
	global_load_ushort v41, v[28:29], off
	v_lshl_add_u64 v[28:29], v[22:23], 0, s[8:9]
	v_readlane_b32 s8, v254, 9
	v_readlane_b32 s9, v254, 10
	global_load_ushort v56, v[28:29], off
	s_lshl_b32 s61, s60, 6
	v_lshl_add_u64 v[30:31], v[22:23], 0, s[8:9]
	global_load_ushort v49, v[30:31], off
	v_lshl_add_u64 v[28:29], v[20:21], 0, s[8:9]
	v_readlane_b32 s8, v255, 63
	v_readlane_b32 s9, v254, 0
	global_load_ushort v28, v[28:29], off
	s_add_i32 s61, s61, 0
	v_lshl_add_u64 v[30:31], v[20:21], 0, s[8:9]
	global_load_ushort v29, v[30:31], off
	v_lshl_add_u64 v[30:31], v[22:23], 0, s[8:9]
	v_readlane_b32 s8, v254, 1
	v_readlane_b32 s9, v254, 2
	global_load_ushort v44, v[30:31], off
	s_lshl_b32 s63, s62, 6
	v_lshl_add_u64 v[32:33], v[22:23], 0, s[8:9]
	global_load_ushort v45, v[32:33], off
	v_lshl_add_u64 v[30:31], v[20:21], 0, s[8:9]
	v_readlane_b32 s8, v254, 3
	v_readlane_b32 s9, v254, 4
	global_load_ushort v30, v[30:31], off
	s_add_i32 s63, s63, 0
	v_lshl_add_u64 v[32:33], v[20:21], 0, s[8:9]
	global_load_ushort v31, v[32:33], off
	v_lshl_add_u64 v[32:33], v[22:23], 0, s[8:9]
	v_readlane_b32 s8, v254, 7
	v_readlane_b32 s9, v254, 8
	global_load_ushort v46, v[32:33], off
	s_lshl_b32 s65, s64, 6
	v_lshl_add_u64 v[90:91], v[22:23], 0, s[8:9]
	global_load_ushort v47, v[90:91], off
	v_lshl_add_u64 v[32:33], v[20:21], 0, s[8:9]
	v_readlane_b32 s8, v254, 11
	v_readlane_b32 s9, v254, 12
	global_load_ushort v32, v[32:33], off
	s_add_i32 s65, s65, 0
	v_lshl_add_u64 v[90:91], v[20:21], 0, s[8:9]
	global_load_ushort v33, v[90:91], off
	v_lshl_add_u64 v[90:91], v[22:23], 0, s[8:9]
	global_load_ushort v48, v[90:91], off
	v_lshl_add_u64 v[90:91], v[20:21], 0, s[4:5]
	v_lshl_add_u64 v[20:21], v[20:21], 0, s[0:1]
	global_load_ushort v27, v[90:91], off
	s_mov_b32 s8, 0x3f317217
	global_load_ushort v20, v[20:21], off
	v_lshl_add_u64 v[90:91], v[22:23], 0, s[4:5]
	v_lshl_add_u64 v[22:23], v[22:23], 0, s[0:1]
	global_load_ushort v42, v[90:91], off
	global_load_ushort v21, v[22:23], off
	s_waitcnt lgkmcnt(0)
	s_barrier
	ds_read_b128 v[184:187], v1 offset:4096
	ds_read_b128 v[188:191], v1 offset:4112
	ds_read_b128 v[192:195], v1 offset:4128
	ds_read_b128 v[196:199], v1 offset:4144
	s_mov_b32 s9, 0x7f800000
	s_lshl_b32 s67, s66, 6
	s_add_i32 s67, s67, 0
	s_lshl_b32 s69, s68, 6
	s_waitcnt lgkmcnt(4)
	s_waitcnt lgkmcnt(3)
	v_mul_f32_e32 v22, v6, v185
	v_fmac_f32_e32 v22, v4, v184
	v_fmac_f32_e32 v22, v8, v186
	v_fmac_f32_e32 v22, v10, v187
	v_add_f32_e32 v22, v26, v22
	s_add_i32 s69, s69, 0
	v_writelane_b32 v253, s59, 27
	s_add_i32 s68, s71, 0
	s_waitcnt lgkmcnt(2)
	v_mul_f32_e32 v23, v7, v189
	v_fmac_f32_e32 v23, v5, v188
	v_fmac_f32_e32 v23, v9, v190
	v_fmac_f32_e32 v23, v11, v191
	v_add_f32_e32 v22, v22, v23
	s_lshl_b32 s71, s50, 6
	s_add_i32 s66, s71, 0
	s_lshl_b32 s71, s2, 6
	s_waitcnt lgkmcnt(1)
	v_mul_f32_e32 v23, v14, v193
	v_fmac_f32_e32 v23, v12, v192
	v_fmac_f32_e32 v23, v16, v194
	v_fmac_f32_e32 v23, v18, v195
	v_add_f32_e32 v22, v22, v23
	s_add_i32 s60, s71, 0
	v_readlane_b32 s82, v255, 3
	v_readlane_b32 s83, v255, 4
	s_waitcnt lgkmcnt(0)
	v_mul_f32_e32 v1, v15, v197
	v_fmac_f32_e32 v1, v13, v196
	v_fmac_f32_e32 v1, v17, v198
	v_fmac_f32_e32 v1, v19, v199
	v_add_f32_e32 v1, v22, v1
	v_max_f32_e64 v22, -v1, 0
	v_mul_f32_e64 v1, |v1|, s6
	v_exp_f32_e32 v1, v1
	s_mov_b64 s[80:81], s[14:15]
	s_mov_b64 s[76:77], s[10:11]
	s_and_b32 s71, s55, 0x3fffff00
	v_add_f32_e32 v1, 1.0, v1
	v_cmp_gt_f32_e64 s[0:1], s7, v1
	s_mov_b64 s[74:75], s[12:13]
	s_lshl_b32 s71, s71, 2
	v_cndmask_b32_e64 v23, 0, 32, s[0:1]
	v_ldexp_f32 v1, v1, v23
	v_log_f32_e32 v1, v1
	s_add_i32 s50, s71, 0
	s_mov_b64 s[70:71], s[22:23]
	s_cmpk_lt_u32 s55, 0x100
	v_mul_f32_e32 v23, 0x3f317217, v1
	v_fma_f32 v23, v1, s8, -v23
	v_fmac_f32_e32 v23, 0x3377d1cf, v1
	v_fmac_f32_e32 v23, 0x3f317217, v1
	v_cmp_lt_f32_e64 s[4:5], |v1|, s9
	v_readlane_b32 s55, v252, 43
	s_cselect_b64 s[88:89], -1, 0
	v_cndmask_b32_e64 v1, v1, v23, s[4:5]
	v_cndmask_b32_e64 v23, 0, v226, s[0:1]
	v_sub_f32_e32 v1, v1, v23
	v_mov_b32_e32 v23, s79
	ds_read_b128 v[184:187], v23 offset:4096
	ds_read_b128 v[188:191], v23 offset:4112
	ds_read_b128 v[192:195], v23 offset:4128
	ds_read_b128 v[196:199], v23 offset:4144
	v_add_f32_e32 v1, v22, v1
	v_mul_f32_e32 v1, 0xbd800000, v1
	v_cndmask_b32_e64 v22, 0, v1, s[90:91]
	v_add_f32_e32 v1, 0, v22
	s_waitcnt lgkmcnt(3)
	v_mul_f32_e32 v91, v6, v185
	v_fmac_f32_e32 v91, v4, v184
	v_fmac_f32_e32 v91, v8, v186
	v_fmac_f32_e32 v91, v10, v187
	v_add_f32_e32 v94, v26, v91
	v_readlane_b32 s78, v254, 15
	v_readlane_b32 s79, v254, 16
	s_add_u32 s84, s55, s48
	v_readlane_b32 s55, v252, 44
	s_waitcnt lgkmcnt(2)
	v_mul_f32_e32 v91, v7, v189
	v_fmac_f32_e32 v91, v5, v188
	v_fmac_f32_e32 v91, v9, v190
	v_fmac_f32_e32 v91, v11, v191
	v_add_f32_e32 v94, v94, v91
	s_addc_u32 s85, s55, s49
	v_readlane_b32 s55, v252, 45
	s_add_u32 s86, s55, s48
	s_mov_b64 s[54:55], s[28:29]
	s_waitcnt lgkmcnt(1)
	v_mul_f32_e32 v91, v14, v193
	v_fmac_f32_e32 v91, v12, v192
	v_fmac_f32_e32 v91, v16, v194
	v_fmac_f32_e32 v91, v18, v195
	v_add_f32_e32 v94, v94, v91
	v_readlane_b32 s48, v252, 46
	s_addc_u32 s87, s48, s49
	s_mov_b64 s[48:49], s[26:27]
	v_readlane_b32 s14, v253, 28
	s_waitcnt lgkmcnt(0)
	v_mul_f32_e32 v23, v15, v197
	v_fmac_f32_e32 v23, v13, v196
	v_fmac_f32_e32 v23, v17, v198
	v_fmac_f32_e32 v23, v19, v199
	v_add_f32_e32 v23, v94, v23
	v_max_f32_e64 v90, -v23, 0
	v_mul_f32_e64 v23, |v23|, s6
	v_exp_f32_e32 v23, v23
	v_mov_b32_e32 v94, s3
	ds_read_b128 v[184:187], v94 offset:4096
	ds_read_b128 v[188:191], v94 offset:4112
	ds_read_b128 v[192:195], v94 offset:4128
	ds_read_b128 v[196:199], v94 offset:4144
	v_readlane_b32 s2, v254, 21
	v_readlane_b32 s3, v254, 22
	v_add_f32_e32 v23, 1.0, v23
	v_cmp_gt_f32_e64 s[0:1], s7, v23
	v_readlane_b32 s15, v253, 29
	s_mov_b64 s[40:41], vcc
	v_cndmask_b32_e64 v91, 0, 32, s[0:1]
	v_ldexp_f32 v23, v23, v91
	v_log_f32_e32 v23, v23
	v_readlane_b32 s24, v255, 53
	v_readlane_b32 s25, v255, 54
	v_readlane_b32 s44, v254, 5
	v_mul_f32_e32 v91, 0x3f317217, v23
	v_fma_f32 v91, v23, s8, -v91
	v_fmac_f32_e32 v91, 0x3377d1cf, v23
	v_fmac_f32_e32 v91, 0x3f317217, v23
	v_cmp_lt_f32_e64 s[4:5], |v23|, s9
	v_readlane_b32 s45, v254, 6
	v_readlane_b32 s26, v255, 41
	v_cndmask_b32_e64 v23, v23, v91, s[4:5]
	v_cndmask_b32_e64 v91, 0, v226, s[0:1]
	v_sub_f32_e32 v23, v23, v91
	v_add_f32_e32 v23, v90, v23
	v_mul_f32_e32 v23, 0xbd800000, v23
	v_cndmask_b32_e64 v23, 0, v23, s[82:83]
	v_add_f32_e32 v1, v1, v23
	v_readlane_b32 s27, v255, 42
	s_waitcnt lgkmcnt(3)
	v_mul_f32_e32 v91, v6, v185
	v_fmac_f32_e32 v91, v4, v184
	v_fmac_f32_e32 v91, v8, v186
	v_fmac_f32_e32 v91, v10, v187
	v_add_f32_e32 v95, v26, v91
	v_readlane_b32 s28, v255, 57
	v_readlane_b32 s29, v255, 58
	v_readlane_b32 s22, v255, 37
	v_readlane_b32 s23, v255, 38
	s_waitcnt lgkmcnt(2)
	v_mul_f32_e32 v91, v7, v189
	v_fmac_f32_e32 v91, v5, v188
	v_fmac_f32_e32 v91, v9, v190
	v_fmac_f32_e32 v91, v11, v191
	v_add_f32_e32 v95, v95, v91
	v_readlane_b32 s10, v255, 61
	v_readlane_b32 s11, v255, 62
	v_readlane_b32 s18, v253, 30
	v_readlane_b32 s19, v253, 31
	s_waitcnt lgkmcnt(1)
	v_mul_f32_e32 v91, v14, v193
	v_fmac_f32_e32 v91, v12, v192
	v_fmac_f32_e32 v91, v16, v194
	v_fmac_f32_e32 v91, v18, v195
	v_add_f32_e32 v95, v95, v91
	v_readlane_b32 s20, v254, 13
	v_readlane_b32 s21, v254, 14
	v_readlane_b32 s12, v254, 17
	v_readlane_b32 s13, v254, 18
	s_waitcnt lgkmcnt(0)
	v_mul_f32_e32 v91, v15, v197
	v_fmac_f32_e32 v91, v13, v196
	v_fmac_f32_e32 v91, v17, v198
	v_fmac_f32_e32 v91, v19, v199
	v_add_f32_e32 v90, v95, v91
	v_max_f32_e64 v91, -v90, 0
	v_mul_f32_e64 v90, |v90|, s6
	v_exp_f32_e32 v90, v90
	s_ashr_i32 s39, s38, 31
	s_cmp_ge_i32 s38, s73
	v_add_f32_e32 v90, 1.0, v90
	v_cmp_gt_f32_e64 s[0:1], s7, v90
	s_nop 1
	v_cndmask_b32_e64 v92, 0, 32, s[0:1]
	v_ldexp_f32 v90, v90, v92
	v_log_f32_e32 v90, v90
	s_nop 0
	v_mul_f32_e32 v92, 0x3f317217, v90
	v_fma_f32 v92, v90, s8, -v92
	v_fmac_f32_e32 v92, 0x3377d1cf, v90
	v_fmac_f32_e32 v92, 0x3f317217, v90
	v_cmp_lt_f32_e64 s[4:5], |v90|, s9
	s_nop 1
	v_cndmask_b32_e64 v90, v90, v92, s[4:5]
	v_cndmask_b32_e64 v92, 0, v226, s[0:1]
	v_sub_f32_e32 v90, v90, v92
	v_add_f32_e32 v90, v91, v90
	v_mov_b32_e32 v91, s17
	ds_read_b128 v[184:187], v91 offset:4096
	ds_read_b128 v[188:191], v91 offset:4112
	ds_read_b128 v[192:195], v91 offset:4128
	ds_read_b128 v[196:199], v91 offset:4144
	v_mul_f32_e32 v90, 0xbd800000, v90
	v_cndmask_b32_e64 v90, 0, v90, s[2:3]
	v_add_f32_e32 v1, v1, v90
	s_waitcnt lgkmcnt(3)
	v_mul_f32_e32 v93, v6, v185
	v_fmac_f32_e32 v93, v4, v184
	v_fmac_f32_e32 v93, v8, v186
	v_fmac_f32_e32 v93, v10, v187
	v_add_f32_e32 v96, v26, v93
	s_waitcnt lgkmcnt(2)
	v_mul_f32_e32 v93, v7, v189
	v_fmac_f32_e32 v93, v5, v188
	v_fmac_f32_e32 v93, v9, v190
	v_fmac_f32_e32 v93, v11, v191
	v_add_f32_e32 v96, v96, v93
	s_waitcnt lgkmcnt(1)
	v_mul_f32_e32 v93, v14, v193
	v_fmac_f32_e32 v93, v12, v192
	v_fmac_f32_e32 v93, v16, v194
	v_fmac_f32_e32 v93, v18, v195
	v_add_f32_e32 v96, v96, v93
	s_waitcnt lgkmcnt(0)
	v_mul_f32_e32 v91, v15, v197
	v_fmac_f32_e32 v91, v13, v196
	v_fmac_f32_e32 v91, v17, v198
	v_fmac_f32_e32 v91, v19, v199
	v_add_f32_e32 v91, v96, v91
	v_max_f32_e64 v92, -v91, 0
	v_mul_f32_e64 v91, |v91|, s6
	v_exp_f32_e32 v91, v91
	v_mov_b32_e32 v96, s53
	ds_read_b128 v[184:187], v96 offset:4096
	ds_read_b128 v[188:191], v96 offset:4112
	ds_read_b128 v[192:195], v96 offset:4128
	ds_read_b128 v[196:199], v96 offset:4144
	v_readlane_b32 s52, v255, 1
	v_readlane_b32 s53, v255, 2
	v_add_f32_e32 v91, 1.0, v91
	v_cmp_gt_f32_e64 s[0:1], s7, v91
	s_nop 1
	v_cndmask_b32_e64 v93, 0, 32, s[0:1]
	v_ldexp_f32 v91, v91, v93
	v_log_f32_e32 v91, v91
	s_nop 0
	v_mul_f32_e32 v93, 0x3f317217, v91
	v_fma_f32 v93, v91, s8, -v93
	v_fmac_f32_e32 v93, 0x3377d1cf, v91
	v_fmac_f32_e32 v93, 0x3f317217, v91
	v_cmp_lt_f32_e64 s[4:5], |v91|, s9
	s_nop 1
	v_cndmask_b32_e64 v91, v91, v93, s[4:5]
	v_cndmask_b32_e64 v93, 0, v226, s[0:1]
	v_sub_f32_e32 v91, v91, v93
	v_add_f32_e32 v91, v92, v91
	v_mul_f32_e32 v91, 0xbd800000, v91
	v_cndmask_b32_e64 v91, 0, v91, s[80:81]
	v_add_f32_e32 v1, v1, v91
	s_waitcnt lgkmcnt(3)
	v_mul_f32_e32 v93, v6, v185
	v_fmac_f32_e32 v93, v4, v184
	v_fmac_f32_e32 v93, v8, v186
	v_fmac_f32_e32 v93, v10, v187
	v_add_f32_e32 v97, v26, v93
	s_waitcnt lgkmcnt(2)
	v_mul_f32_e32 v93, v7, v189
	v_fmac_f32_e32 v93, v5, v188
	v_fmac_f32_e32 v93, v9, v190
	v_fmac_f32_e32 v93, v11, v191
	v_add_f32_e32 v97, v97, v93
	s_waitcnt lgkmcnt(1)
	v_mul_f32_e32 v93, v14, v193
	v_fmac_f32_e32 v93, v12, v192
	v_fmac_f32_e32 v93, v16, v194
	v_fmac_f32_e32 v93, v18, v195
	v_add_f32_e32 v97, v97, v93
	s_waitcnt lgkmcnt(0)
	v_mul_f32_e32 v93, v15, v197
	v_fmac_f32_e32 v93, v13, v196
	v_fmac_f32_e32 v93, v17, v198
	v_fmac_f32_e32 v93, v19, v199
	v_add_f32_e32 v92, v97, v93
	v_max_f32_e64 v93, -v92, 0
	v_mul_f32_e64 v92, |v92|, s6
	v_exp_f32_e32 v92, v92
	s_nop 0
	v_add_f32_e32 v92, 1.0, v92
	v_cmp_gt_f32_e64 s[0:1], s7, v92
	s_nop 1
	v_cndmask_b32_e64 v94, 0, 32, s[0:1]
	v_ldexp_f32 v92, v92, v94
	v_log_f32_e32 v92, v92
	s_nop 0
	v_mul_f32_e32 v94, 0x3f317217, v92
	v_fma_f32 v94, v92, s8, -v94
	v_fmac_f32_e32 v94, 0x3377d1cf, v92
	v_fmac_f32_e32 v94, 0x3f317217, v92
	v_cmp_lt_f32_e64 s[4:5], |v92|, s9
	s_nop 1
	v_cndmask_b32_e64 v92, v92, v94, s[4:5]
	v_cndmask_b32_e64 v94, 0, v226, s[0:1]
	v_sub_f32_e32 v92, v92, v94
	v_add_f32_e32 v92, v93, v92
	v_mov_b32_e32 v93, s57
	ds_read_b128 v[184:187], v93 offset:4096
	ds_read_b128 v[188:191], v93 offset:4112
	ds_read_b128 v[192:195], v93 offset:4128
	ds_read_b128 v[196:199], v93 offset:4144
	v_mul_f32_e32 v92, 0xbd800000, v92
	v_cndmask_b32_e64 v92, 0, v92, s[78:79]
	v_add_f32_e32 v1, v1, v92
	v_readlane_b32 s56, v253, 32
	s_waitcnt lgkmcnt(3)
	v_mul_f32_e32 v95, v6, v185
	v_fmac_f32_e32 v95, v4, v184
	v_fmac_f32_e32 v95, v8, v186
	v_fmac_f32_e32 v95, v10, v187
	v_add_f32_e32 v98, v26, v95
	v_readlane_b32 s57, v253, 33
	s_waitcnt lgkmcnt(2)
	v_mul_f32_e32 v95, v7, v189
	v_fmac_f32_e32 v95, v5, v188
	v_fmac_f32_e32 v95, v9, v190
	v_fmac_f32_e32 v95, v11, v191
	v_add_f32_e32 v98, v98, v95
	s_waitcnt lgkmcnt(1)
	v_mul_f32_e32 v95, v14, v193
	v_fmac_f32_e32 v95, v12, v192
	v_fmac_f32_e32 v95, v16, v194
	v_fmac_f32_e32 v95, v18, v195
	v_add_f32_e32 v98, v98, v95
	s_waitcnt lgkmcnt(0)
	v_mul_f32_e32 v93, v15, v197
	v_fmac_f32_e32 v93, v13, v196
	v_fmac_f32_e32 v93, v17, v198
	v_fmac_f32_e32 v93, v19, v199
	v_add_f32_e32 v93, v98, v93
	v_max_f32_e64 v94, -v93, 0
	v_mul_f32_e64 v93, |v93|, s6
	v_exp_f32_e32 v93, v93
	v_mov_b32_e32 v98, s59
	ds_read_b128 v[184:187], v98 offset:4096
	ds_read_b128 v[188:191], v98 offset:4112
	ds_read_b128 v[192:195], v98 offset:4128
	ds_read_b128 v[196:199], v98 offset:4144
	v_readlane_b32 s58, v255, 27
	v_readlane_b32 s59, v255, 28
	v_add_f32_e32 v93, 1.0, v93
	v_cmp_gt_f32_e64 s[0:1], s7, v93
	s_nop 1
	v_cndmask_b32_e64 v95, 0, 32, s[0:1]
	v_ldexp_f32 v93, v93, v95
	v_log_f32_e32 v93, v93
	s_nop 0
	v_mul_f32_e32 v95, 0x3f317217, v93
	v_fma_f32 v95, v93, s8, -v95
	v_fmac_f32_e32 v95, 0x3377d1cf, v93
	v_fmac_f32_e32 v95, 0x3f317217, v93
	v_cmp_lt_f32_e64 s[4:5], |v93|, s9
	s_nop 1
	v_cndmask_b32_e64 v93, v93, v95, s[4:5]
	v_cndmask_b32_e64 v95, 0, v226, s[0:1]
	v_sub_f32_e32 v93, v93, v95
	v_add_f32_e32 v93, v94, v93
	v_mul_f32_e32 v93, 0xbd800000, v93
	v_cndmask_b32_e64 v93, 0, v93, s[76:77]
	v_add_f32_e32 v1, v1, v93
	s_waitcnt lgkmcnt(3)
	v_mul_f32_e32 v95, v6, v185
	v_fmac_f32_e32 v95, v4, v184
	v_fmac_f32_e32 v95, v8, v186
	v_fmac_f32_e32 v95, v10, v187
	v_add_f32_e32 v99, v26, v95
	s_waitcnt lgkmcnt(2)
	v_mul_f32_e32 v95, v7, v189
	v_fmac_f32_e32 v95, v5, v188
	v_fmac_f32_e32 v95, v9, v190
	v_fmac_f32_e32 v95, v11, v191
	v_add_f32_e32 v99, v99, v95
	s_waitcnt lgkmcnt(1)
	v_mul_f32_e32 v95, v14, v193
	v_fmac_f32_e32 v95, v12, v192
	v_fmac_f32_e32 v95, v16, v194
	v_fmac_f32_e32 v95, v18, v195
	v_add_f32_e32 v99, v99, v95
	s_waitcnt lgkmcnt(0)
	v_mul_f32_e32 v95, v15, v197
	v_fmac_f32_e32 v95, v13, v196
	v_fmac_f32_e32 v95, v17, v198
	v_fmac_f32_e32 v95, v19, v199
	v_add_f32_e32 v94, v99, v95
	v_max_f32_e64 v95, -v94, 0
	v_mul_f32_e64 v94, |v94|, s6
	v_exp_f32_e32 v94, v94
	s_nop 0
	v_add_f32_e32 v94, 1.0, v94
	v_cmp_gt_f32_e64 s[0:1], s7, v94
	s_nop 1
	v_cndmask_b32_e64 v96, 0, 32, s[0:1]
	v_ldexp_f32 v94, v94, v96
	v_log_f32_e32 v94, v94
	s_nop 0
	v_mul_f32_e32 v96, 0x3f317217, v94
	v_fma_f32 v96, v94, s8, -v96
	v_fmac_f32_e32 v96, 0x3377d1cf, v94
	v_fmac_f32_e32 v96, 0x3f317217, v94
	v_cmp_lt_f32_e64 s[4:5], |v94|, s9
	s_nop 1
	v_cndmask_b32_e64 v94, v94, v96, s[4:5]
	v_cndmask_b32_e64 v96, 0, v226, s[0:1]
	v_sub_f32_e32 v94, v94, v96
	v_add_f32_e32 v94, v95, v94
	v_mov_b32_e32 v95, s61
	ds_read_b128 v[184:187], v95 offset:4096
	ds_read_b128 v[188:191], v95 offset:4112
	ds_read_b128 v[192:195], v95 offset:4128
	ds_read_b128 v[196:199], v95 offset:4144
	v_mul_f32_e32 v94, 0xbd800000, v94
	s_waitcnt lgkmcnt(3)
	v_mul_f32_e32 v95, v6, v185
	v_fmac_f32_e32 v95, v4, v184
	s_waitcnt lgkmcnt(2)
	v_mul_f32_e32 v96, v7, v189
	v_fmac_f32_e32 v95, v8, v186
	v_fmac_f32_e32 v96, v5, v188
	v_fmac_f32_e32 v95, v10, v187
	v_fmac_f32_e32 v96, v9, v190
	v_add_f32_e32 v95, v26, v95
	v_fmac_f32_e32 v96, v11, v191
	v_add_f32_e32 v95, v95, v96
	s_waitcnt lgkmcnt(1)
	v_mul_f32_e32 v96, v14, v193
	v_fmac_f32_e32 v96, v12, v192
	v_fmac_f32_e32 v96, v16, v194
	v_fmac_f32_e32 v96, v18, v195
	v_add_f32_e32 v95, v95, v96
	s_waitcnt lgkmcnt(0)
	v_mul_f32_e32 v96, v15, v197
	v_fmac_f32_e32 v96, v13, v196
	v_fmac_f32_e32 v96, v17, v198
	v_fmac_f32_e32 v96, v19, v199
	v_add_f32_e32 v95, v95, v96
	v_max_f32_e64 v96, -v95, 0
	v_mul_f32_e64 v95, |v95|, s6
	v_exp_f32_e32 v95, v95
	v_mov_b32_e32 v108, s63
	ds_read_b128 v[184:187], v108 offset:4096
	ds_read_b128 v[188:191], v108 offset:4112
	ds_read_b128 v[192:195], v108 offset:4128
	ds_read_b128 v[196:199], v108 offset:4144
	v_cndmask_b32_e64 v94, 0, v94, s[74:75]
	v_readlane_b32 s62, v255, 23
	v_add_f32_e32 v95, 1.0, v95
	v_cmp_gt_f32_e64 s[0:1], s7, v95
	v_add_f32_e32 v1, v1, v94
	v_readlane_b32 s63, v255, 24
	v_cndmask_b32_e64 v97, 0, 32, s[0:1]
	v_ldexp_f32 v95, v95, v97
	v_log_f32_e32 v95, v95
	s_nop 0
	v_mul_f32_e32 v97, 0x3f317217, v95
	v_fma_f32 v97, v95, s8, -v97
	v_fmac_f32_e32 v97, 0x3377d1cf, v95
	v_fmac_f32_e32 v97, 0x3f317217, v95
	v_cmp_lt_f32_e64 s[4:5], |v95|, s9
	s_nop 1
	v_cndmask_b32_e64 v95, v95, v97, s[4:5]
	v_cndmask_b32_e64 v97, 0, v226, s[0:1]
	v_sub_f32_e32 v95, v95, v97
	v_add_f32_e32 v95, v96, v95
	v_mul_f32_e32 v95, 0xbd800000, v95
	s_waitcnt lgkmcnt(3)
	v_mul_f32_e32 v97, v6, v185
	v_fmac_f32_e32 v97, v4, v184
	v_fmac_f32_e32 v97, v8, v186
	v_fmac_f32_e32 v97, v10, v187
	v_add_f32_e32 v96, v26, v97
	s_waitcnt lgkmcnt(2)
	v_mul_f32_e32 v97, v7, v189
	v_fmac_f32_e32 v97, v5, v188
	v_fmac_f32_e32 v97, v9, v190
	v_fmac_f32_e32 v97, v11, v191
	v_add_f32_e32 v96, v96, v97
	s_waitcnt lgkmcnt(1)
	v_mul_f32_e32 v97, v14, v193
	v_fmac_f32_e32 v97, v12, v192
	v_fmac_f32_e32 v97, v16, v194
	v_fmac_f32_e32 v97, v18, v195
	v_add_f32_e32 v96, v96, v97
	s_waitcnt lgkmcnt(0)
	v_mul_f32_e32 v97, v15, v197
	v_fmac_f32_e32 v97, v13, v196
	v_fmac_f32_e32 v97, v17, v198
	v_fmac_f32_e32 v97, v19, v199
	v_add_f32_e32 v96, v96, v97
	v_max_f32_e64 v97, -v96, 0
	v_mul_f32_e64 v96, |v96|, s6
	v_exp_f32_e32 v96, v96
	v_cndmask_b32_e64 v95, 0, v95, s[70:71]
	v_add_f32_e32 v1, v1, v95
	v_add_f32_e32 v96, 1.0, v96
	v_cmp_gt_f32_e64 s[0:1], s7, v96
	s_nop 1
	v_cndmask_b32_e64 v98, 0, 32, s[0:1]
	v_ldexp_f32 v96, v96, v98
	v_log_f32_e32 v96, v96
	s_nop 0
	v_mul_f32_e32 v98, 0x3f317217, v96
	v_fma_f32 v98, v96, s8, -v98
	v_fmac_f32_e32 v98, 0x3377d1cf, v96
	v_fmac_f32_e32 v98, 0x3f317217, v96
	v_cmp_lt_f32_e64 s[4:5], |v96|, s9
	s_nop 1
	v_cndmask_b32_e64 v96, v96, v98, s[4:5]
	v_cndmask_b32_e64 v98, 0, v226, s[0:1]
	v_sub_f32_e32 v96, v96, v98
	v_add_f32_e32 v96, v97, v96
	v_mov_b32_e32 v97, s65
	ds_read_b128 v[184:187], v97 offset:4096
	ds_read_b128 v[188:191], v97 offset:4112
	ds_read_b128 v[192:195], v97 offset:4128
	ds_read_b128 v[196:199], v97 offset:4144
	v_mul_f32_e32 v96, 0xbd800000, v96
	s_waitcnt lgkmcnt(3)
	v_mul_f32_e32 v97, v6, v185
	v_fmac_f32_e32 v97, v4, v184
	s_waitcnt lgkmcnt(2)
	v_mul_f32_e32 v98, v7, v189
	v_fmac_f32_e32 v97, v8, v186
	v_fmac_f32_e32 v98, v5, v188
	v_fmac_f32_e32 v97, v10, v187
	v_fmac_f32_e32 v98, v9, v190
	v_add_f32_e32 v97, v26, v97
	v_fmac_f32_e32 v98, v11, v191
	v_add_f32_e32 v97, v97, v98
	s_waitcnt lgkmcnt(1)
	v_mul_f32_e32 v98, v14, v193
	v_fmac_f32_e32 v98, v12, v192
	v_fmac_f32_e32 v98, v16, v194
	v_fmac_f32_e32 v98, v18, v195
	v_add_f32_e32 v97, v97, v98
	s_waitcnt lgkmcnt(0)
	v_mul_f32_e32 v98, v15, v197
	v_fmac_f32_e32 v98, v13, v196
	v_fmac_f32_e32 v98, v17, v198
	v_fmac_f32_e32 v98, v19, v199
	v_add_f32_e32 v97, v97, v98
	v_max_f32_e64 v98, -v97, 0
	v_mul_f32_e64 v97, |v97|, s6
	v_exp_f32_e32 v97, v97
	v_mov_b32_e32 v110, s67
	ds_read_b128 v[184:187], v110 offset:4096
	ds_read_b128 v[188:191], v110 offset:4112
	ds_read_b128 v[192:195], v110 offset:4128
	ds_read_b128 v[196:199], v110 offset:4144
	v_readlane_b32 s64, v255, 17
	v_cndmask_b32_e64 v96, 0, v96, s[62:63]
	v_add_f32_e32 v97, 1.0, v97
	v_cmp_gt_f32_e64 s[0:1], s7, v97
	v_readlane_b32 s65, v255, 18
	v_add_f32_e32 v1, v1, v96
	v_cndmask_b32_e64 v99, 0, 32, s[0:1]
	v_ldexp_f32 v97, v97, v99
	v_log_f32_e32 v97, v97
	s_nop 0
	v_mul_f32_e32 v99, 0x3f317217, v97
	v_fma_f32 v99, v97, s8, -v99
	v_fmac_f32_e32 v99, 0x3377d1cf, v97
	v_fmac_f32_e32 v99, 0x3f317217, v97
	v_cmp_lt_f32_e64 s[4:5], |v97|, s9
	s_nop 1
	v_cndmask_b32_e64 v97, v97, v99, s[4:5]
	v_cndmask_b32_e64 v99, 0, v226, s[0:1]
	v_sub_f32_e32 v97, v97, v99
	v_add_f32_e32 v97, v98, v97
	v_mul_f32_e32 v97, 0xbd800000, v97
	s_waitcnt lgkmcnt(3)
	v_mul_f32_e32 v99, v6, v185
	v_fmac_f32_e32 v99, v4, v184
	v_fmac_f32_e32 v99, v8, v186
	v_fmac_f32_e32 v99, v10, v187
	v_add_f32_e32 v98, v26, v99
	s_waitcnt lgkmcnt(2)
	v_mul_f32_e32 v99, v7, v189
	v_fmac_f32_e32 v99, v5, v188
	v_fmac_f32_e32 v99, v9, v190
	v_fmac_f32_e32 v99, v11, v191
	v_add_f32_e32 v98, v98, v99
	s_waitcnt lgkmcnt(1)
	v_mul_f32_e32 v99, v14, v193
	v_fmac_f32_e32 v99, v12, v192
	v_fmac_f32_e32 v99, v16, v194
	v_fmac_f32_e32 v99, v18, v195
	v_add_f32_e32 v98, v98, v99
	s_waitcnt lgkmcnt(0)
	v_mul_f32_e32 v99, v15, v197
	v_fmac_f32_e32 v99, v13, v196
	v_fmac_f32_e32 v99, v17, v198
	v_fmac_f32_e32 v99, v19, v199
	v_add_f32_e32 v98, v98, v99
	v_max_f32_e64 v99, -v98, 0
	v_mul_f32_e64 v98, |v98|, s6
	v_exp_f32_e32 v98, v98
	v_cndmask_b32_e64 v97, 0, v97, s[64:65]
	v_add_f32_e32 v1, v1, v97
	v_add_f32_e32 v98, 1.0, v98
	v_cmp_gt_f32_e64 s[0:1], s7, v98
	s_nop 1
	v_cndmask_b32_e64 v100, 0, 32, s[0:1]
	v_ldexp_f32 v98, v98, v100
	v_log_f32_e32 v98, v98
	s_nop 0
	v_mul_f32_e32 v100, 0x3f317217, v98
	v_fma_f32 v100, v98, s8, -v100
	v_fmac_f32_e32 v100, 0x3377d1cf, v98
	v_fmac_f32_e32 v100, 0x3f317217, v98
	v_cmp_lt_f32_e64 s[4:5], |v98|, s9
	s_nop 1
	v_cndmask_b32_e64 v98, v98, v100, s[4:5]
	v_cndmask_b32_e64 v100, 0, v226, s[0:1]
	v_sub_f32_e32 v98, v98, v100
	v_add_f32_e32 v98, v99, v98
	v_mov_b32_e32 v99, s69
	ds_read_b128 v[184:187], v99 offset:4096
	ds_read_b128 v[188:191], v99 offset:4112
	ds_read_b128 v[192:195], v99 offset:4128
	ds_read_b128 v[196:199], v99 offset:4144
	v_mul_f32_e32 v98, 0xbd800000, v98
	s_waitcnt lgkmcnt(3)
	v_mul_f32_e32 v99, v6, v185
	v_fmac_f32_e32 v99, v4, v184
	s_waitcnt lgkmcnt(2)
	v_mul_f32_e32 v100, v7, v189
	v_fmac_f32_e32 v99, v8, v186
	v_fmac_f32_e32 v100, v5, v188
	v_fmac_f32_e32 v99, v10, v187
	v_fmac_f32_e32 v100, v9, v190
	v_add_f32_e32 v99, v26, v99
	v_fmac_f32_e32 v100, v11, v191
	v_add_f32_e32 v99, v99, v100
	s_waitcnt lgkmcnt(1)
	v_mul_f32_e32 v100, v14, v193
	v_fmac_f32_e32 v100, v12, v192
	v_fmac_f32_e32 v100, v16, v194
	v_fmac_f32_e32 v100, v18, v195
	v_add_f32_e32 v99, v99, v100
	s_waitcnt lgkmcnt(0)
	v_mul_f32_e32 v100, v15, v197
	v_fmac_f32_e32 v100, v13, v196
	v_fmac_f32_e32 v100, v17, v198
	v_fmac_f32_e32 v100, v19, v199
	v_add_f32_e32 v99, v99, v100
	v_max_f32_e64 v100, -v99, 0
	v_mul_f32_e64 v99, |v99|, s6
	v_exp_f32_e32 v99, v99
	v_cndmask_b32_e64 v98, 0, v98, s[58:59]
	v_add_f32_e32 v1, v1, v98
	v_add_f32_e32 v99, 1.0, v99
	v_cmp_gt_f32_e64 s[0:1], s7, v99
	s_nop 1
	v_cndmask_b32_e64 v101, 0, 32, s[0:1]
	v_ldexp_f32 v99, v99, v101
	v_log_f32_e32 v99, v99
	s_nop 0
	v_mul_f32_e32 v101, 0x3f317217, v99
	v_fma_f32 v101, v99, s8, -v101
	v_fmac_f32_e32 v101, 0x3377d1cf, v99
	v_fmac_f32_e32 v101, 0x3f317217, v99
	v_cmp_lt_f32_e64 s[4:5], |v99|, s9
	s_nop 1
	v_cndmask_b32_e64 v99, v99, v101, s[4:5]
	v_cndmask_b32_e64 v101, 0, v226, s[0:1]
	v_readlane_b32 s0, v255, 13
	v_sub_f32_e32 v99, v99, v101
	v_add_f32_e32 v99, v100, v99
	v_mov_b32_e32 v112, s0
	ds_read_b128 v[184:187], v112 offset:4096
	ds_read_b128 v[188:191], v112 offset:4112
	ds_read_b128 v[192:195], v112 offset:4128
	ds_read_b128 v[196:199], v112 offset:4144
	v_mul_f32_e32 v99, 0xbd800000, v99
	s_waitcnt lgkmcnt(3)
	v_mul_f32_e32 v101, v6, v185
	v_fmac_f32_e32 v101, v4, v184
	v_fmac_f32_e32 v101, v8, v186
	v_fmac_f32_e32 v101, v10, v187
	v_add_f32_e32 v100, v26, v101
	s_waitcnt lgkmcnt(2)
	v_mul_f32_e32 v101, v7, v189
	v_fmac_f32_e32 v101, v5, v188
	v_fmac_f32_e32 v101, v9, v190
	v_fmac_f32_e32 v101, v11, v191
	v_add_f32_e32 v100, v100, v101
	s_waitcnt lgkmcnt(1)
	v_mul_f32_e32 v101, v14, v193
	v_fmac_f32_e32 v101, v12, v192
	v_fmac_f32_e32 v101, v16, v194
	v_fmac_f32_e32 v101, v18, v195
	v_add_f32_e32 v100, v100, v101
	s_waitcnt lgkmcnt(0)
	v_mul_f32_e32 v101, v15, v197
	v_fmac_f32_e32 v101, v13, v196
	v_fmac_f32_e32 v101, v17, v198
	v_fmac_f32_e32 v101, v19, v199
	v_add_f32_e32 v100, v100, v101
	v_max_f32_e64 v101, -v100, 0
	v_mul_f32_e64 v100, |v100|, s6
	v_exp_f32_e32 v100, v100
	v_cndmask_b32_e64 v99, 0, v99, s[56:57]
	v_add_f32_e32 v1, v1, v99
	v_add_f32_e32 v100, 1.0, v100
	v_cmp_gt_f32_e64 s[0:1], s7, v100
	s_nop 1
	v_cndmask_b32_e64 v102, 0, 32, s[0:1]
	v_ldexp_f32 v100, v100, v102
	v_log_f32_e32 v100, v100
	s_nop 0
	v_mul_f32_e32 v102, 0x3f317217, v100
	v_fma_f32 v102, v100, s8, -v102
	v_fmac_f32_e32 v102, 0x3377d1cf, v100
	v_fmac_f32_e32 v102, 0x3f317217, v100
	v_cmp_lt_f32_e64 s[4:5], |v100|, s9
	s_nop 1
	v_cndmask_b32_e64 v100, v100, v102, s[4:5]
	v_cndmask_b32_e64 v102, 0, v226, s[0:1]
	v_sub_f32_e32 v100, v100, v102
	v_readlane_b32 s0, v255, 9
	v_add_f32_e32 v100, v101, v100
	v_mul_f32_e32 v100, 0xbd800000, v100
	v_mov_b32_e32 v101, s0
	ds_read_b128 v[184:187], v101 offset:4096
	ds_read_b128 v[188:191], v101 offset:4112
	ds_read_b128 v[192:195], v101 offset:4128
	ds_read_b128 v[196:199], v101 offset:4144
	v_cndmask_b32_e64 v100, 0, v100, s[54:55]
	s_waitcnt lgkmcnt(3)
	v_mul_f32_e32 v101, v6, v185
	v_fmac_f32_e32 v101, v4, v184
	s_waitcnt lgkmcnt(2)
	v_mul_f32_e32 v102, v7, v189
	v_fmac_f32_e32 v101, v8, v186
	v_fmac_f32_e32 v102, v5, v188
	v_fmac_f32_e32 v101, v10, v187
	v_fmac_f32_e32 v102, v9, v190
	v_add_f32_e32 v101, v26, v101
	v_fmac_f32_e32 v102, v11, v191
	v_add_f32_e32 v101, v101, v102
	s_waitcnt lgkmcnt(1)
	v_mul_f32_e32 v102, v14, v193
	v_fmac_f32_e32 v102, v12, v192
	v_fmac_f32_e32 v102, v16, v194
	v_fmac_f32_e32 v102, v18, v195
	v_add_f32_e32 v101, v101, v102
	s_waitcnt lgkmcnt(0)
	v_mul_f32_e32 v102, v15, v197
	v_fmac_f32_e32 v102, v13, v196
	v_fmac_f32_e32 v102, v17, v198
	v_fmac_f32_e32 v102, v19, v199
	v_add_f32_e32 v101, v101, v102
	v_max_f32_e64 v102, -v101, 0
	v_mul_f32_e64 v101, |v101|, s6
	v_exp_f32_e32 v101, v101
	v_add_f32_e32 v1, v1, v100
	v_add_f32_e32 v101, 1.0, v101
	v_cmp_gt_f32_e64 s[0:1], s7, v101
	s_nop 1
	v_cndmask_b32_e64 v103, 0, 32, s[0:1]
	v_ldexp_f32 v101, v101, v103
	v_log_f32_e32 v101, v101
	s_nop 0
	v_mul_f32_e32 v103, 0x3f317217, v101
	v_fma_f32 v103, v101, s8, -v103
	v_fmac_f32_e32 v103, 0x3377d1cf, v101
	v_fmac_f32_e32 v103, 0x3f317217, v101
	v_cmp_lt_f32_e64 s[4:5], |v101|, s9
	s_nop 1
	v_cndmask_b32_e64 v101, v101, v103, s[4:5]
	v_cndmask_b32_e64 v103, 0, v226, s[0:1]
	v_readlane_b32 s0, v254, 49
	v_sub_f32_e32 v101, v101, v103
	v_add_f32_e32 v101, v102, v101
	v_mov_b32_e32 v114, s0
	ds_read_b128 v[184:187], v114 offset:4096
	ds_read_b128 v[188:191], v114 offset:4112
	ds_read_b128 v[192:195], v114 offset:4128
	ds_read_b128 v[196:199], v114 offset:4144
	v_mul_f32_e32 v101, 0xbd800000, v101
	s_waitcnt lgkmcnt(3)
	v_mul_f32_e32 v103, v6, v185
	v_fmac_f32_e32 v103, v4, v184
	v_fmac_f32_e32 v103, v8, v186
	v_fmac_f32_e32 v103, v10, v187
	v_add_f32_e32 v102, v26, v103
	s_waitcnt lgkmcnt(2)
	v_mul_f32_e32 v103, v7, v189
	v_fmac_f32_e32 v103, v5, v188
	v_fmac_f32_e32 v103, v9, v190
	v_fmac_f32_e32 v103, v11, v191
	v_add_f32_e32 v102, v102, v103
	s_waitcnt lgkmcnt(1)
	v_mul_f32_e32 v103, v14, v193
	v_fmac_f32_e32 v103, v12, v192
	v_fmac_f32_e32 v103, v16, v194
	v_fmac_f32_e32 v103, v18, v195
	v_add_f32_e32 v102, v102, v103
	s_waitcnt lgkmcnt(0)
	v_mul_f32_e32 v103, v15, v197
	v_fmac_f32_e32 v103, v13, v196
	v_fmac_f32_e32 v103, v17, v198
	v_fmac_f32_e32 v103, v19, v199
	v_add_f32_e32 v102, v102, v103
	v_max_f32_e64 v103, -v102, 0
	v_mul_f32_e64 v102, |v102|, s6
	v_exp_f32_e32 v102, v102
	v_cndmask_b32_e64 v101, 0, v101, s[52:53]
	v_add_f32_e32 v1, v1, v101
	v_add_f32_e32 v102, 1.0, v102
	v_cmp_gt_f32_e64 s[0:1], s7, v102
	s_nop 1
	v_cndmask_b32_e64 v104, 0, 32, s[0:1]
	v_ldexp_f32 v102, v102, v104
	v_log_f32_e32 v102, v102
	s_nop 0
	v_mul_f32_e32 v104, 0x3f317217, v102
	v_fma_f32 v104, v102, s8, -v104
	v_fmac_f32_e32 v104, 0x3377d1cf, v102
	v_fmac_f32_e32 v104, 0x3f317217, v102
	v_cmp_lt_f32_e64 s[4:5], |v102|, s9
	s_nop 1
	v_cndmask_b32_e64 v102, v102, v104, s[4:5]
	v_cndmask_b32_e64 v104, 0, v226, s[0:1]
	v_sub_f32_e32 v102, v102, v104
	v_readlane_b32 s0, v254, 52
	v_add_f32_e32 v102, v103, v102
	v_mul_f32_e32 v102, 0xbd800000, v102
	v_mov_b32_e32 v103, s0
	ds_read_b128 v[184:187], v103 offset:4096
	ds_read_b128 v[188:191], v103 offset:4112
	ds_read_b128 v[192:195], v103 offset:4128
	ds_read_b128 v[196:199], v103 offset:4144
	v_cndmask_b32_e64 v102, 0, v102, s[48:49]
	s_waitcnt lgkmcnt(3)
	v_mul_f32_e32 v103, v6, v185
	v_fmac_f32_e32 v103, v4, v184
	s_waitcnt lgkmcnt(2)
	v_mul_f32_e32 v104, v7, v189
	v_fmac_f32_e32 v103, v8, v186
	v_fmac_f32_e32 v104, v5, v188
	v_fmac_f32_e32 v103, v10, v187
	v_fmac_f32_e32 v104, v9, v190
	v_add_f32_e32 v103, v26, v103
	v_fmac_f32_e32 v104, v11, v191
	v_add_f32_e32 v103, v103, v104
	s_waitcnt lgkmcnt(1)
	v_mul_f32_e32 v104, v14, v193
	v_fmac_f32_e32 v104, v12, v192
	v_fmac_f32_e32 v104, v16, v194
	v_fmac_f32_e32 v104, v18, v195
	v_add_f32_e32 v103, v103, v104
	s_waitcnt lgkmcnt(0)
	v_mul_f32_e32 v104, v15, v197
	v_fmac_f32_e32 v104, v13, v196
	v_fmac_f32_e32 v104, v17, v198
	v_fmac_f32_e32 v104, v19, v199
	v_add_f32_e32 v103, v103, v104
	v_max_f32_e64 v104, -v103, 0
	v_mul_f32_e64 v103, |v103|, s6
	v_exp_f32_e32 v103, v103
	v_add_f32_e32 v1, v1, v102
	v_add_f32_e32 v103, 1.0, v103
	v_cmp_gt_f32_e64 s[0:1], s7, v103
	s_nop 1
	v_cndmask_b32_e64 v105, 0, 32, s[0:1]
	v_ldexp_f32 v103, v103, v105
	v_log_f32_e32 v103, v103
	s_nop 0
	v_mul_f32_e32 v105, 0x3f317217, v103
	v_fma_f32 v105, v103, s8, -v105
	v_fmac_f32_e32 v105, 0x3377d1cf, v103
	v_fmac_f32_e32 v105, 0x3f317217, v103
	v_cmp_lt_f32_e64 s[4:5], |v103|, s9
	s_nop 1
	v_cndmask_b32_e64 v103, v103, v105, s[4:5]
	v_cndmask_b32_e64 v105, 0, v226, s[0:1]
	v_readlane_b32 s0, v254, 55
	v_sub_f32_e32 v103, v103, v105
	v_add_f32_e32 v103, v104, v103
	v_mov_b32_e32 v116, s0
	ds_read_b128 v[184:187], v116 offset:4096
	ds_read_b128 v[188:191], v116 offset:4112
	ds_read_b128 v[192:195], v116 offset:4128
	ds_read_b128 v[196:199], v116 offset:4144
	v_mul_f32_e32 v103, 0xbd800000, v103
	s_waitcnt lgkmcnt(3)
	v_mul_f32_e32 v105, v6, v185
	v_fmac_f32_e32 v105, v4, v184
	v_fmac_f32_e32 v105, v8, v186
	v_fmac_f32_e32 v105, v10, v187
	v_add_f32_e32 v104, v26, v105
	s_waitcnt lgkmcnt(2)
	v_mul_f32_e32 v105, v7, v189
	v_fmac_f32_e32 v105, v5, v188
	v_fmac_f32_e32 v105, v9, v190
	v_fmac_f32_e32 v105, v11, v191
	v_add_f32_e32 v104, v104, v105
	s_waitcnt lgkmcnt(1)
	v_mul_f32_e32 v105, v14, v193
	v_fmac_f32_e32 v105, v12, v192
	v_fmac_f32_e32 v105, v16, v194
	v_fmac_f32_e32 v105, v18, v195
	v_add_f32_e32 v104, v104, v105
	s_waitcnt lgkmcnt(0)
	v_mul_f32_e32 v105, v15, v197
	v_fmac_f32_e32 v105, v13, v196
	v_fmac_f32_e32 v105, v17, v198
	v_fmac_f32_e32 v105, v19, v199
	v_add_f32_e32 v104, v104, v105
	v_max_f32_e64 v105, -v104, 0
	v_mul_f32_e64 v104, |v104|, s6
	v_exp_f32_e32 v104, v104
	v_cndmask_b32_e64 v103, 0, v103, s[46:47]
	v_add_f32_e32 v1, v1, v103
	v_add_f32_e32 v104, 1.0, v104
	v_cmp_gt_f32_e64 s[0:1], s7, v104
	s_nop 1
	v_cndmask_b32_e64 v106, 0, 32, s[0:1]
	v_ldexp_f32 v104, v104, v106
	v_log_f32_e32 v104, v104
	s_nop 0
	v_mul_f32_e32 v106, 0x3f317217, v104
	v_fma_f32 v106, v104, s8, -v106
	v_fmac_f32_e32 v106, 0x3377d1cf, v104
	v_fmac_f32_e32 v106, 0x3f317217, v104
	v_cmp_lt_f32_e64 s[4:5], |v104|, s9
	s_nop 1
	v_cndmask_b32_e64 v104, v104, v106, s[4:5]
	v_cndmask_b32_e64 v106, 0, v226, s[0:1]
	v_sub_f32_e32 v104, v104, v106
	v_readlane_b32 s0, v254, 58
	v_add_f32_e32 v104, v105, v104
	v_mul_f32_e32 v104, 0xbd800000, v104
	v_mov_b32_e32 v105, s0
	ds_read_b128 v[184:187], v105 offset:4096
	ds_read_b128 v[188:191], v105 offset:4112
	ds_read_b128 v[192:195], v105 offset:4128
	ds_read_b128 v[196:199], v105 offset:4144
	v_cndmask_b32_e64 v104, 0, v104, s[42:43]
	s_waitcnt lgkmcnt(3)
	v_mul_f32_e32 v105, v6, v185
	v_fmac_f32_e32 v105, v4, v184
	s_waitcnt lgkmcnt(2)
	v_mul_f32_e32 v106, v7, v189
	v_fmac_f32_e32 v105, v8, v186
	v_fmac_f32_e32 v106, v5, v188
	v_fmac_f32_e32 v105, v10, v187
	v_fmac_f32_e32 v106, v9, v190
	v_add_f32_e32 v105, v26, v105
	v_fmac_f32_e32 v106, v11, v191
	v_add_f32_e32 v105, v105, v106
	s_waitcnt lgkmcnt(1)
	v_mul_f32_e32 v106, v14, v193
	v_fmac_f32_e32 v106, v12, v192
	v_fmac_f32_e32 v106, v16, v194
	v_fmac_f32_e32 v106, v18, v195
	v_add_f32_e32 v105, v105, v106
	s_waitcnt lgkmcnt(0)
	v_mul_f32_e32 v106, v15, v197
	v_fmac_f32_e32 v106, v13, v196
	v_fmac_f32_e32 v106, v17, v198
	v_fmac_f32_e32 v106, v19, v199
	v_add_f32_e32 v105, v105, v106
	v_max_f32_e64 v106, -v105, 0
	v_mul_f32_e64 v105, |v105|, s6
	v_exp_f32_e32 v105, v105
	v_add_f32_e32 v1, v1, v104
	v_add_f32_e32 v105, 1.0, v105
	v_cmp_gt_f32_e64 s[0:1], s7, v105
	s_nop 1
	v_cndmask_b32_e64 v107, 0, 32, s[0:1]
	v_ldexp_f32 v105, v105, v107
	v_log_f32_e32 v105, v105
	s_nop 0
	v_mul_f32_e32 v107, 0x3f317217, v105
	v_fma_f32 v107, v105, s8, -v107
	v_fmac_f32_e32 v107, 0x3377d1cf, v105
	v_fmac_f32_e32 v107, 0x3f317217, v105
	v_cmp_lt_f32_e64 s[4:5], |v105|, s9
	s_nop 1
	v_cndmask_b32_e64 v105, v105, v107, s[4:5]
	v_cndmask_b32_e64 v107, 0, v226, s[0:1]
	v_readlane_b32 s0, v254, 61
	v_sub_f32_e32 v105, v105, v107
	v_add_f32_e32 v105, v106, v105
	v_mov_b32_e32 v118, s0
	ds_read_b128 v[184:187], v118 offset:4096
	ds_read_b128 v[188:191], v118 offset:4112
	ds_read_b128 v[192:195], v118 offset:4128
	ds_read_b128 v[196:199], v118 offset:4144
	v_mul_f32_e32 v105, 0xbd800000, v105
	s_waitcnt lgkmcnt(3)
	v_mul_f32_e32 v107, v6, v185
	v_fmac_f32_e32 v107, v4, v184
	v_fmac_f32_e32 v107, v8, v186
	v_fmac_f32_e32 v107, v10, v187
	v_add_f32_e32 v106, v26, v107
	s_waitcnt lgkmcnt(2)
	v_mul_f32_e32 v107, v7, v189
	v_fmac_f32_e32 v107, v5, v188
	v_fmac_f32_e32 v107, v9, v190
	v_fmac_f32_e32 v107, v11, v191
	v_add_f32_e32 v106, v106, v107
	s_waitcnt lgkmcnt(1)
	v_mul_f32_e32 v107, v14, v193
	v_fmac_f32_e32 v107, v12, v192
	v_fmac_f32_e32 v107, v16, v194
	v_fmac_f32_e32 v107, v18, v195
	v_add_f32_e32 v106, v106, v107
	s_waitcnt lgkmcnt(0)
	v_mul_f32_e32 v107, v15, v197
	v_fmac_f32_e32 v107, v13, v196
	v_fmac_f32_e32 v107, v17, v198
	v_fmac_f32_e32 v107, v19, v199
	v_add_f32_e32 v106, v106, v107
	v_max_f32_e64 v107, -v106, 0
	v_mul_f32_e64 v106, |v106|, s6
	v_exp_f32_e32 v106, v106
	v_cndmask_b32_e64 v105, 0, v105, s[14:15]
	v_add_f32_e32 v1, v1, v105
	v_add_f32_e32 v106, 1.0, v106
	v_cmp_gt_f32_e64 s[0:1], s7, v106
	s_nop 1
	v_cndmask_b32_e64 v108, 0, 32, s[0:1]
	v_ldexp_f32 v106, v106, v108
	v_log_f32_e32 v106, v106
	s_nop 0
	v_mul_f32_e32 v108, 0x3f317217, v106
	v_fma_f32 v108, v106, s8, -v108
	v_fmac_f32_e32 v108, 0x3377d1cf, v106
	v_fmac_f32_e32 v108, 0x3f317217, v106
	v_cmp_lt_f32_e64 s[4:5], |v106|, s9
	s_nop 1
	v_cndmask_b32_e64 v106, v106, v108, s[4:5]
	v_cndmask_b32_e64 v108, 0, v226, s[0:1]
	v_sub_f32_e32 v106, v106, v108
	v_readlane_b32 s0, v253, 0
	v_add_f32_e32 v106, v107, v106
	v_mul_f32_e32 v106, 0xbd800000, v106
	v_mov_b32_e32 v107, s0
	ds_read_b128 v[184:187], v107 offset:4096
	ds_read_b128 v[188:191], v107 offset:4112
	ds_read_b128 v[192:195], v107 offset:4128
	ds_read_b128 v[196:199], v107 offset:4144
	v_cndmask_b32_e64 v106, 0, v106, s[40:41]
	s_waitcnt lgkmcnt(3)
	v_mul_f32_e32 v107, v6, v185
	v_fmac_f32_e32 v107, v4, v184
	s_waitcnt lgkmcnt(2)
	v_mul_f32_e32 v108, v7, v189
	v_fmac_f32_e32 v107, v8, v186
	v_fmac_f32_e32 v108, v5, v188
	v_fmac_f32_e32 v107, v10, v187
	v_fmac_f32_e32 v108, v9, v190
	v_add_f32_e32 v107, v26, v107
	v_fmac_f32_e32 v108, v11, v191
	v_add_f32_e32 v107, v107, v108
	s_waitcnt lgkmcnt(1)
	v_mul_f32_e32 v108, v14, v193
	v_fmac_f32_e32 v108, v12, v192
	v_fmac_f32_e32 v108, v16, v194
	v_fmac_f32_e32 v108, v18, v195
	v_add_f32_e32 v107, v107, v108
	s_waitcnt lgkmcnt(0)
	v_mul_f32_e32 v108, v15, v197
	v_fmac_f32_e32 v108, v13, v196
	v_fmac_f32_e32 v108, v17, v198
	v_fmac_f32_e32 v108, v19, v199
	v_add_f32_e32 v107, v107, v108
	v_max_f32_e64 v108, -v107, 0
	v_mul_f32_e64 v107, |v107|, s6
	v_exp_f32_e32 v107, v107
	v_add_f32_e32 v1, v1, v106
	v_add_f32_e32 v107, 1.0, v107
	v_cmp_gt_f32_e64 s[0:1], s7, v107
	s_nop 1
	v_cndmask_b32_e64 v109, 0, 32, s[0:1]
	v_ldexp_f32 v107, v107, v109
	v_log_f32_e32 v107, v107
	s_nop 0
	v_mul_f32_e32 v109, 0x3f317217, v107
	v_fma_f32 v109, v107, s8, -v109
	v_fmac_f32_e32 v109, 0x3377d1cf, v107
	v_fmac_f32_e32 v109, 0x3f317217, v107
	v_cmp_lt_f32_e64 s[4:5], |v107|, s9
	s_nop 1
	v_cndmask_b32_e64 v107, v107, v109, s[4:5]
	v_cndmask_b32_e64 v109, 0, v226, s[0:1]
	v_readlane_b32 s0, v253, 3
	v_sub_f32_e32 v107, v107, v109
	v_add_f32_e32 v107, v108, v107
	v_mov_b32_e32 v120, s0
	ds_read_b128 v[184:187], v120 offset:4096
	ds_read_b128 v[188:191], v120 offset:4112
	ds_read_b128 v[192:195], v120 offset:4128
	ds_read_b128 v[196:199], v120 offset:4144
	v_mul_f32_e32 v107, 0xbd800000, v107
	s_waitcnt lgkmcnt(3)
	v_mul_f32_e32 v109, v6, v185
	v_fmac_f32_e32 v109, v4, v184
	v_fmac_f32_e32 v109, v8, v186
	v_fmac_f32_e32 v109, v10, v187
	v_add_f32_e32 v108, v26, v109
	s_waitcnt lgkmcnt(2)
	v_mul_f32_e32 v109, v7, v189
	v_fmac_f32_e32 v109, v5, v188
	v_fmac_f32_e32 v109, v9, v190
	v_fmac_f32_e32 v109, v11, v191
	v_add_f32_e32 v108, v108, v109
	s_waitcnt lgkmcnt(1)
	v_mul_f32_e32 v109, v14, v193
	v_fmac_f32_e32 v109, v12, v192
	v_fmac_f32_e32 v109, v16, v194
	v_fmac_f32_e32 v109, v18, v195
	v_add_f32_e32 v108, v108, v109
	s_waitcnt lgkmcnt(0)
	v_mul_f32_e32 v109, v15, v197
	v_fmac_f32_e32 v109, v13, v196
	v_fmac_f32_e32 v109, v17, v198
	v_fmac_f32_e32 v109, v19, v199
	v_add_f32_e32 v108, v108, v109
	v_max_f32_e64 v109, -v108, 0
	v_mul_f32_e64 v108, |v108|, s6
	v_exp_f32_e32 v108, v108
	v_cndmask_b32_e64 v107, 0, v107, s[36:37]
	v_add_f32_e32 v1, v1, v107
	v_add_f32_e32 v108, 1.0, v108
	v_cmp_gt_f32_e64 s[0:1], s7, v108
	s_nop 1
	v_cndmask_b32_e64 v110, 0, 32, s[0:1]
	v_ldexp_f32 v108, v108, v110
	v_log_f32_e32 v108, v108
	s_nop 0
	v_mul_f32_e32 v110, 0x3f317217, v108
	v_fma_f32 v110, v108, s8, -v110
	v_fmac_f32_e32 v110, 0x3377d1cf, v108
	v_fmac_f32_e32 v110, 0x3f317217, v108
	v_cmp_lt_f32_e64 s[4:5], |v108|, s9
	s_nop 1
	v_cndmask_b32_e64 v108, v108, v110, s[4:5]
	v_cndmask_b32_e64 v110, 0, v226, s[0:1]
	v_sub_f32_e32 v108, v108, v110
	v_readlane_b32 s0, v253, 6
	v_add_f32_e32 v108, v109, v108
	v_mul_f32_e32 v108, 0xbd800000, v108
	v_mov_b32_e32 v109, s0
	ds_read_b128 v[184:187], v109 offset:4096
	ds_read_b128 v[188:191], v109 offset:4112
	ds_read_b128 v[192:195], v109 offset:4128
	ds_read_b128 v[196:199], v109 offset:4144
	v_cndmask_b32_e64 v108, 0, v108, s[34:35]
	s_waitcnt lgkmcnt(3)
	v_mul_f32_e32 v109, v6, v185
	v_fmac_f32_e32 v109, v4, v184
	s_waitcnt lgkmcnt(2)
	v_mul_f32_e32 v110, v7, v189
	v_fmac_f32_e32 v109, v8, v186
	v_fmac_f32_e32 v110, v5, v188
	v_fmac_f32_e32 v109, v10, v187
	v_fmac_f32_e32 v110, v9, v190
	v_add_f32_e32 v109, v26, v109
	v_fmac_f32_e32 v110, v11, v191
	v_add_f32_e32 v109, v109, v110
	s_waitcnt lgkmcnt(1)
	v_mul_f32_e32 v110, v14, v193
	v_fmac_f32_e32 v110, v12, v192
	v_fmac_f32_e32 v110, v16, v194
	v_fmac_f32_e32 v110, v18, v195
	v_add_f32_e32 v109, v109, v110
	s_waitcnt lgkmcnt(0)
	v_mul_f32_e32 v110, v15, v197
	v_fmac_f32_e32 v110, v13, v196
	v_fmac_f32_e32 v110, v17, v198
	v_fmac_f32_e32 v110, v19, v199
	v_add_f32_e32 v109, v109, v110
	v_max_f32_e64 v110, -v109, 0
	v_mul_f32_e64 v109, |v109|, s6
	v_exp_f32_e32 v109, v109
	v_mov_b32_e32 v122, s97
	ds_read_b128 v[184:187], v122 offset:4096
	ds_read_b128 v[188:191], v122 offset:4112
	ds_read_b128 v[192:195], v122 offset:4128
	ds_read_b128 v[196:199], v122 offset:4144
	v_add_f32_e32 v1, v1, v108
	v_add_f32_e32 v109, 1.0, v109
	v_cmp_gt_f32_e64 s[0:1], s7, v109
	s_nop 1
	v_cndmask_b32_e64 v111, 0, 32, s[0:1]
	v_ldexp_f32 v109, v109, v111
	v_log_f32_e32 v109, v109
	s_nop 0
	v_mul_f32_e32 v111, 0x3f317217, v109
	v_fma_f32 v111, v109, s8, -v111
	v_fmac_f32_e32 v111, 0x3377d1cf, v109
	v_fmac_f32_e32 v111, 0x3f317217, v109
	v_cmp_lt_f32_e64 s[4:5], |v109|, s9
	s_nop 1
	v_cndmask_b32_e64 v109, v109, v111, s[4:5]
	v_cndmask_b32_e64 v111, 0, v226, s[0:1]
	v_sub_f32_e32 v109, v109, v111
	v_add_f32_e32 v109, v110, v109
	v_mul_f32_e32 v109, 0xbd800000, v109
	s_waitcnt lgkmcnt(3)
	v_mul_f32_e32 v111, v6, v185
	v_fmac_f32_e32 v111, v4, v184
	v_fmac_f32_e32 v111, v8, v186
	v_fmac_f32_e32 v111, v10, v187
	v_add_f32_e32 v110, v26, v111
	s_waitcnt lgkmcnt(2)
	v_mul_f32_e32 v111, v7, v189
	v_fmac_f32_e32 v111, v5, v188
	v_fmac_f32_e32 v111, v9, v190
	v_fmac_f32_e32 v111, v11, v191
	v_add_f32_e32 v110, v110, v111
	s_waitcnt lgkmcnt(1)
	v_mul_f32_e32 v111, v14, v193
	v_fmac_f32_e32 v111, v12, v192
	v_fmac_f32_e32 v111, v16, v194
	v_fmac_f32_e32 v111, v18, v195
	v_add_f32_e32 v110, v110, v111
	s_waitcnt lgkmcnt(0)
	v_mul_f32_e32 v111, v15, v197
	v_fmac_f32_e32 v111, v13, v196
	v_fmac_f32_e32 v111, v17, v198
	v_fmac_f32_e32 v111, v19, v199
	v_add_f32_e32 v110, v110, v111
	v_max_f32_e64 v111, -v110, 0
	v_mul_f32_e64 v110, |v110|, s6
	v_exp_f32_e32 v110, v110
	v_cndmask_b32_e64 v109, 0, v109, s[30:31]
	v_add_f32_e32 v1, v1, v109
	v_add_f32_e32 v110, 1.0, v110
	v_cmp_gt_f32_e64 s[0:1], s7, v110
	s_nop 1
	v_cndmask_b32_e64 v112, 0, 32, s[0:1]
	v_ldexp_f32 v110, v110, v112
	v_log_f32_e32 v110, v110
	s_nop 0
	v_mul_f32_e32 v112, 0x3f317217, v110
	v_fma_f32 v112, v110, s8, -v112
	v_fmac_f32_e32 v112, 0x3377d1cf, v110
	v_fmac_f32_e32 v112, 0x3f317217, v110
	v_cmp_lt_f32_e64 s[4:5], |v110|, s9
	s_nop 1
	v_cndmask_b32_e64 v110, v110, v112, s[4:5]
	v_cndmask_b32_e64 v112, 0, v226, s[0:1]
	v_sub_f32_e32 v110, v110, v112
	v_add_f32_e32 v110, v111, v110
	v_mov_b32_e32 v111, s95
	ds_read_b128 v[184:187], v111 offset:4096
	ds_read_b128 v[188:191], v111 offset:4112
	ds_read_b128 v[192:195], v111 offset:4128
	ds_read_b128 v[196:199], v111 offset:4144
	v_mul_f32_e32 v110, 0xbd800000, v110
	s_waitcnt lgkmcnt(3)
	v_mul_f32_e32 v111, v6, v185
	v_fmac_f32_e32 v111, v4, v184
	s_waitcnt lgkmcnt(2)
	v_mul_f32_e32 v112, v7, v189
	v_fmac_f32_e32 v111, v8, v186
	v_fmac_f32_e32 v112, v5, v188
	v_fmac_f32_e32 v111, v10, v187
	v_fmac_f32_e32 v112, v9, v190
	v_add_f32_e32 v111, v26, v111
	v_fmac_f32_e32 v112, v11, v191
	v_add_f32_e32 v111, v111, v112
	s_waitcnt lgkmcnt(1)
	v_mul_f32_e32 v112, v14, v193
	v_fmac_f32_e32 v112, v12, v192
	v_fmac_f32_e32 v112, v16, v194
	v_fmac_f32_e32 v112, v18, v195
	v_add_f32_e32 v111, v111, v112
	s_waitcnt lgkmcnt(0)
	v_mul_f32_e32 v112, v15, v197
	v_fmac_f32_e32 v112, v13, v196
	v_fmac_f32_e32 v112, v17, v198
	v_fmac_f32_e32 v112, v19, v199
	v_add_f32_e32 v111, v111, v112
	v_max_f32_e64 v112, -v111, 0
	v_mul_f32_e64 v111, |v111|, s6
	v_exp_f32_e32 v111, v111
	v_mov_b32_e32 v124, s94
	ds_read_b128 v[184:187], v124 offset:4096
	ds_read_b128 v[188:191], v124 offset:4112
	ds_read_b128 v[192:195], v124 offset:4128
	ds_read_b128 v[196:199], v124 offset:4144
	v_cndmask_b32_e64 v110, 0, v110, s[24:25]
	v_add_f32_e32 v1, v1, v110
	v_add_f32_e32 v111, 1.0, v111
	v_cmp_gt_f32_e64 s[0:1], s7, v111
	s_nop 1
	v_cndmask_b32_e64 v113, 0, 32, s[0:1]
	v_ldexp_f32 v111, v111, v113
	v_log_f32_e32 v111, v111
	s_nop 0
	v_mul_f32_e32 v113, 0x3f317217, v111
	v_fma_f32 v113, v111, s8, -v113
	v_fmac_f32_e32 v113, 0x3377d1cf, v111
	v_fmac_f32_e32 v113, 0x3f317217, v111
	v_cmp_lt_f32_e64 s[4:5], |v111|, s9
	s_nop 1
	v_cndmask_b32_e64 v111, v111, v113, s[4:5]
	v_cndmask_b32_e64 v113, 0, v226, s[0:1]
	v_sub_f32_e32 v111, v111, v113
	v_add_f32_e32 v111, v112, v111
	v_mul_f32_e32 v111, 0xbd800000, v111
	s_waitcnt lgkmcnt(3)
	v_mul_f32_e32 v113, v6, v185
	v_fmac_f32_e32 v113, v4, v184
	v_fmac_f32_e32 v113, v8, v186
	v_fmac_f32_e32 v113, v10, v187
	v_add_f32_e32 v112, v26, v113
	s_waitcnt lgkmcnt(2)
	v_mul_f32_e32 v113, v7, v189
	v_fmac_f32_e32 v113, v5, v188
	v_fmac_f32_e32 v113, v9, v190
	v_fmac_f32_e32 v113, v11, v191
	v_add_f32_e32 v112, v112, v113
	s_waitcnt lgkmcnt(1)
	v_mul_f32_e32 v113, v14, v193
	v_fmac_f32_e32 v113, v12, v192
	v_fmac_f32_e32 v113, v16, v194
	v_fmac_f32_e32 v113, v18, v195
	v_add_f32_e32 v112, v112, v113
	s_waitcnt lgkmcnt(0)
	v_mul_f32_e32 v113, v15, v197
	v_fmac_f32_e32 v113, v13, v196
	v_fmac_f32_e32 v113, v17, v198
	v_fmac_f32_e32 v113, v19, v199
	v_add_f32_e32 v112, v112, v113
	v_max_f32_e64 v113, -v112, 0
	v_mul_f32_e64 v112, |v112|, s6
	v_exp_f32_e32 v112, v112
	v_cndmask_b32_e64 v111, 0, v111, s[44:45]
	v_add_f32_e32 v1, v1, v111
	v_add_f32_e32 v112, 1.0, v112
	v_cmp_gt_f32_e64 s[0:1], s7, v112
	s_nop 1
	v_cndmask_b32_e64 v114, 0, 32, s[0:1]
	v_ldexp_f32 v112, v112, v114
	v_log_f32_e32 v112, v112
	s_nop 0
	v_mul_f32_e32 v114, 0x3f317217, v112
	v_fma_f32 v114, v112, s8, -v114
	v_fmac_f32_e32 v114, 0x3377d1cf, v112
	v_fmac_f32_e32 v114, 0x3f317217, v112
	v_cmp_lt_f32_e64 s[4:5], |v112|, s9
	s_nop 1
	v_cndmask_b32_e64 v112, v112, v114, s[4:5]
	v_cndmask_b32_e64 v114, 0, v226, s[0:1]
	v_sub_f32_e32 v112, v112, v114
	v_add_f32_e32 v112, v113, v112
	v_mov_b32_e32 v113, s93
	ds_read_b128 v[184:187], v113 offset:4096
	ds_read_b128 v[188:191], v113 offset:4112
	ds_read_b128 v[192:195], v113 offset:4128
	ds_read_b128 v[196:199], v113 offset:4144
	v_mul_f32_e32 v112, 0xbd800000, v112
	s_waitcnt lgkmcnt(3)
	v_mul_f32_e32 v113, v6, v185
	v_fmac_f32_e32 v113, v4, v184
	s_waitcnt lgkmcnt(2)
	v_mul_f32_e32 v114, v7, v189
	v_fmac_f32_e32 v113, v8, v186
	v_fmac_f32_e32 v114, v5, v188
	v_fmac_f32_e32 v113, v10, v187
	v_fmac_f32_e32 v114, v9, v190
	v_add_f32_e32 v113, v26, v113
	v_fmac_f32_e32 v114, v11, v191
	v_add_f32_e32 v113, v113, v114
	s_waitcnt lgkmcnt(1)
	v_mul_f32_e32 v114, v14, v193
	v_fmac_f32_e32 v114, v12, v192
	v_fmac_f32_e32 v114, v16, v194
	v_fmac_f32_e32 v114, v18, v195
	v_add_f32_e32 v113, v113, v114
	s_waitcnt lgkmcnt(0)
	v_mul_f32_e32 v114, v15, v197
	v_fmac_f32_e32 v114, v13, v196
	v_fmac_f32_e32 v114, v17, v198
	v_fmac_f32_e32 v114, v19, v199
	v_add_f32_e32 v113, v113, v114
	v_max_f32_e64 v114, -v113, 0
	v_mul_f32_e64 v113, |v113|, s6
	v_exp_f32_e32 v113, v113
	v_mov_b32_e32 v126, s92
	ds_read_b128 v[184:187], v126 offset:4096
	ds_read_b128 v[188:191], v126 offset:4112
	ds_read_b128 v[192:195], v126 offset:4128
	v_cndmask_b32_e64 v112, 0, v112, s[26:27]
	v_add_f32_e32 v1, v1, v112
	v_add_f32_e32 v113, 1.0, v113
	v_cmp_gt_f32_e64 s[0:1], s7, v113
	s_nop 1
	v_cndmask_b32_e64 v115, 0, 32, s[0:1]
	v_ldexp_f32 v113, v113, v115
	v_log_f32_e32 v113, v113
	s_nop 0
	v_mul_f32_e32 v115, 0x3f317217, v113
	v_fma_f32 v115, v113, s8, -v115
	v_fmac_f32_e32 v115, 0x3377d1cf, v113
	v_fmac_f32_e32 v115, 0x3f317217, v113
	v_cmp_lt_f32_e64 s[4:5], |v113|, s9
	s_nop 1
	v_cndmask_b32_e64 v113, v113, v115, s[4:5]
	v_cndmask_b32_e64 v115, 0, v226, s[0:1]
	v_sub_f32_e32 v113, v113, v115
	v_add_f32_e32 v113, v114, v113
	ds_read_b128 v[126:129], v126 offset:4144
	v_mul_f32_e32 v113, 0xbd800000, v113
	s_waitcnt lgkmcnt(3)
	v_mul_f32_e32 v115, v6, v185
	v_fmac_f32_e32 v115, v4, v184
	v_fmac_f32_e32 v115, v8, v186
	v_fmac_f32_e32 v115, v10, v187
	v_add_f32_e32 v114, v26, v115
	s_waitcnt lgkmcnt(2)
	v_mul_f32_e32 v115, v7, v189
	v_fmac_f32_e32 v115, v5, v188
	v_fmac_f32_e32 v115, v9, v190
	v_fmac_f32_e32 v115, v11, v191
	v_add_f32_e32 v118, v114, v115
	s_waitcnt lgkmcnt(0)
	v_mov_b32_e32 v115, v126
	v_mov_b32_e32 v126, v193
	v_mov_b32_e32 v114, v192
	v_pk_mul_f32 v[116:117], v[14:15], v[126:127]
	v_cndmask_b32_e64 v113, 0, v113, s[28:29]
	v_pk_fma_f32 v[114:115], v[12:13], v[114:115], v[116:117]
	v_mov_b32_e32 v116, v194
	v_mov_b32_e32 v117, v128
	v_pk_fma_f32 v[114:115], v[16:17], v[116:117], v[114:115]
	v_mov_b32_e32 v128, v195
	v_pk_fma_f32 v[114:115], v[18:19], v[128:129], v[114:115]
	v_add_f32_e32 v1, v1, v113
	v_add_f32_e32 v114, v118, v114
	v_add_f32_e32 v114, v114, v115
	v_max_f32_e64 v115, -v114, 0
	v_mul_f32_e64 v114, |v114|, s6
	v_exp_f32_e32 v114, v114
	s_nop 0
	v_add_f32_e32 v114, 1.0, v114
	v_cmp_gt_f32_e64 s[0:1], s7, v114
	s_nop 1
	v_cndmask_b32_e64 v116, 0, 32, s[0:1]
	v_ldexp_f32 v114, v114, v116
	v_log_f32_e32 v114, v114
	s_nop 0
	v_mul_f32_e32 v116, 0x3f317217, v114
	v_fma_f32 v116, v114, s8, -v116
	v_fmac_f32_e32 v116, 0x3377d1cf, v114
	v_fmac_f32_e32 v116, 0x3f317217, v114
	v_cmp_lt_f32_e64 s[4:5], |v114|, s9
	s_nop 1
	v_cndmask_b32_e64 v114, v114, v116, s[4:5]
	v_cndmask_b32_e64 v116, 0, v226, s[0:1]
	v_sub_f32_e32 v114, v114, v116
	v_readlane_b32 s0, v254, 19
	v_add_f32_e32 v114, v115, v114
	v_mul_f32_e32 v114, 0xbd800000, v114
	v_mov_b32_e32 v115, s0
	ds_read_b128 v[184:187], v115 offset:4096
	ds_read_b128 v[188:191], v115 offset:4112
	ds_read_b128 v[192:195], v115 offset:4128
	ds_read_b128 v[128:131], v115 offset:4144
	v_cndmask_b32_e64 v114, 0, v114, s[22:23]
	s_waitcnt lgkmcnt(3)
	v_mul_f32_e32 v115, v6, v185
	v_fmac_f32_e32 v115, v4, v184
	s_waitcnt lgkmcnt(2)
	v_mul_f32_e32 v116, v7, v189
	v_fmac_f32_e32 v115, v8, v186
	v_fmac_f32_e32 v116, v5, v188
	v_fmac_f32_e32 v115, v10, v187
	v_fmac_f32_e32 v116, v9, v190
	v_add_f32_e32 v115, v26, v115
	v_fmac_f32_e32 v116, v11, v191
	s_waitcnt lgkmcnt(0)
	v_mov_b32_e32 v117, v128
	v_mov_b32_e32 v128, v193
	v_add_f32_e32 v115, v115, v116
	v_mov_b32_e32 v116, v192
	v_pk_mul_f32 v[118:119], v[14:15], v[128:129]
	v_mov_b32_e32 v128, s96
	ds_read_b128 v[184:187], v128 offset:4096
	v_pk_fma_f32 v[116:117], v[12:13], v[116:117], v[118:119]
	v_mov_b32_e32 v118, v194
	v_mov_b32_e32 v119, v130
	v_pk_fma_f32 v[116:117], v[16:17], v[118:119], v[116:117]
	v_mov_b32_e32 v130, v195
	v_pk_fma_f32 v[116:117], v[18:19], v[130:131], v[116:117]
	v_add_f32_e32 v1, v1, v114
	v_add_f32_e32 v115, v115, v116
	v_add_f32_e32 v115, v115, v117
	v_max_f32_e64 v116, -v115, 0
	v_mul_f32_e64 v115, |v115|, s6
	v_exp_f32_e32 v115, v115
	s_nop 0
	v_add_f32_e32 v115, 1.0, v115
	v_cmp_gt_f32_e64 s[0:1], s7, v115
	s_nop 1
	v_cndmask_b32_e64 v117, 0, 32, s[0:1]
	v_ldexp_f32 v115, v115, v117
	v_log_f32_e32 v115, v115
	s_nop 0
	v_mul_f32_e32 v117, 0x3f317217, v115
	v_fma_f32 v117, v115, s8, -v117
	v_fmac_f32_e32 v117, 0x3377d1cf, v115
	v_fmac_f32_e32 v117, 0x3f317217, v115
	v_cmp_lt_f32_e64 s[4:5], |v115|, s9
	s_nop 1
	v_cndmask_b32_e64 v115, v115, v117, s[4:5]
	v_cndmask_b32_e64 v117, 0, v226, s[0:1]
	v_sub_f32_e32 v115, v115, v117
	v_add_f32_e32 v115, v116, v115
	ds_read_b128 v[188:191], v128 offset:4128
	ds_read_b128 v[120:123], v128 offset:4112
	ds_read_b128 v[128:131], v128 offset:4144
	v_mul_f32_e32 v115, 0xbd800000, v115
	s_waitcnt lgkmcnt(3)
	v_mov_b32_e32 v132, v184
	s_waitcnt lgkmcnt(1)
	v_mov_b32_e32 v133, v120
	v_mov_b32_e32 v120, v185
	v_pk_mul_f32 v[116:117], v[6:7], v[120:121]
	v_mov_b32_e32 v120, v186
	v_pk_fma_f32 v[116:117], v[4:5], v[132:133], v[116:117]
	v_mov_b32_e32 v121, v122
	v_pk_fma_f32 v[116:117], v[8:9], v[120:121], v[116:117]
	v_mov_b32_e32 v122, v187
	v_pk_fma_f32 v[116:117], v[10:11], v[122:123], v[116:117]
	v_cndmask_b32_e64 v115, 0, v115, s[10:11]
	v_add_f32_e32 v116, v26, v116
	v_add_f32_e32 v120, v116, v117
	s_waitcnt lgkmcnt(0)
	v_mov_b32_e32 v117, v128
	v_mov_b32_e32 v128, v189
	v_mov_b32_e32 v116, v188
	v_pk_mul_f32 v[118:119], v[14:15], v[128:129]
	v_add_f32_e32 v1, v1, v115
	v_pk_fma_f32 v[116:117], v[12:13], v[116:117], v[118:119]
	v_mov_b32_e32 v118, v190
	v_mov_b32_e32 v119, v130
	v_pk_fma_f32 v[116:117], v[16:17], v[118:119], v[116:117]
	v_mov_b32_e32 v130, v191
	v_pk_fma_f32 v[116:117], v[18:19], v[130:131], v[116:117]
	s_nop 0
	v_add_f32_e32 v116, v120, v116
	v_add_f32_e32 v116, v116, v117
	v_max_f32_e64 v117, -v116, 0
	v_mul_f32_e64 v116, |v116|, s6
	v_exp_f32_e32 v116, v116
	s_nop 0
	v_add_f32_e32 v116, 1.0, v116
	v_cmp_gt_f32_e64 s[0:1], s7, v116
	s_nop 1
	v_cndmask_b32_e64 v118, 0, 32, s[0:1]
	v_ldexp_f32 v116, v116, v118
	v_log_f32_e32 v116, v116
	s_nop 0
	v_mul_f32_e32 v118, 0x3f317217, v116
	v_fma_f32 v118, v116, s8, -v118
	v_fmac_f32_e32 v118, 0x3377d1cf, v116
	v_fmac_f32_e32 v118, 0x3f317217, v116
	v_cmp_lt_f32_e64 s[4:5], |v116|, s9
	s_nop 1
	v_cndmask_b32_e64 v116, v116, v118, s[4:5]
	v_cndmask_b32_e64 v118, 0, v226, s[0:1]
	v_sub_f32_e32 v116, v116, v118
	v_add_f32_e32 v116, v117, v116
	v_mov_b32_e32 v117, s68
	ds_read_b128 v[184:187], v117 offset:4096
	ds_read_b128 v[188:191], v117 offset:4128
	ds_read_b128 v[122:125], v117 offset:4112
	ds_read_b128 v[130:133], v117 offset:4144
	v_mul_f32_e32 v116, 0xbd800000, v116
	s_waitcnt lgkmcnt(3)
	v_mov_b32_e32 v134, v184
	s_waitcnt lgkmcnt(1)
	v_mov_b32_e32 v135, v122
	v_mov_b32_e32 v122, v185
	v_pk_mul_f32 v[118:119], v[6:7], v[122:123]
	v_mov_b32_e32 v122, v186
	v_pk_fma_f32 v[118:119], v[4:5], v[134:135], v[118:119]
	v_mov_b32_e32 v123, v124
	v_pk_fma_f32 v[118:119], v[8:9], v[122:123], v[118:119]
	v_mov_b32_e32 v124, v187
	v_pk_fma_f32 v[118:119], v[10:11], v[124:125], v[118:119]
	v_cndmask_b32_e64 v116, 0, v116, s[18:19]
	v_add_f32_e32 v117, v26, v118
	v_add_f32_e32 v117, v117, v119
	s_waitcnt lgkmcnt(0)
	v_mov_b32_e32 v119, v130
	v_mov_b32_e32 v130, v189
	v_mov_b32_e32 v118, v188
	v_pk_mul_f32 v[120:121], v[14:15], v[130:131]
	v_mov_b32_e32 v130, s66
	ds_read_b128 v[184:187], v130 offset:4096
	v_pk_fma_f32 v[118:119], v[12:13], v[118:119], v[120:121]
	v_mov_b32_e32 v120, v190
	v_mov_b32_e32 v121, v132
	v_pk_fma_f32 v[118:119], v[16:17], v[120:121], v[118:119]
	v_mov_b32_e32 v132, v191
	v_pk_fma_f32 v[118:119], v[18:19], v[132:133], v[118:119]
	v_add_f32_e32 v1, v1, v116
	v_add_f32_e32 v117, v117, v118
	v_add_f32_e32 v117, v117, v119
	v_max_f32_e64 v118, -v117, 0
	v_mul_f32_e64 v117, |v117|, s6
	v_exp_f32_e32 v117, v117
	s_nop 0
	v_add_f32_e32 v117, 1.0, v117
	v_cmp_gt_f32_e64 s[0:1], s7, v117
	s_nop 1
	v_cndmask_b32_e64 v119, 0, 32, s[0:1]
	v_ldexp_f32 v117, v117, v119
	v_log_f32_e32 v117, v117
	s_nop 0
	v_mul_f32_e32 v119, 0x3f317217, v117
	v_fma_f32 v119, v117, s8, -v119
	v_fmac_f32_e32 v119, 0x3377d1cf, v117
	v_fmac_f32_e32 v119, 0x3f317217, v117
	v_cmp_lt_f32_e64 s[4:5], |v117|, s9
	s_nop 1
	v_cndmask_b32_e64 v117, v117, v119, s[4:5]
	v_cndmask_b32_e64 v119, 0, v226, s[0:1]
	v_sub_f32_e32 v117, v117, v119
	v_add_f32_e32 v117, v118, v117
	ds_read_b128 v[188:191], v130 offset:4128
	ds_read_b128 v[122:125], v130 offset:4112
	ds_read_b128 v[130:133], v130 offset:4144
	v_mul_f32_e32 v117, 0xbd800000, v117
	s_waitcnt lgkmcnt(3)
	v_mov_b32_e32 v134, v184
	s_waitcnt lgkmcnt(1)
	v_mov_b32_e32 v135, v122
	v_mov_b32_e32 v122, v185
	v_pk_mul_f32 v[118:119], v[6:7], v[122:123]
	v_mov_b32_e32 v122, v186
	v_pk_fma_f32 v[118:119], v[4:5], v[134:135], v[118:119]
	v_mov_b32_e32 v123, v124
	v_pk_fma_f32 v[118:119], v[8:9], v[122:123], v[118:119]
	v_mov_b32_e32 v124, v187
	v_pk_fma_f32 v[118:119], v[10:11], v[124:125], v[118:119]
	v_cndmask_b32_e64 v117, 0, v117, s[20:21]
	v_add_f32_e32 v118, v26, v118
	v_add_f32_e32 v122, v118, v119
	s_waitcnt lgkmcnt(0)
	v_mov_b32_e32 v119, v130
	v_mov_b32_e32 v130, v189
	v_mov_b32_e32 v118, v188
	v_pk_mul_f32 v[120:121], v[14:15], v[130:131]
	v_add_f32_e32 v1, v1, v117
	v_pk_fma_f32 v[118:119], v[12:13], v[118:119], v[120:121]
	v_mov_b32_e32 v120, v190
	v_mov_b32_e32 v121, v132
	v_pk_fma_f32 v[118:119], v[16:17], v[120:121], v[118:119]
	v_mov_b32_e32 v132, v191
	v_pk_fma_f32 v[118:119], v[18:19], v[132:133], v[118:119]
	s_nop 0
	v_add_f32_e32 v118, v122, v118
	v_add_f32_e32 v118, v118, v119
	v_max_f32_e64 v119, -v118, 0
	v_mul_f32_e64 v118, |v118|, s6
	v_exp_f32_e32 v118, v118
	s_nop 0
	v_add_f32_e32 v118, 1.0, v118
	v_cmp_gt_f32_e64 s[0:1], s7, v118
	s_nop 1
	v_cndmask_b32_e64 v120, 0, 32, s[0:1]
	v_ldexp_f32 v118, v118, v120
	v_log_f32_e32 v118, v118
	s_nop 0
	v_mul_f32_e32 v120, 0x3f317217, v118
	v_fma_f32 v120, v118, s8, -v120
	v_fmac_f32_e32 v120, 0x3377d1cf, v118
	v_fmac_f32_e32 v120, 0x3f317217, v118
	v_cmp_lt_f32_e64 s[4:5], |v118|, s9
	s_nop 1
	v_cndmask_b32_e64 v118, v118, v120, s[4:5]
	v_cndmask_b32_e64 v120, 0, v226, s[0:1]
	v_sub_f32_e32 v118, v118, v120
	v_add_f32_e32 v118, v119, v118
	v_mov_b32_e32 v119, s60
	ds_read_b128 v[120:123], v119 offset:4096
	ds_read_b128 v[124:127], v119 offset:4112
	ds_read_b128 v[128:131], v119 offset:4128
	ds_read_b128 v[132:135], v119 offset:4144
	v_mul_f32_e32 v118, 0xbd800000, v118
	s_waitcnt lgkmcnt(3)
	v_mov_b32_e32 v136, v120
	s_waitcnt lgkmcnt(2)
	v_mov_b32_e32 v137, v124
	v_mov_b32_e32 v124, v121
	v_pk_mul_f32 v[6:7], v[6:7], v[124:125]
	v_cndmask_b32_e64 v118, 0, v118, s[12:13]
	v_pk_fma_f32 v[4:5], v[4:5], v[136:137], v[6:7]
	v_mov_b32_e32 v6, v122
	v_mov_b32_e32 v7, v126
	v_pk_fma_f32 v[4:5], v[8:9], v[6:7], v[4:5]
	v_mov_b32_e32 v126, v123
	v_pk_fma_f32 v[4:5], v[10:11], v[126:127], v[4:5]
	v_add_f32_e32 v1, v1, v118
	v_add_f32_e32 v4, v26, v4
	v_add_f32_e32 v8, v4, v5
	s_waitcnt lgkmcnt(0)
	v_mov_b32_e32 v5, v132
	v_mov_b32_e32 v132, v129
	v_mov_b32_e32 v4, v128
	v_pk_mul_f32 v[6:7], v[14:15], v[132:133]
	s_nop 0
	v_pk_fma_f32 v[4:5], v[12:13], v[4:5], v[6:7]
	v_mov_b32_e32 v6, v130
	v_mov_b32_e32 v7, v134
	v_pk_fma_f32 v[4:5], v[16:17], v[6:7], v[4:5]
	v_mov_b32_e32 v134, v131
	v_pk_fma_f32 v[4:5], v[18:19], v[134:135], v[4:5]
	s_nop 0
	v_add_f32_e32 v4, v8, v4
	v_add_f32_e32 v4, v4, v5
	v_max_f32_e64 v5, -v4, 0
	v_mul_f32_e64 v4, |v4|, s6
	v_exp_f32_e32 v4, v4
	s_nop 0
	v_add_f32_e32 v4, 1.0, v4
	v_cmp_gt_f32_e64 s[0:1], s7, v4
	s_mov_b64 s[6:7], s[88:89]
	s_nop 0
	v_cndmask_b32_e64 v6, 0, 32, s[0:1]
	v_ldexp_f32 v4, v4, v6
	v_log_f32_e32 v4, v4
	s_nop 0
	v_mul_f32_e32 v6, 0x3f317217, v4
	v_fma_f32 v6, v4, s8, -v6
	v_fmac_f32_e32 v6, 0x3377d1cf, v4
	v_fmac_f32_e32 v6, 0x3f317217, v4
	v_cmp_lt_f32_e64 s[4:5], |v4|, s9
	s_nop 1
	v_cndmask_b32_e64 v4, v4, v6, s[4:5]
	v_cndmask_b32_e64 v6, 0, v226, s[0:1]
	v_sub_f32_e32 v4, v4, v6
	v_readlane_b32 s4, v253, 10
	v_add_f32_e32 v4, v5, v4
	v_readlane_b32 s5, v253, 11
	v_mul_f32_e32 v4, 0xbd800000, v4
	v_lshl_add_u64 v[6:7], s[84:85], 0, v[2:3]
	v_cndmask_b32_e64 v12, 0, v4, s[4:5]
	v_lshlrev_b32_sdwa v4, v228, v25 dst_sel:DWORD dst_unused:UNUSED_PAD src0_sel:DWORD src1_sel:BYTE_0
	v_add_f32_e32 v1, v1, v12
	v_add_u32_e32 v5, s50, v4
	ds_write_b32 v5, v1
	v_add_u32_e32 v1, 0, v4
	s_waitcnt lgkmcnt(0)
	s_barrier
	ds_read2st64_b32 v[4:5], v1 offset1:4
	v_lshl_add_u64 v[2:3], s[86:87], 0, v[2:3]
	s_waitcnt lgkmcnt(0)
	v_cndmask_b32_e64 v1, v4, 0, s[6:7]
	v_add_f32_e32 v9, v22, v1
	v_sub_f32_e32 v1, v4, v9
	v_mul_f32_e32 v1, 0x3fb8aa3b, v1
	v_exp_f32_e32 v1, v1
	s_nop 0
	v_mul_f32_e32 v8, v1, v89
	s_cbranch_scc1 .LBB0_531
	v_sub_f32_e32 v1, v9, v4
	v_mul_f32_e32 v1, 0x3fb8aa3b, v1
	v_exp_f32_e32 v1, v1
	v_lshlrev_b32_e32 v10, 16, v86
	v_mul_f32_e32 v1, v1, v10
	v_cvt_pk_bf16_f32 v1, v1, s0
	s_lshl_b64 s[0:1], s[38:39], 11
	v_lshl_add_u64 v[10:11], v[6:7], 0, s[0:1]
	global_store_short v[10:11], v1, off
	v_cvt_pk_bf16_f32 v1, v8, s0
	v_lshl_add_u64 v[10:11], v[2:3], 0, s[0:1]
	global_store_short v[10:11], v1, off

.LBB0_707:
	ds_read_b64_tr_b16 v[134:135], v211
	ds_read_b64_tr_b16 v[136:137], v211 offset:1088
	ds_read_b64_tr_b16 v[130:131], v211 offset:8704
	ds_read_b64_tr_b16 v[132:133], v211 offset:9792
	v_mov_b32_e32 v138, 0
	s_andn2_b64 vcc, exec, s[18:19]
	v_mov_b32_e32 v140, 0
	v_mov_b32_e32 v141, 0
	v_mov_b32_e32 v142, 0
	v_mov_b32_e32 v143, 0
	s_cbranch_vccnz .LBB0_709
	ds_read_b128 v[102:105], v221
	ds_read_b128 v[106:109], v232
	ds_read_b128 v[110:113], v221 offset:64
	ds_read_b128 v[114:117], v232 offset:64
	ds_read_b128 v[118:121], v221 offset:128
	ds_read_b128 v[122:125], v232 offset:128
	s_waitcnt lgkmcnt(6)
	s_waitcnt lgkmcnt(4)
	v_mfma_f32_16x16x32_bf16 v[140:143], v[102:105], v[106:109], 0
	ds_read_b128 v[102:105], v221 offset:192
	ds_read_b128 v[106:109], v232 offset:192
	s_waitcnt lgkmcnt(4)
	v_mfma_f32_16x16x32_bf16 v[140:143], v[110:113], v[114:117], v[140:143]
	ds_read_b128 v[110:113], v221 offset:256
	ds_read_b128 v[114:117], v232 offset:256
	s_waitcnt lgkmcnt(4)
	v_mfma_f32_16x16x32_bf16 v[140:143], v[118:121], v[122:125], v[140:143]
	ds_read_b128 v[118:121], v221 offset:320
	ds_read_b128 v[122:125], v232 offset:320
	s_waitcnt lgkmcnt(4)
	v_mfma_f32_16x16x32_bf16 v[140:143], v[102:105], v[106:109], v[140:143]
	ds_read_b128 v[102:105], v221 offset:384
	ds_read_b128 v[106:109], v232 offset:384
	s_waitcnt lgkmcnt(4)
	v_mfma_f32_16x16x32_bf16 v[140:143], v[110:113], v[114:117], v[140:143]
	s_waitcnt lgkmcnt(2)
	v_mfma_f32_16x16x32_bf16 v[140:143], v[118:121], v[122:125], v[140:143]
	s_waitcnt lgkmcnt(0)
	v_mfma_f32_16x16x32_bf16 v[140:143], v[102:105], v[106:109], v[140:143]
	ds_read_b128 v[144:147], v221 offset:448
	ds_read_b128 v[148:151], v232 offset:448
	s_waitcnt lgkmcnt(0)
	v_mfma_f32_16x16x32_bf16 v[140:143], v[144:147], v[148:151], v[140:143]
.LBB0_709:
	s_nop 7
	v_cndmask_b32_e64 v1, v140, 0, s[40:41]
	v_cndmask_b32_e64 v35, 0, v141, s[42:43]
	v_cndmask_b32_e64 v1, v1, v140, s[42:43]
	v_cndmask_b32_e64 v37, v142, 0, s[44:45]
	v_cndmask_b32_e64 v139, v143, 0, s[46:47]
	v_cvt_pk_bf16_f32 v36, v1, v35
	v_cvt_pk_bf16_f32 v37, v37, v139
	s_andn2_b64 vcc, exec, s[20:21]
	v_mov_b32_e32 v139, 0
	v_mov_b32_e32 v140, 0
	v_mov_b32_e32 v141, 0
	ds_write_b64 v212, v[36:37]
	s_cbranch_vccnz .LBB0_711
	ds_read_b128 v[102:105], v221 offset:8448
	ds_read_b128 v[106:109], v232
	ds_read_b128 v[110:113], v221 offset:8512
	ds_read_b128 v[114:117], v232 offset:64
	ds_read_b128 v[118:121], v221 offset:8576
	ds_read_b128 v[122:125], v232 offset:128
	s_waitcnt lgkmcnt(6)
	s_waitcnt lgkmcnt(4)
	v_mfma_f32_16x16x32_bf16 v[138:141], v[102:105], v[106:109], 0
	ds_read_b128 v[102:105], v221 offset:8640
	ds_read_b128 v[106:109], v232 offset:192
	s_waitcnt lgkmcnt(4)
	v_mfma_f32_16x16x32_bf16 v[138:141], v[110:113], v[114:117], v[138:141]
	ds_read_b128 v[110:113], v221 offset:8704
	ds_read_b128 v[114:117], v232 offset:256
	s_waitcnt lgkmcnt(4)
	v_mfma_f32_16x16x32_bf16 v[138:141], v[118:121], v[122:125], v[138:141]
	ds_read_b128 v[118:121], v221 offset:8768
	ds_read_b128 v[122:125], v232 offset:320
	s_waitcnt lgkmcnt(4)
	v_mfma_f32_16x16x32_bf16 v[138:141], v[102:105], v[106:109], v[138:141]
	ds_read_b128 v[102:105], v221 offset:8832
	ds_read_b128 v[106:109], v232 offset:384
	s_waitcnt lgkmcnt(4)
	v_mfma_f32_16x16x32_bf16 v[138:141], v[110:113], v[114:117], v[138:141]
	s_waitcnt lgkmcnt(2)
	v_mfma_f32_16x16x32_bf16 v[138:141], v[118:121], v[122:125], v[138:141]
	s_waitcnt lgkmcnt(0)
	v_mfma_f32_16x16x32_bf16 v[138:141], v[102:105], v[106:109], v[138:141]
	ds_read_b128 v[142:145], v221 offset:8896
	ds_read_b128 v[146:149], v232 offset:448
	s_waitcnt lgkmcnt(0)
	v_mfma_f32_16x16x32_bf16 v[138:141], v[142:145], v[146:149], v[138:141]
.LBB0_711:
	s_nop 7
	v_cndmask_b32_e64 v1, v138, 0, s[48:49]
	v_cndmask_b32_e64 v35, v139, 0, s[50:51]
	v_cndmask_b32_e64 v37, v140, 0, s[52:53]
	v_cndmask_b32_e64 v138, v141, 0, s[54:55]
	v_cvt_pk_bf16_f32 v36, v1, v35
	v_cvt_pk_bf16_f32 v37, v37, v138
	ds_write_b64 v213, v[36:37]
	ds_read_b128 v[102:105], v155
	ds_read_b128 v[106:109], v180
	ds_read_b64 v[110:111], v157
	ds_read_b64 v[112:113], v157 offset:32
	v_add_u32_e32 v1, 0x2000, v157
	ds_read_b64 v[114:115], v1 offset:256
	ds_read_b64 v[116:117], v1 offset:288
	v_add_u32_e32 v35, 0x4000, v157
	ds_read_b64 v[118:119], v35 offset:512
	ds_read_b64 v[120:121], v35 offset:544
	v_add_u32_e32 v246, 0x6000, v157
	ds_read_b64 v[122:123], v246 offset:768
	ds_read_b64 v[124:125], v246 offset:800
	s_waitcnt lgkmcnt(11)
	s_waitcnt lgkmcnt(9)
	v_pk_mul_f32 v[36:37], v[4:5], v[104:105]
	ds_read_b128 v[126:129], v181
	v_pk_mul_f32 v[138:139], v[2:3], v[102:103]
	s_waitcnt lgkmcnt(9)
	v_pk_mul_f32 v[140:141], v[10:11], v[106:107]
	ds_read_b128 v[102:105], v182
	v_cvt_pk_bf16_f32 v138, v138, v139
	v_cvt_pk_bf16_f32 v139, v36, v37
	v_pk_mul_f32 v[36:37], v[12:13], v[108:109]
	v_cvt_pk_bf16_f32 v140, v140, v141
	v_cvt_pk_bf16_f32 v141, v36, v37
	s_nop 0
	s_waitcnt lgkmcnt(8)
	v_mfma_f32_16x16x32_bf16 v[142:145], v[138:141], v[110:113], 0
	ds_read_b64 v[106:107], v157 offset:64
	ds_read_b64 v[108:109], v157 offset:96
	s_andn2_b64 vcc, exec, s[22:23]
	s_waitcnt lgkmcnt(8)
	v_mfma_f32_16x16x32_bf16 v[146:149], v[138:141], v[114:117], 0
	ds_read_b64 v[110:111], v1 offset:320
	ds_read_b64 v[112:113], v1 offset:352
	s_waitcnt lgkmcnt(8)
	v_mfma_f32_16x16x32_bf16 v[150:153], v[138:141], v[118:121], 0
	ds_read_b64 v[114:115], v35 offset:576
	ds_read_b64 v[116:117], v35 offset:608
	s_waitcnt lgkmcnt(8)
	v_mfma_f32_16x16x32_bf16 v[138:141], v[138:141], v[122:125], 0
	ds_read_b64 v[118:119], v246 offset:832
	ds_read_b64 v[120:121], v246 offset:864
	s_waitcnt lgkmcnt(9)
	v_pk_mul_f32 v[36:37], v[8:9], v[128:129]
	ds_read_b128 v[122:125], v183
	v_pk_mul_f32 v[234:235], v[6:7], v[126:127]
	s_waitcnt lgkmcnt(9)
	v_pk_mul_f32 v[236:237], v[14:15], v[102:103]
	ds_read_b128 v[126:129], v184
	v_cvt_pk_bf16_f32 v234, v234, v235
	v_cvt_pk_bf16_f32 v235, v36, v37
	v_pk_mul_f32 v[36:37], v[16:17], v[104:105]
	v_cvt_pk_bf16_f32 v236, v236, v237
	v_cvt_pk_bf16_f32 v237, v36, v37
	s_nop 0
	s_waitcnt lgkmcnt(8)
	v_mfma_f32_16x16x32_bf16 v[142:145], v[234:237], v[106:109], v[142:145]
	ds_read_b64 v[102:103], v157 offset:128
	ds_read_b64 v[104:105], v157 offset:160
	s_waitcnt lgkmcnt(8)
	v_mfma_f32_16x16x32_bf16 v[146:149], v[234:237], v[110:113], v[146:149]
	ds_read_b64 v[106:107], v1 offset:384
	ds_read_b64 v[108:109], v1 offset:416
	s_waitcnt lgkmcnt(8)
	v_mfma_f32_16x16x32_bf16 v[150:153], v[234:237], v[114:117], v[150:153]
	ds_read_b64 v[110:111], v35 offset:640
	ds_read_b64 v[112:113], v35 offset:672
	s_waitcnt lgkmcnt(8)
	v_mfma_f32_16x16x32_bf16 v[138:141], v[234:237], v[118:121], v[138:141]
	ds_read_b64 v[114:115], v246 offset:896
	ds_read_b64 v[116:117], v246 offset:928
	s_waitcnt lgkmcnt(9)
	v_pk_mul_f32 v[36:37], v[20:21], v[124:125]
	ds_read_b128 v[118:121], v185
	v_pk_mul_f32 v[234:235], v[18:19], v[122:123]
	s_waitcnt lgkmcnt(9)
	v_pk_mul_f32 v[236:237], v[22:23], v[126:127]
	ds_read_b128 v[122:125], v186
	v_cvt_pk_bf16_f32 v234, v234, v235
	v_cvt_pk_bf16_f32 v235, v36, v37
	v_pk_mul_f32 v[36:37], v[24:25], v[128:129]
	v_cvt_pk_bf16_f32 v236, v236, v237
	v_cvt_pk_bf16_f32 v237, v36, v37
	s_nop 0
	s_waitcnt lgkmcnt(8)
	v_mfma_f32_16x16x32_bf16 v[142:145], v[234:237], v[102:105], v[142:145]
	ds_read_b64 v[102:103], v157 offset:192
	ds_read_b64 v[104:105], v157 offset:224
	s_waitcnt lgkmcnt(8)
	v_mfma_f32_16x16x32_bf16 v[146:149], v[234:237], v[106:109], v[146:149]
	ds_read_b64 v[106:107], v1 offset:448
	ds_read_b64 v[108:109], v1 offset:480
	s_waitcnt lgkmcnt(8)
	v_mfma_f32_16x16x32_bf16 v[150:153], v[234:237], v[110:113], v[150:153]
	ds_read_b64 v[110:111], v35 offset:704
	ds_read_b64 v[112:113], v35 offset:736
	s_waitcnt lgkmcnt(8)
	v_mfma_f32_16x16x32_bf16 v[138:141], v[234:237], v[114:117], v[138:141]
	ds_read_b64 v[114:115], v246 offset:960
	ds_read_b64 v[116:117], v246 offset:992
	s_waitcnt lgkmcnt(9)
	v_pk_mul_f32 v[36:37], v[28:29], v[120:121]
	ds_read_b128 v[126:129], v187
	v_pk_mul_f32 v[234:235], v[26:27], v[118:119]
	s_waitcnt lgkmcnt(9)
	v_pk_mul_f32 v[236:237], v[30:31], v[122:123]
	ds_read_b128 v[118:121], v188
	v_cvt_pk_bf16_f32 v234, v234, v235
	v_cvt_pk_bf16_f32 v235, v36, v37
	v_pk_mul_f32 v[36:37], v[32:33], v[124:125]
	v_cvt_pk_bf16_f32 v236, v236, v237
	v_cvt_pk_bf16_f32 v237, v36, v37
	s_nop 0
	s_waitcnt lgkmcnt(8)
	v_mfma_f32_16x16x32_bf16 v[142:145], v[234:237], v[102:105], v[142:145]
	ds_read_b64 v[102:103], v157 offset:256
	ds_read_b64 v[104:105], v157 offset:288
	s_waitcnt lgkmcnt(8)
	v_mfma_f32_16x16x32_bf16 v[146:149], v[234:237], v[106:109], v[146:149]
	ds_read_b64 v[106:107], v1 offset:512
	ds_read_b64 v[108:109], v1 offset:544
	s_waitcnt lgkmcnt(8)
	v_mfma_f32_16x16x32_bf16 v[150:153], v[234:237], v[110:113], v[150:153]
	ds_read_b64 v[110:111], v35 offset:768
	ds_read_b64 v[112:113], v35 offset:800
	s_waitcnt lgkmcnt(8)
	v_mfma_f32_16x16x32_bf16 v[138:141], v[234:237], v[114:117], v[138:141]
	ds_read_b64 v[114:115], v246 offset:1024
	ds_read_b64 v[116:117], v246 offset:1056
	s_waitcnt lgkmcnt(9)
	v_pk_mul_f32 v[36:37], v[40:41], v[128:129]
	ds_read_b128 v[122:125], v189
	v_pk_mul_f32 v[234:235], v[38:39], v[126:127]
	s_waitcnt lgkmcnt(9)
	v_pk_mul_f32 v[236:237], v[42:43], v[118:119]
	ds_read_b128 v[126:129], v190
	v_cvt_pk_bf16_f32 v234, v234, v235
	v_cvt_pk_bf16_f32 v235, v36, v37
	v_pk_mul_f32 v[36:37], v[44:45], v[120:121]
	v_cvt_pk_bf16_f32 v236, v236, v237
	v_cvt_pk_bf16_f32 v237, v36, v37
	s_nop 0
	s_waitcnt lgkmcnt(8)
	v_mfma_f32_16x16x32_bf16 v[142:145], v[234:237], v[102:105], v[142:145]
	ds_read_b64 v[102:103], v157 offset:320
	ds_read_b64 v[104:105], v157 offset:352
	s_waitcnt lgkmcnt(8)
	v_mfma_f32_16x16x32_bf16 v[146:149], v[234:237], v[106:109], v[146:149]
	ds_read_b64 v[106:107], v1 offset:576
	ds_read_b64 v[108:109], v1 offset:608
	s_waitcnt lgkmcnt(8)
	v_mfma_f32_16x16x32_bf16 v[150:153], v[234:237], v[110:113], v[150:153]
	ds_read_b64 v[110:111], v35 offset:832
	ds_read_b64 v[112:113], v35 offset:864
	s_waitcnt lgkmcnt(8)
	v_mfma_f32_16x16x32_bf16 v[138:141], v[234:237], v[114:117], v[138:141]
	ds_read_b64 v[114:115], v246 offset:1088
	ds_read_b64 v[116:117], v246 offset:1120
	s_waitcnt lgkmcnt(9)
	v_pk_mul_f32 v[36:37], v[48:49], v[124:125]
	ds_read_b128 v[118:121], v191
	v_pk_mul_f32 v[234:235], v[46:47], v[122:123]
	s_waitcnt lgkmcnt(9)
	v_pk_mul_f32 v[236:237], v[50:51], v[126:127]
	ds_read_b128 v[122:125], v192
	v_cvt_pk_bf16_f32 v234, v234, v235
	v_cvt_pk_bf16_f32 v235, v36, v37
	v_pk_mul_f32 v[36:37], v[52:53], v[128:129]
	v_cvt_pk_bf16_f32 v236, v236, v237
	v_cvt_pk_bf16_f32 v237, v36, v37
	s_nop 0
	s_waitcnt lgkmcnt(8)
	v_mfma_f32_16x16x32_bf16 v[142:145], v[234:237], v[102:105], v[142:145]
	ds_read_b64 v[102:103], v157 offset:384
	ds_read_b64 v[104:105], v157 offset:416
	s_waitcnt lgkmcnt(8)
	v_mfma_f32_16x16x32_bf16 v[146:149], v[234:237], v[106:109], v[146:149]
	ds_read_b64 v[106:107], v1 offset:640
	ds_read_b64 v[108:109], v1 offset:672
	s_waitcnt lgkmcnt(8)
	v_mfma_f32_16x16x32_bf16 v[150:153], v[234:237], v[110:113], v[150:153]
	ds_read_b64 v[110:111], v35 offset:896
	ds_read_b64 v[112:113], v35 offset:928
	s_waitcnt lgkmcnt(8)
	v_mfma_f32_16x16x32_bf16 v[138:141], v[234:237], v[114:117], v[138:141]
	ds_read_b64 v[114:115], v246 offset:1152
	ds_read_b64 v[116:117], v246 offset:1184
	s_waitcnt lgkmcnt(9)
	v_pk_mul_f32 v[36:37], v[56:57], v[120:121]
	ds_read_b128 v[126:129], v193
	v_pk_mul_f32 v[234:235], v[54:55], v[118:119]
	s_waitcnt lgkmcnt(9)
	v_pk_mul_f32 v[236:237], v[58:59], v[122:123]
	ds_read_b128 v[118:121], v194
	v_cvt_pk_bf16_f32 v234, v234, v235
	v_cvt_pk_bf16_f32 v235, v36, v37
	v_pk_mul_f32 v[36:37], v[60:61], v[124:125]
	v_cvt_pk_bf16_f32 v236, v236, v237
	v_cvt_pk_bf16_f32 v237, v36, v37
	s_nop 0
	s_waitcnt lgkmcnt(8)
	v_mfma_f32_16x16x32_bf16 v[142:145], v[234:237], v[102:105], v[142:145]
	ds_read_b64 v[102:103], v157 offset:448
	ds_read_b64 v[104:105], v157 offset:480
	s_waitcnt lgkmcnt(8)
	v_mfma_f32_16x16x32_bf16 v[146:149], v[234:237], v[106:109], v[146:149]
	s_waitcnt lgkmcnt(6)
	v_mfma_f32_16x16x32_bf16 v[238:241], v[234:237], v[110:113], v[150:153]
	s_nop 2
	s_waitcnt lgkmcnt(4)
	v_mfma_f32_16x16x32_bf16 v[138:141], v[234:237], v[114:117], v[138:141]
	s_waitcnt lgkmcnt(3)
	v_pk_mul_f32 v[36:37], v[64:65], v[128:129]
	v_pk_mul_f32 v[150:151], v[62:63], v[126:127]
	v_cvt_pk_bf16_f32 v243, v36, v37
	v_cvt_pk_bf16_f32 v242, v150, v151
	s_waitcnt lgkmcnt(2)
	v_pk_mul_f32 v[36:37], v[68:69], v[120:121]
	v_pk_mul_f32 v[150:151], v[66:67], v[118:119]
	v_cvt_pk_bf16_f32 v245, v36, v37
	v_cvt_pk_bf16_f32 v244, v150, v151
	ds_read_b64 v[106:107], v1 offset:704
	ds_read_b64 v[108:109], v1 offset:736
	ds_read_b64 v[234:235], v246 offset:1216
	ds_read_b64 v[236:237], v246 offset:1248
	s_waitcnt lgkmcnt(4)
	v_mfma_f32_16x16x32_bf16 v[150:153], v[242:245], v[102:105], v[142:145]
	s_nop 2
	s_waitcnt lgkmcnt(2)
	v_mfma_f32_16x16x32_bf16 v[146:149], v[242:245], v[106:109], v[146:149]
	ds_read_b64 v[142:143], v35 offset:960
	ds_read_b64 v[144:145], v35 offset:992
	s_waitcnt lgkmcnt(0)
	s_barrier
	v_mfma_f32_16x16x32_bf16 v[142:145], v[242:245], v[142:145], v[238:241]
	v_mfma_f32_16x16x32_bf16 v[138:141], v[242:245], v[234:237], v[138:141]
	s_cbranch_vccnz .LBB0_719
	v_mov_b32_e32 v1, v158
	s_mov_b32 s22, s79
	v_ashrrev_i32_e32 v35, 5, v1
	v_lshlrev_b32_e32 v1, 4, v1
	v_and_b32_e32 v1, 0x1f0, v1
	v_mul_lo_u32 v35, v35, s84
	v_add3_u32 v1, 0, v1, v35
	s_waitcnt vmcnt(0)
	ds_write_b128 v1, v[70:73]
	ds_write_b128 v1, v[74:77] offset:33792
	ds_write_b128 v1, v[78:81] offset:8448
	ds_write_b128 v1, v[82:85] offset:42240
	ds_write_b128 v1, v[86:89] offset:16896
	ds_write_b128 v1, v[90:93] offset:50688
	ds_write_b128 v1, v[94:97] offset:25344
	ds_write_b128 v1, v[98:101] offset:59136
	v_mov_b32_e32 v1, v158
	s_lshl_b32 s26, s22, 6
	s_add_i32 s22, s22, s75
	s_ashr_i32 s23, s22, 31
	s_ashr_i32 s27, s26, 31
	s_sub_i32 s80, s7, s26
	s_lshl_b64 s[24:25], s[22:23], 17
	s_add_u32 s24, s73, s24
	v_lshlrev_b32_e32 v36, 3, v1
	s_addc_u32 s25, s74, s25
	v_mov_b32_e32 v37, v34
	v_lshl_add_u64 v[110:111], v[36:37], 1, s[24:25]
	s_movk_i32 s24, 0x2000
	v_add_co_u32_e32 v106, vcc, s24, v110
	s_movk_i32 s24, 0x4000
	s_nop 0
	v_addc_co_u32_e32 v107, vcc, 0, v111, vcc
	v_add_co_u32_e32 v112, vcc, s24, v110
	s_movk_i32 s24, 0x6000
	s_nop 0
	v_addc_co_u32_e32 v113, vcc, 0, v111, vcc
	v_add_co_u32_e32 v114, vcc, s24, v110
	global_load_dwordx4 v[102:105], v[110:111], off
	s_nop 0
	global_load_dwordx4 v[106:109], v[106:107], off
	v_addc_co_u32_e32 v115, vcc, 0, v111, vcc
	global_load_dwordx4 v[110:113], v[112:113], off
	s_nop 0
	global_load_dwordx4 v[114:117], v[114:115], off
	v_ashrrev_i32_e32 v35, 4, v1
	v_and_b32_e32 v1, 0x78, v36
	s_add_u32 s24, s26, s71
	v_mov_b32_e32 v126, 0
	v_mov_b32_e32 v127, v34
	v_lshl_or_b32 v36, v35, 11, v1
	s_addc_u32 s25, s27, s72
	s_min_i32 s80, s80, 64
	v_mov_b32_e32 v128, v34
	v_mov_b32_e32 v129, v34
	v_mov_b64_e32 v[118:119], v[126:127]
	v_lshl_add_u64 v[36:37], v[36:37], 1, s[14:15]
	v_cmp_gt_i32_e32 vcc, s80, v35
	v_mov_b64_e32 v[120:121], v[128:129]
	s_and_saveexec_b64 s[26:27], vcc
	s_cbranch_execz .LBB0_714
	s_lshl_b64 s[82:83], s[24:25], 12
	v_lshl_add_u64 v[118:119], v[36:37], 0, s[82:83]
	global_load_dwordx4 v[118:121], v[118:119], off

.LBB0_735:
	s_or_b64 exec, exec, s[24:25]
	ds_read_b128 v[70:73], v163
	ds_read_b128 v[74:77], v218
	ds_read_b128 v[78:81], v218 offset:64
	ds_read_b128 v[82:85], v195
	ds_read_b128 v[86:89], v218 offset:2304
	ds_read_b128 v[90:93], v218 offset:2368
	v_cmp_gt_i32_e32 vcc, s26, v158
	s_and_b64 s[26:27], s[56:57], vcc
	s_waitcnt lgkmcnt(6)
	s_waitcnt lgkmcnt(5)
	v_pk_mul_f32 v[4:5], v[4:5], v[72:73]
	ds_read_b128 v[94:97], v196
	v_pk_mul_f32 v[2:3], v[2:3], v[70:71]
	s_nop 0
	s_waitcnt lgkmcnt(5)
	v_mfma_f32_16x16x32_bf16 v[2:5], v[74:77], v[134:137], v[2:5]
	ds_read_b128 v[70:73], v218 offset:4608
	s_waitcnt lgkmcnt(5)
	v_mfma_f32_16x16x32_bf16 v[2:5], v[78:81], v[130:133], v[2:5]
	ds_read_b128 v[74:77], v218 offset:4672
	s_waitcnt lgkmcnt(5)
	v_pk_mul_f32 v[12:13], v[12:13], v[84:85]
	ds_read_b128 v[78:81], v197
	v_pk_mul_f32 v[10:11], v[10:11], v[82:83]
	s_nop 0
	s_waitcnt lgkmcnt(5)
	v_mfma_f32_16x16x32_bf16 v[10:13], v[86:89], v[134:137], v[10:13]
	ds_read_b128 v[82:85], v218 offset:6912
	s_waitcnt lgkmcnt(5)
	v_mfma_f32_16x16x32_bf16 v[10:13], v[90:93], v[130:133], v[10:13]
	ds_read_b128 v[86:89], v218 offset:6976
	s_waitcnt lgkmcnt(5)
	v_pk_mul_f32 v[8:9], v[8:9], v[96:97]
	ds_read_b128 v[90:93], v198
	v_pk_mul_f32 v[6:7], v[6:7], v[94:95]
	s_nop 0
	s_waitcnt lgkmcnt(5)
	v_mfma_f32_16x16x32_bf16 v[6:9], v[70:73], v[134:137], v[6:9]
	ds_read_b128 v[70:73], v218 offset:9216
	s_waitcnt lgkmcnt(5)
	v_mfma_f32_16x16x32_bf16 v[6:9], v[74:77], v[130:133], v[6:9]
	ds_read_b128 v[74:77], v218 offset:9280
	s_waitcnt lgkmcnt(5)
	v_pk_mul_f32 v[16:17], v[16:17], v[80:81]
	ds_read_b128 v[94:97], v199
	v_pk_mul_f32 v[14:15], v[14:15], v[78:79]
	s_nop 0
	s_waitcnt lgkmcnt(5)
	v_mfma_f32_16x16x32_bf16 v[14:17], v[82:85], v[134:137], v[14:17]
	ds_read_b128 v[78:81], v218 offset:11520
	s_waitcnt lgkmcnt(5)
	v_mfma_f32_16x16x32_bf16 v[14:17], v[86:89], v[130:133], v[14:17]
	ds_read_b128 v[82:85], v218 offset:11584
	s_waitcnt lgkmcnt(5)
	v_pk_mul_f32 v[20:21], v[20:21], v[92:93]
	ds_read_b128 v[86:89], v200
	v_pk_mul_f32 v[18:19], v[18:19], v[90:91]
	s_nop 0
	s_waitcnt lgkmcnt(5)
	v_mfma_f32_16x16x32_bf16 v[18:21], v[70:73], v[134:137], v[18:21]
	ds_read_b128 v[70:73], v218 offset:13824
	s_waitcnt lgkmcnt(5)
	v_mfma_f32_16x16x32_bf16 v[18:21], v[74:77], v[130:133], v[18:21]
	ds_read_b128 v[74:77], v218 offset:13888
	s_waitcnt lgkmcnt(5)
	v_pk_mul_f32 v[24:25], v[24:25], v[96:97]
	ds_read_b128 v[90:93], v201
	v_pk_mul_f32 v[22:23], v[22:23], v[94:95]
	s_nop 0
	s_waitcnt lgkmcnt(5)
	v_mfma_f32_16x16x32_bf16 v[22:25], v[78:81], v[134:137], v[22:25]
	ds_read_b128 v[78:81], v218 offset:16128
	s_waitcnt lgkmcnt(5)
	v_mfma_f32_16x16x32_bf16 v[22:25], v[82:85], v[130:133], v[22:25]
	ds_read_b128 v[82:85], v218 offset:16192
	s_waitcnt lgkmcnt(5)
	v_pk_mul_f32 v[28:29], v[28:29], v[88:89]
	ds_read_b128 v[94:97], v202
	v_pk_mul_f32 v[26:27], v[26:27], v[86:87]
	s_nop 0
	s_waitcnt lgkmcnt(5)
	v_mfma_f32_16x16x32_bf16 v[26:29], v[70:73], v[134:137], v[26:29]
	ds_read_b128 v[70:73], v218 offset:18432
	s_waitcnt lgkmcnt(5)
	v_mfma_f32_16x16x32_bf16 v[26:29], v[74:77], v[130:133], v[26:29]
	ds_read_b128 v[74:77], v218 offset:18496
	s_waitcnt lgkmcnt(5)
	v_pk_mul_f32 v[32:33], v[32:33], v[92:93]
	ds_read_b128 v[86:89], v203
	v_pk_mul_f32 v[30:31], v[30:31], v[90:91]
	s_nop 0
	s_waitcnt lgkmcnt(5)
	v_mfma_f32_16x16x32_bf16 v[30:33], v[78:81], v[134:137], v[30:33]
	ds_read_b128 v[78:81], v218 offset:20736
	s_waitcnt lgkmcnt(5)
	v_mfma_f32_16x16x32_bf16 v[30:33], v[82:85], v[130:133], v[30:33]
	ds_read_b128 v[82:85], v218 offset:20800
	s_waitcnt lgkmcnt(5)
	v_pk_mul_f32 v[40:41], v[40:41], v[96:97]
	ds_read_b128 v[90:93], v204
	v_pk_mul_f32 v[38:39], v[38:39], v[94:95]
	s_nop 0
	s_waitcnt lgkmcnt(5)
	v_mfma_f32_16x16x32_bf16 v[36:39], v[70:73], v[134:137], v[38:41]
	ds_read_b128 v[70:73], v218 offset:23040
	s_waitcnt lgkmcnt(5)
	v_mfma_f32_16x16x32_bf16 v[38:41], v[74:77], v[130:133], v[36:39]
	ds_read_b128 v[74:77], v218 offset:23104
	s_waitcnt lgkmcnt(5)
	v_pk_mul_f32 v[44:45], v[44:45], v[88:89]
	ds_read_b128 v[94:97], v205
	v_pk_mul_f32 v[42:43], v[42:43], v[86:87]
	s_nop 0
	s_waitcnt lgkmcnt(5)
	v_mfma_f32_16x16x32_bf16 v[42:45], v[78:81], v[134:137], v[42:45]
	ds_read_b128 v[78:81], v218 offset:25344
	s_waitcnt lgkmcnt(5)
	v_mfma_f32_16x16x32_bf16 v[42:45], v[82:85], v[130:133], v[42:45]
	ds_read_b128 v[82:85], v218 offset:25408
	s_waitcnt lgkmcnt(5)
	v_pk_mul_f32 v[48:49], v[48:49], v[92:93]
	ds_read_b128 v[86:89], v206
	v_pk_mul_f32 v[46:47], v[46:47], v[90:91]
	s_nop 0
	s_waitcnt lgkmcnt(5)
	v_mfma_f32_16x16x32_bf16 v[46:49], v[70:73], v[134:137], v[46:49]
	ds_read_b128 v[70:73], v218 offset:27648
	s_waitcnt lgkmcnt(5)
	v_mfma_f32_16x16x32_bf16 v[46:49], v[74:77], v[130:133], v[46:49]
	ds_read_b128 v[74:77], v218 offset:27712
	s_waitcnt lgkmcnt(5)
	v_pk_mul_f32 v[52:53], v[52:53], v[96:97]
	ds_read_b128 v[90:93], v207
	v_pk_mul_f32 v[50:51], v[50:51], v[94:95]
	s_nop 0
	s_waitcnt lgkmcnt(5)
	v_mfma_f32_16x16x32_bf16 v[50:53], v[78:81], v[134:137], v[50:53]
	ds_read_b128 v[78:81], v218 offset:29952
	s_waitcnt lgkmcnt(5)
	v_mfma_f32_16x16x32_bf16 v[50:53], v[82:85], v[130:133], v[50:53]
	ds_read_b128 v[82:85], v218 offset:30016
	s_waitcnt lgkmcnt(5)
	v_pk_mul_f32 v[56:57], v[56:57], v[88:89]
	ds_read_b128 v[94:97], v208
	v_pk_mul_f32 v[54:55], v[54:55], v[86:87]
	s_nop 0
	s_waitcnt lgkmcnt(5)
	v_mfma_f32_16x16x32_bf16 v[54:57], v[70:73], v[134:137], v[54:57]
	ds_read_b128 v[70:73], v218 offset:32256
	s_waitcnt lgkmcnt(5)
	v_mfma_f32_16x16x32_bf16 v[54:57], v[74:77], v[130:133], v[54:57]
	ds_read_b128 v[74:77], v218 offset:32320
	s_waitcnt lgkmcnt(5)
	v_pk_mul_f32 v[60:61], v[60:61], v[92:93]
	ds_read_b128 v[86:89], v209
	v_pk_mul_f32 v[58:59], v[58:59], v[90:91]
	s_nop 0
	s_waitcnt lgkmcnt(5)
	v_mfma_f32_16x16x32_bf16 v[58:61], v[78:81], v[134:137], v[58:61]
	s_waitcnt lgkmcnt(4)
	v_mfma_f32_16x16x32_bf16 v[58:61], v[82:85], v[130:133], v[58:61]
	s_waitcnt lgkmcnt(3)
	v_pk_mul_f32 v[64:65], v[64:65], v[96:97]
	v_pk_mul_f32 v[62:63], v[62:63], v[94:95]
	s_nop 0
	s_waitcnt lgkmcnt(2)
	v_mfma_f32_16x16x32_bf16 v[62:65], v[70:73], v[134:137], v[62:65]
	s_waitcnt lgkmcnt(1)
	v_mfma_f32_16x16x32_bf16 v[62:65], v[74:77], v[130:133], v[62:65]
	s_waitcnt lgkmcnt(0)
	v_pk_mul_f32 v[68:69], v[68:69], v[88:89]
	v_pk_mul_f32 v[66:67], v[66:67], v[86:87]
	ds_read_b128 v[138:141], v218 offset:34560
	s_waitcnt lgkmcnt(0)
	v_mfma_f32_16x16x32_bf16 v[66:69], v[138:141], v[134:137], v[66:69]
	ds_read_b128 v[134:137], v218 offset:34624
	s_waitcnt lgkmcnt(0)
	s_barrier
	v_mfma_f32_16x16x32_bf16 v[66:69], v[134:137], v[130:133], v[66:69]
	s_and_saveexec_b64 s[24:25], s[26:27]
	s_cbranch_execz .LBB0_694
	ds_read_b128 v[130:133], v220
	ds_read_b128 v[134:137], v220 offset:16
	s_waitcnt lgkmcnt(0)
	v_mov_b32_e32 v36, v130
	v_mov_b32_e32 v37, v134
	v_mov_b32_e32 v134, v131
	v_mov_b32_e32 v130, v132
	v_mov_b32_e32 v131, v136
	v_mov_b32_e32 v136, v133
	v_pk_add_f32 v[36:37], v[36:37], v[134:135]
	v_pk_add_f32 v[130:131], v[130:131], v[136:137]
	s_nop 0
	v_pk_add_f32 v[36:37], v[36:37], v[130:131]
	s_nop 0
	v_add_f32_e32 v1, v36, v37
	v_lshl_add_u64 v[36:37], s[22:23], 0, v[158:159]
	v_lshlrev_b64 v[36:37], 7, v[36:37]
	v_lshl_add_u64 v[36:37], s[16:17], 0, v[36:37]
	global_store_dword v[36:37], v1, off
	s_branch .LBB0_694

.LBB0_823:
	s_waitcnt vmcnt(0) lgkmcnt(0)
	v_add_f32_e32 v1, 0, v91
	v_add_f32_e32 v1, v120, v1
	v_add_f32_e32 v1, v121, v1
	v_add_f32_e32 v1, v122, v1
	v_add_f32_e32 v1, v123, v1
	v_add_f32_e32 v1, v124, v1
	v_add_f32_e32 v1, v125, v1
	v_add_f32_e32 v1, v126, v1
	v_add_f32_e32 v1, v128, v1
	v_add_f32_e32 v1, v131, v1
	v_add_f32_e32 v1, v134, v1
	v_add_f32_e32 v1, v144, v1
	v_add_f32_e32 v1, v147, v1
	v_add_f32_e32 v1, v155, v1
	v_add_f32_e32 v1, v175, v1
	v_add_f32_e32 v1, v176, v1
	v_add_u32_e32 v35, s93, v129
	ds_write_b128 v156, v[42:45]
	ds_write_b128 v156, v[46:49] offset:8704
	ds_write_b128 v157, v[50:53] offset:53248
	ds_write_b128 v157, v[54:57] offset:61952
	ds_write_b32 v35, v1
	v_add_u32_e32 v35, 0, v129
	v_add_u32_e32 v1, 0x13800, v35
	s_waitcnt lgkmcnt(0)
	s_barrier
	ds_read2st64_b32 v[36:37], v1 offset1:2
	ds_read2st64_b32 v[58:59], v1 offset0:4 offset1:6
	s_andn2_b64 vcc, exec, s[12:13]
	s_waitcnt lgkmcnt(1)
	v_add_f32_e32 v60, 0, v36
	v_cndmask_b32_e64 v61, 0, v37, s[40:41]
	v_cndmask_b32_e64 v36, 0, v60, s[38:39]
	s_waitcnt lgkmcnt(0)
	v_cndmask_b32_e64 v1, 0, v58, s[42:43]
	v_add_f32_e32 v36, v36, v61
	v_cndmask_b32_e64 v62, 0, v59, s[44:45]
	v_add_f32_e32 v1, v36, v1
	v_add_f32_e32 v61, v1, v62
	v_mov_b32_e32 v90, v37
	v_pk_add_f32 v[36:37], v[60:61], v[90:91]
	s_nop 0
	v_add_f32_e32 v1, v36, v58
	v_add_f32_e32 v59, v1, v59
	v_sub_f32_e32 v1, v59, v36
	v_mul_f32_e32 v1, 0x3fb8aa3b, v1
	v_exp_f32_e32 v58, v1
	v_add_u32_e32 v1, s96, v130
	ds_read_u16 v184, v1
	v_sub_f32_e32 v62, v37, v36
	v_mul_f32_e32 v62, 0x3fb8aa3b, v62
	v_exp_f32_e32 v63, v62
	v_sub_f32_e32 v62, v36, v37
	s_waitcnt lgkmcnt(1)
	s_waitcnt lgkmcnt(0)
	v_lshlrev_b32_e32 v61, 16, v184
	v_add_f32_e32 v64, v120, v37
	v_mul_f32_e32 v61, v63, v61
	v_cvt_pk_bf16_f32 v61, v61, s0
	s_mul_i32 s0, s76, 0x110
	v_add_u32_e32 v37, s0, v130
	ds_read_u16 v184, v37
	ds_read_u16 v188, v37 offset:272
	ds_read_u16 v192, v37 offset:544
	ds_read_u16 v196, v37 offset:816
	ds_read_u16 v200, v37 offset:1088
	ds_read_u16 v204, v37 offset:1360
	ds_write_b16 v1, v61
	v_sub_f32_e32 v63, v64, v36
	v_mul_f32_e32 v63, 0x3fb8aa3b, v63
	v_mul_f32_e32 v60, 0x3fb8aa3b, v91
	v_exp_f32_e32 v66, v63
	s_waitcnt lgkmcnt(6)
	v_lshlrev_b32_e32 v65, 16, v184
	ds_read_u16 v184, v37 offset:1632
	v_mul_f32_e32 v61, 0x3fb8aa3b, v120
	v_sub_f32_e32 v63, v36, v64
	v_exp_f32_e32 v60, v60
	v_mul_f32_e32 v62, 0x3fb8aa3b, v62
	v_exp_f32_e32 v61, v61
	v_mul_f32_e32 v63, 0x3fb8aa3b, v63
	v_exp_f32_e32 v62, v62
	v_exp_f32_e32 v63, v63
	v_pk_add_f32 v[60:61], v[60:61], 1.0 op_sel_hi:[1,0] neg_lo:[1,0] neg_hi:[1,0]
	v_mul_f32_e32 v65, v66, v65
	v_cvt_pk_bf16_f32 v65, v65, s0
	v_pk_mul_f32 v[62:63], v[60:61], v[62:63]
	ds_write_b16 v37, v65
	v_cvt_pk_bf16_f32 v60, v62, s0
	ds_write_b16 v1, v60 offset:17408
	v_cvt_pk_bf16_f32 v1, v63, s0
	ds_write_b16 v37, v1 offset:17408
	v_add_f32_e32 v1, v121, v64
	v_pk_mul_f32 v[60:61], v[58:59], v[62:63] op_sel_hi:[0,1]
	v_sub_f32_e32 v64, v1, v36
	v_mul_f32_e32 v64, 0x3fb8aa3b, v64
	v_exp_f32_e32 v65, v64
	v_sub_f32_e32 v64, v36, v1
	s_waitcnt lgkmcnt(9)
	v_lshlrev_b32_e32 v63, 16, v188
	ds_read_u16 v188, v37 offset:1904
	v_add_f32_e32 v1, v122, v1
	v_mul_f32_e32 v63, v65, v63
	v_cvt_pk_bf16_f32 v63, v63, s0
	ds_write_b16 v37, v63 offset:272
	v_sub_f32_e32 v65, v1, v36
	v_mul_f32_e32 v65, 0x3fb8aa3b, v65
	v_mul_f32_e32 v62, 0x3fb8aa3b, v121
	v_exp_f32_e32 v67, v65
	s_waitcnt lgkmcnt(10)
	v_lshlrev_b32_e32 v66, 16, v192
	ds_read_u16 v192, v37 offset:2176
	v_mul_f32_e32 v63, 0x3fb8aa3b, v122
	v_sub_f32_e32 v65, v36, v1
	v_exp_f32_e32 v62, v62
	v_mul_f32_e32 v64, 0x3fb8aa3b, v64
	v_exp_f32_e32 v63, v63
	v_mul_f32_e32 v65, 0x3fb8aa3b, v65
	v_exp_f32_e32 v64, v64
	v_exp_f32_e32 v65, v65
	v_pk_add_f32 v[62:63], v[62:63], 1.0 op_sel_hi:[1,0] neg_lo:[1,0] neg_hi:[1,0]
	v_mul_f32_e32 v66, v67, v66
	v_cvt_pk_bf16_f32 v66, v66, s0
	v_pk_mul_f32 v[64:65], v[62:63], v[64:65]
	v_add_f32_e32 v1, v123, v1
	v_cvt_pk_bf16_f32 v62, v64, s0
	ds_write_b16 v37, v62 offset:17680
	v_pk_mul_f32 v[62:63], v[58:59], v[64:65] op_sel_hi:[0,1]
	v_cvt_pk_bf16_f32 v64, v65, s0
	ds_write_b16 v37, v66 offset:544
	ds_write_b16 v37, v64 offset:17952
	v_sub_f32_e32 v66, v1, v36
	v_mul_f32_e32 v66, 0x3fb8aa3b, v66
	v_exp_f32_e32 v67, v66
	v_sub_f32_e32 v66, v36, v1
	s_waitcnt lgkmcnt(13)
	v_lshlrev_b32_e32 v65, 16, v196
	ds_read_u16 v196, v37 offset:2448
	v_add_f32_e32 v1, v124, v1
	v_mul_f32_e32 v65, v67, v65
	v_cvt_pk_bf16_f32 v65, v65, s0
	ds_write_b16 v37, v65 offset:816
	v_sub_f32_e32 v67, v1, v36
	v_mul_f32_e32 v67, 0x3fb8aa3b, v67
	v_mul_f32_e32 v64, 0x3fb8aa3b, v123
	v_exp_f32_e32 v69, v67
	s_waitcnt lgkmcnt(14)
	v_lshlrev_b32_e32 v68, 16, v200
	ds_read_u16 v200, v37 offset:2720
	v_mul_f32_e32 v65, 0x3fb8aa3b, v124
	v_sub_f32_e32 v67, v36, v1
	v_exp_f32_e32 v64, v64
	v_mul_f32_e32 v66, 0x3fb8aa3b, v66
	v_exp_f32_e32 v65, v65
	v_mul_f32_e32 v67, 0x3fb8aa3b, v67
	v_exp_f32_e32 v66, v66
	v_exp_f32_e32 v67, v67
	v_pk_add_f32 v[64:65], v[64:65], 1.0 op_sel_hi:[1,0] neg_lo:[1,0] neg_hi:[1,0]
	v_mul_f32_e32 v68, v69, v68
	v_cvt_pk_bf16_f32 v68, v68, s0
	v_pk_mul_f32 v[66:67], v[64:65], v[66:67]
	v_add_f32_e32 v1, v125, v1
	v_cvt_pk_bf16_f32 v64, v66, s0
	ds_write_b16 v37, v64 offset:18224
	v_pk_mul_f32 v[64:65], v[58:59], v[66:67] op_sel_hi:[0,1]
	v_cvt_pk_bf16_f32 v66, v67, s0
	ds_write_b16 v37, v68 offset:1088
	ds_write_b16 v37, v66 offset:18496
	v_sub_f32_e32 v68, v1, v36
	v_mul_f32_e32 v68, 0x3fb8aa3b, v68
	v_exp_f32_e32 v69, v68
	v_sub_f32_e32 v68, v36, v1
	s_waitcnt lgkmcnt(15)
	v_lshlrev_b32_e32 v67, 16, v204
	ds_read_u16 v204, v37 offset:2992
	v_add_f32_e32 v1, v126, v1
	v_mul_f32_e32 v67, v69, v67
	v_cvt_pk_bf16_f32 v67, v67, s0
	ds_write_b16 v37, v67 offset:1360
	v_sub_f32_e32 v69, v1, v36
	v_mul_f32_e32 v69, 0x3fb8aa3b, v69
	v_mul_f32_e32 v66, 0x3fb8aa3b, v125
	v_exp_f32_e32 v71, v69
	s_waitcnt lgkmcnt(15)
	v_lshlrev_b32_e32 v70, 16, v184
	ds_read_u16 v184, v37 offset:3264
	v_mul_f32_e32 v67, 0x3fb8aa3b, v126
	v_sub_f32_e32 v69, v36, v1
	v_exp_f32_e32 v66, v66
	v_mul_f32_e32 v68, 0x3fb8aa3b, v68
	v_exp_f32_e32 v67, v67
	v_mul_f32_e32 v69, 0x3fb8aa3b, v69
	v_exp_f32_e32 v68, v68
	v_exp_f32_e32 v69, v69
	v_pk_add_f32 v[66:67], v[66:67], 1.0 op_sel_hi:[1,0] neg_lo:[1,0] neg_hi:[1,0]
	v_mul_f32_e32 v70, v71, v70
	v_cvt_pk_bf16_f32 v70, v70, s0
	v_pk_mul_f32 v[66:67], v[66:67], v[68:69]
	v_cvt_pk_bf16_f32 v60, v60, v61
	v_cvt_pk_bf16_f32 v68, v66, s0
	ds_write_b16 v37, v68 offset:18768
	v_pk_mul_f32 v[68:69], v[58:59], v[66:67] op_sel_hi:[0,1]
	v_cvt_pk_bf16_f32 v66, v67, s0
	v_cvt_pk_bf16_f32 v61, v62, v63
	v_cvt_pk_bf16_f32 v62, v64, v65
	v_cvt_pk_bf16_f32 v63, v68, v69
	ds_write_b16 v37, v70 offset:1632
	ds_write_b16 v37, v66 offset:19040
	ds_write_b128 v158, v[60:63] offset:34816
	v_add_f32_e32 v1, v128, v1
	v_sub_f32_e32 v62, v1, v36
	v_mul_f32_e32 v62, 0x3fb8aa3b, v62
	v_exp_f32_e32 v63, v62
	v_sub_f32_e32 v62, v36, v1
	s_waitcnt lgkmcnt(15)
	v_lshlrev_b32_e32 v61, 16, v188
	ds_read_u16 v188, v37 offset:3536
	v_add_f32_e32 v1, v131, v1
	v_mul_f32_e32 v61, v63, v61
	v_cvt_pk_bf16_f32 v61, v61, s0
	ds_write_b16 v37, v61 offset:1904
	v_sub_f32_e32 v63, v1, v36
	v_mul_f32_e32 v63, 0x3fb8aa3b, v63
	v_mul_f32_e32 v60, 0x3fb8aa3b, v128
	v_exp_f32_e32 v65, v63
	s_waitcnt lgkmcnt(15)
	v_lshlrev_b32_e32 v64, 16, v192
	ds_read_u16 v192, v37 offset:3808
	v_mul_f32_e32 v61, 0x3fb8aa3b, v131
	v_sub_f32_e32 v63, v36, v1
	v_exp_f32_e32 v60, v60
	v_mul_f32_e32 v62, 0x3fb8aa3b, v62
	v_exp_f32_e32 v61, v61
	v_mul_f32_e32 v63, 0x3fb8aa3b, v63
	v_exp_f32_e32 v62, v62
	v_exp_f32_e32 v63, v63
	v_pk_add_f32 v[60:61], v[60:61], 1.0 op_sel_hi:[1,0] neg_lo:[1,0] neg_hi:[1,0]
	v_mul_f32_e32 v64, v65, v64
	v_cvt_pk_bf16_f32 v64, v64, s0
	v_pk_mul_f32 v[62:63], v[60:61], v[62:63]
	v_add_f32_e32 v1, v134, v1
	v_cvt_pk_bf16_f32 v60, v62, s0
	ds_write_b16 v37, v60 offset:19312
	v_pk_mul_f32 v[60:61], v[58:59], v[62:63] op_sel_hi:[0,1]
	v_cvt_pk_bf16_f32 v62, v63, s0
	ds_write_b16 v37, v64 offset:2176
	ds_write_b16 v37, v62 offset:19584
	v_sub_f32_e32 v64, v1, v36
	v_mul_f32_e32 v64, 0x3fb8aa3b, v64
	v_exp_f32_e32 v65, v64
	v_sub_f32_e32 v64, v36, v1
	s_waitcnt lgkmcnt(15)
	v_lshlrev_b32_e32 v63, 16, v196
	v_add_f32_e32 v1, v144, v1
	v_mul_f32_e32 v63, v65, v63
	v_cvt_pk_bf16_f32 v63, v63, s0
	ds_write_b16 v37, v63 offset:2448
	v_sub_f32_e32 v65, v1, v36
	v_mul_f32_e32 v65, 0x3fb8aa3b, v65
	v_mul_f32_e32 v62, 0x3fb8aa3b, v134
	v_exp_f32_e32 v67, v65
	s_waitcnt lgkmcnt(15)
	v_lshlrev_b32_e32 v66, 16, v200
	v_mul_f32_e32 v63, 0x3fb8aa3b, v144
	v_sub_f32_e32 v65, v36, v1
	v_exp_f32_e32 v62, v62
	v_mul_f32_e32 v64, 0x3fb8aa3b, v64
	v_exp_f32_e32 v63, v63
	v_mul_f32_e32 v65, 0x3fb8aa3b, v65
	v_exp_f32_e32 v64, v64
	v_exp_f32_e32 v65, v65
	v_pk_add_f32 v[62:63], v[62:63], 1.0 op_sel_hi:[1,0] neg_lo:[1,0] neg_hi:[1,0]
	v_mul_f32_e32 v66, v67, v66
	v_cvt_pk_bf16_f32 v66, v66, s0
	v_pk_mul_f32 v[64:65], v[62:63], v[64:65]
	v_add_f32_e32 v1, v147, v1
	v_cvt_pk_bf16_f32 v62, v64, s0
	ds_write_b16 v37, v62 offset:19856
	v_pk_mul_f32 v[62:63], v[58:59], v[64:65] op_sel_hi:[0,1]
	v_cvt_pk_bf16_f32 v64, v65, s0
	ds_write_b16 v37, v66 offset:2720
	ds_write_b16 v37, v64 offset:20128
	v_sub_f32_e32 v66, v1, v36
	v_mul_f32_e32 v66, 0x3fb8aa3b, v66
	v_exp_f32_e32 v67, v66
	v_sub_f32_e32 v66, v36, v1
	s_waitcnt lgkmcnt(15)
	v_lshlrev_b32_e32 v65, 16, v204
	v_add_f32_e32 v1, v155, v1
	v_mul_f32_e32 v65, v67, v65
	v_cvt_pk_bf16_f32 v65, v65, s0
	ds_write_b16 v37, v65 offset:2992
	v_sub_f32_e32 v67, v1, v36
	v_mul_f32_e32 v67, 0x3fb8aa3b, v67
	v_mul_f32_e32 v64, 0x3fb8aa3b, v147
	v_exp_f32_e32 v69, v67
	s_waitcnt lgkmcnt(15)
	v_lshlrev_b32_e32 v68, 16, v184
	v_mul_f32_e32 v65, 0x3fb8aa3b, v155
	v_sub_f32_e32 v67, v36, v1
	v_exp_f32_e32 v64, v64
	v_mul_f32_e32 v66, 0x3fb8aa3b, v66
	v_exp_f32_e32 v65, v65
	v_mul_f32_e32 v67, 0x3fb8aa3b, v67
	v_exp_f32_e32 v66, v66
	v_exp_f32_e32 v67, v67
	v_pk_add_f32 v[64:65], v[64:65], 1.0 op_sel_hi:[1,0] neg_lo:[1,0] neg_hi:[1,0]
	v_mul_f32_e32 v68, v69, v68
	v_cvt_pk_bf16_f32 v68, v68, s0
	v_pk_mul_f32 v[66:67], v[64:65], v[66:67]
	v_add_f32_e32 v1, v175, v1
	v_cvt_pk_bf16_f32 v64, v66, s0
	ds_write_b16 v37, v64 offset:20400
	v_pk_mul_f32 v[64:65], v[58:59], v[66:67] op_sel_hi:[0,1]
	v_cvt_pk_bf16_f32 v66, v67, s0
	ds_write_b16 v37, v68 offset:3264
	ds_write_b16 v37, v66 offset:20672
	v_sub_f32_e32 v68, v1, v36
	v_mul_f32_e32 v68, 0x3fb8aa3b, v68
	v_exp_f32_e32 v69, v68
	v_sub_f32_e32 v68, v36, v1
	s_waitcnt lgkmcnt(13)
	v_lshlrev_b32_e32 v67, 16, v188
	v_add_f32_e32 v1, v176, v1
	v_mul_f32_e32 v67, v69, v67
	v_cvt_pk_bf16_f32 v67, v67, s0
	ds_write_b16 v37, v67 offset:3536
	v_sub_f32_e32 v69, v1, v36
	v_mul_f32_e32 v66, 0x3fb8aa3b, v175
	v_mul_f32_e32 v69, 0x3fb8aa3b, v69
	v_sub_f32_e32 v1, v36, v1
	s_waitcnt lgkmcnt(12)
	v_lshlrev_b32_e32 v70, 16, v192
	v_mul_f32_e32 v67, 0x3fb8aa3b, v176
	v_exp_f32_e32 v66, v66
	v_mul_f32_e32 v68, 0x3fb8aa3b, v68
	v_exp_f32_e32 v67, v67
	v_exp_f32_e32 v71, v69
	v_mul_f32_e32 v1, 0x3fb8aa3b, v1
	v_exp_f32_e32 v68, v68
	v_exp_f32_e32 v69, v1
	v_mul_f32_e32 v1, v71, v70
	v_pk_add_f32 v[66:67], v[66:67], 1.0 op_sel_hi:[1,0] neg_lo:[1,0] neg_hi:[1,0]
	v_cvt_pk_bf16_f32 v1, v1, s0
	v_pk_mul_f32 v[66:67], v[66:67], v[68:69]
	ds_write_b16 v37, v1 offset:3808
	v_cvt_pk_bf16_f32 v1, v66, s0
	v_pk_mul_f32 v[68:69], v[58:59], v[66:67] op_sel_hi:[0,1]
	ds_write_b16 v37, v1 offset:20944
	v_cvt_pk_bf16_f32 v1, v67, s0
	v_cvt_pk_bf16_f32 v60, v60, v61
	v_cvt_pk_bf16_f32 v61, v62, v63
	v_cvt_pk_bf16_f32 v62, v64, v65
	v_cvt_pk_bf16_f32 v63, v68, v69
	ds_write_b16 v37, v1 offset:21216
	ds_write_b128 v158, v[60:63] offset:34832
	s_cbranch_vccnz .LBB0_825
	v_mul_f32_e32 v1, 0x3fb8aa3b, v36
	v_exp_f32_e32 v1, v1
	v_mul_f32_e32 v36, 0x3fb8aa3b, v59
	v_exp_f32_e32 v36, v36
	v_add_u32_e32 v37, 0x14000, v35
	ds_write_b32 v37, v1
	v_add_u32_e32 v1, 0x14200, v35
	ds_write_b32 v1, v36

.LBB0_835:
	ds_read_b64_tr_b16 v[62:63], v159 offset:53248
	ds_read_b64_tr_b16 v[64:65], v159 offset:54336
	ds_read_b64_tr_b16 v[58:59], v159 offset:61952
	ds_read_b64_tr_b16 v[60:61], v159 offset:63040
	v_mov_b32_e32 v66, 0
	s_andn2_b64 vcc, exec, s[14:15]
	v_mov_b32_e32 v68, 0
	v_mov_b32_e32 v69, 0
	v_mov_b32_e32 v70, 0
	v_mov_b32_e32 v71, 0
	s_cbranch_vccnz .LBB0_837
	ds_read_b128 v[184:187], v172
	ds_read_b128 v[188:191], v173
	ds_read_b128 v[192:195], v172 offset:64
	ds_read_b128 v[196:199], v173 offset:64
	ds_read_b128 v[200:203], v172 offset:128
	ds_read_b128 v[204:207], v173 offset:128
	s_waitcnt lgkmcnt(6)
	s_waitcnt lgkmcnt(4)
	v_mfma_f32_16x16x32_bf16 v[68:71], v[184:187], v[188:191], 0
	s_waitcnt lgkmcnt(2)
	v_mfma_f32_16x16x32_bf16 v[68:71], v[192:195], v[196:199], v[68:71]
	s_waitcnt lgkmcnt(0)
	v_mfma_f32_16x16x32_bf16 v[68:71], v[200:203], v[204:207], v[68:71]
	ds_read_b128 v[72:75], v172 offset:192
	ds_read_b128 v[76:79], v173 offset:192
	s_waitcnt lgkmcnt(0)
	v_mfma_f32_16x16x32_bf16 v[68:71], v[72:75], v[76:79], v[68:71]
.LBB0_837:
	s_nop 7
	v_cndmask_b32_e64 v1, v68, 0, s[46:47]
	v_cndmask_b32_e64 v35, 0, v69, s[48:49]
	v_cndmask_b32_e64 v1, v1, v68, s[48:49]
	v_cndmask_b32_e64 v37, v70, 0, s[50:51]
	v_cndmask_b32_e64 v67, v71, 0, s[52:53]
	v_cvt_pk_bf16_f32 v36, v1, v35
	v_cvt_pk_bf16_f32 v37, v37, v67
	s_andn2_b64 vcc, exec, s[16:17]
	v_mov_b32_e32 v67, 0
	v_mov_b32_e32 v68, 0
	v_mov_b32_e32 v69, 0
	ds_write_b64 v160, v[36:37]
	s_cbranch_vccnz .LBB0_839
	ds_read_b128 v[184:187], v172 offset:4352
	ds_read_b128 v[188:191], v173
	ds_read_b128 v[192:195], v172 offset:4416
	ds_read_b128 v[196:199], v173 offset:64
	ds_read_b128 v[200:203], v172 offset:4480
	ds_read_b128 v[204:207], v173 offset:128
	s_waitcnt lgkmcnt(6)
	s_waitcnt lgkmcnt(4)
	v_mfma_f32_16x16x32_bf16 v[66:69], v[184:187], v[188:191], 0
	s_waitcnt lgkmcnt(2)
	v_mfma_f32_16x16x32_bf16 v[66:69], v[192:195], v[196:199], v[66:69]
	s_waitcnt lgkmcnt(0)
	v_mfma_f32_16x16x32_bf16 v[66:69], v[200:203], v[204:207], v[66:69]
	ds_read_b128 v[70:73], v172 offset:4544
	ds_read_b128 v[74:77], v173 offset:192
	s_waitcnt lgkmcnt(0)
	v_mfma_f32_16x16x32_bf16 v[66:69], v[70:73], v[74:77], v[66:69]
.LBB0_839:
	s_nop 7
	v_cndmask_b32_e64 v1, v66, 0, s[54:55]
	v_cndmask_b32_e64 v35, v67, 0, s[56:57]
	v_cndmask_b32_e64 v37, v68, 0, s[58:59]
	v_cndmask_b32_e64 v67, v69, 0, s[60:61]
	v_cvt_pk_bf16_f32 v66, v1, v35
	v_cvt_pk_bf16_f32 v67, v37, v67
	ds_write_b64 v161, v[66:67]
	ds_read_b128 v[184:187], v132
	ds_read_b128 v[188:191], v135
	v_add_u32_e32 v1, 0x1000, v162
	ds_read_b64 v[192:193], v1 offset:256
	ds_read_b64 v[194:195], v1 offset:288
	ds_read_b64 v[196:197], v162
	ds_read_b64 v[198:199], v162 offset:32
	v_add_u32_e32 v35, 0x2000, v162
	ds_read_b64 v[200:201], v35 offset:512
	ds_read_b64 v[202:203], v35 offset:544
	v_add_u32_e32 v37, 0x3000, v162
	ds_read_b64 v[204:205], v37 offset:768
	ds_read_b64 v[206:207], v37 offset:800
	s_waitcnt lgkmcnt(11)
	s_waitcnt lgkmcnt(9)
	v_pk_mul_f32 v[68:69], v[4:5], v[186:187]
	ds_read_b128 v[208:211], v136
	v_pk_mul_f32 v[66:67], v[2:3], v[184:185]
	s_waitcnt lgkmcnt(9)
	v_pk_mul_f32 v[72:73], v[12:13], v[190:191]
	ds_read_b128 v[184:187], v137
	v_cvt_pk_bf16_f32 v66, v66, v67
	v_cvt_pk_bf16_f32 v67, v68, v69
	v_pk_mul_f32 v[68:69], v[10:11], v[188:189]
	v_cvt_pk_bf16_f32 v68, v68, v69
	v_cvt_pk_bf16_f32 v69, v72, v73
	s_nop 0
	s_waitcnt lgkmcnt(6)
	v_mfma_f32_16x16x32_bf16 v[70:73], v[66:69], v[196:199], 0
	s_sub_i32 s5, s8, 64
	s_add_u32 s18, s5, s72
	s_addc_u32 s19, 0, s74
	v_mfma_f32_16x16x32_bf16 v[74:77], v[66:69], v[192:195], 0
	ds_read_b64 v[188:189], v162 offset:64
	ds_read_b64 v[190:191], v162 offset:96
	ds_read_b64 v[192:193], v1 offset:320
	ds_read_b64 v[194:195], v1 offset:352
	v_mov_b32_e32 v36, 0
	v_cmp_gt_i32_e64 s[68:69], s9, v95
	v_or_b32_e32 v116, s18, v95
	s_waitcnt lgkmcnt(8)
	v_mfma_f32_16x16x32_bf16 v[78:81], v[66:69], v[200:203], 0
	ds_read_b64 v[196:197], v35 offset:576
	ds_read_b64 v[198:199], v35 offset:608
	s_waitcnt lgkmcnt(8)
	v_mfma_f32_16x16x32_bf16 v[66:69], v[66:69], v[204:207], 0
	ds_read_b64 v[200:201], v37 offset:832
	ds_read_b64 v[202:203], v37 offset:864
	s_waitcnt lgkmcnt(9)
	v_pk_mul_f32 v[106:107], v[8:9], v[210:211]
	ds_read_b128 v[204:207], v138
	v_pk_mul_f32 v[104:105], v[6:7], v[208:209]
	s_waitcnt lgkmcnt(9)
	v_pk_mul_f32 v[110:111], v[16:17], v[186:187]
	ds_read_b128 v[208:211], v139
	v_cvt_pk_bf16_f32 v104, v104, v105
	v_cvt_pk_bf16_f32 v105, v106, v107
	v_pk_mul_f32 v[106:107], v[14:15], v[184:185]
	s_nop 0
	v_cvt_pk_bf16_f32 v106, v106, v107
	v_cvt_pk_bf16_f32 v107, v110, v111
	s_nop 0
	s_waitcnt lgkmcnt(8)
	v_mfma_f32_16x16x32_bf16 v[70:73], v[104:107], v[188:191], v[70:73]
	ds_read_b64 v[184:185], v162 offset:128
	ds_read_b64 v[186:187], v162 offset:160
	s_waitcnt lgkmcnt(8)
	v_mfma_f32_16x16x32_bf16 v[74:77], v[104:107], v[192:195], v[74:77]
	ds_read_b64 v[188:189], v1 offset:384
	ds_read_b64 v[190:191], v1 offset:416
	s_waitcnt lgkmcnt(8)
	v_mfma_f32_16x16x32_bf16 v[78:81], v[104:107], v[196:199], v[78:81]
	ds_read_b64 v[192:193], v35 offset:640
	ds_read_b64 v[194:195], v35 offset:672
	s_waitcnt lgkmcnt(8)
	v_mfma_f32_16x16x32_bf16 v[66:69], v[104:107], v[200:203], v[66:69]
	ds_read_b64 v[196:197], v37 offset:896
	ds_read_b64 v[198:199], v37 offset:928
	s_waitcnt lgkmcnt(9)
	v_pk_mul_f32 v[106:107], v[20:21], v[206:207]
	ds_read_b128 v[200:203], v140
	v_pk_mul_f32 v[104:105], v[18:19], v[204:205]
	s_waitcnt lgkmcnt(9)
	v_pk_mul_f32 v[110:111], v[24:25], v[210:211]
	ds_read_b128 v[204:207], v141
	v_cvt_pk_bf16_f32 v104, v104, v105
	v_cvt_pk_bf16_f32 v105, v106, v107
	v_pk_mul_f32 v[106:107], v[22:23], v[208:209]
	s_nop 0
	v_cvt_pk_bf16_f32 v106, v106, v107
	v_cvt_pk_bf16_f32 v107, v110, v111
	s_nop 0
	s_waitcnt lgkmcnt(8)
	v_mfma_f32_16x16x32_bf16 v[70:73], v[104:107], v[184:187], v[70:73]
	ds_read_b64 v[184:185], v162 offset:192
	ds_read_b64 v[186:187], v162 offset:224
	s_waitcnt lgkmcnt(8)
	v_mfma_f32_16x16x32_bf16 v[74:77], v[104:107], v[188:191], v[74:77]
	ds_read_b64 v[188:189], v1 offset:448
	ds_read_b64 v[190:191], v1 offset:480
	s_waitcnt lgkmcnt(8)
	v_mfma_f32_16x16x32_bf16 v[78:81], v[104:107], v[192:195], v[78:81]
	ds_read_b64 v[192:193], v35 offset:704
	ds_read_b64 v[194:195], v35 offset:736
	s_waitcnt lgkmcnt(8)
	v_mfma_f32_16x16x32_bf16 v[66:69], v[104:107], v[196:199], v[66:69]
	s_waitcnt lgkmcnt(7)
	v_pk_mul_f32 v[106:107], v[28:29], v[202:203]
	v_pk_mul_f32 v[104:105], v[26:27], v[200:201]
	s_waitcnt lgkmcnt(6)
	v_pk_mul_f32 v[110:111], v[32:33], v[206:207]
	v_cvt_pk_bf16_f32 v104, v104, v105
	v_cvt_pk_bf16_f32 v105, v106, v107
	v_pk_mul_f32 v[106:107], v[30:31], v[204:205]
	s_nop 0
	v_cvt_pk_bf16_f32 v106, v106, v107
	v_cvt_pk_bf16_f32 v107, v110, v111
	s_nop 0
	s_waitcnt lgkmcnt(4)
	v_mfma_f32_16x16x32_bf16 v[108:111], v[104:107], v[184:187], v[70:73]
	s_nop 2
	s_waitcnt lgkmcnt(2)
	v_mfma_f32_16x16x32_bf16 v[74:77], v[104:107], v[188:191], v[74:77]
	s_waitcnt lgkmcnt(0)
	v_mfma_f32_16x16x32_bf16 v[70:73], v[104:107], v[192:195], v[78:81]
	s_nop 2
	ds_read_b64 v[78:79], v37 offset:960
	ds_read_b64 v[80:81], v37 offset:992
	s_waitcnt lgkmcnt(0)
	v_mfma_f32_16x16x32_bf16 v[66:69], v[104:107], v[78:81], v[66:69]
	s_barrier
	ds_read_b128 v[78:81], v174
	ds_read_b128 v[104:107], v174 offset:64
	s_waitcnt lgkmcnt(0)
	v_mfma_f32_16x16x32_bf16 v[78:81], v[62:65], v[78:81], v[108:111]
	v_mov_b32_e32 v37, 0
	v_mfma_f32_16x16x32_bf16 v[78:81], v[58:61], v[104:107], v[78:81]
	s_and_saveexec_b64 s[20:21], s[68:69]
	s_cbranch_execz .LBB0_841
	v_mov_b32_e32 v117, s19
	v_lshlrev_b64 v[36:37], 12, v[116:117]
	v_lshl_add_u64 v[36:37], v[102:103], 0, v[36:37]
	global_load_dwordx2 v[36:37], v[36:37], off

.LBB0_873:
	ds_read_b128 v[184:187], v133
	ds_read_b128 v[188:191], v163
	ds_read_b128 v[192:195], v163 offset:64
	ds_read_b128 v[196:199], v148
	ds_read_b128 v[200:203], v163 offset:2304
	ds_read_b128 v[204:207], v163 offset:2368
	s_waitcnt lgkmcnt(6)
	s_waitcnt lgkmcnt(5)
	v_pk_mul_f32 v[4:5], v[4:5], v[186:187]
	ds_read_b128 v[208:211], v149
	v_pk_mul_f32 v[2:3], v[2:3], v[184:185]
	s_nop 0
	s_waitcnt lgkmcnt(5)
	v_mfma_f32_16x16x32_bf16 v[2:5], v[188:191], v[62:65], v[2:5]
	ds_read_b128 v[184:187], v163 offset:4608
	s_waitcnt lgkmcnt(5)
	v_mfma_f32_16x16x32_bf16 v[2:5], v[192:195], v[58:61], v[2:5]
	ds_read_b128 v[188:191], v163 offset:4672
	s_waitcnt lgkmcnt(5)
	v_pk_mul_f32 v[12:13], v[12:13], v[198:199]
	ds_read_b128 v[192:195], v150
	v_pk_mul_f32 v[10:11], v[10:11], v[196:197]
	s_nop 0
	s_waitcnt lgkmcnt(5)
	v_mfma_f32_16x16x32_bf16 v[10:13], v[200:203], v[62:65], v[10:13]
	ds_read_b128 v[196:199], v163 offset:6912
	s_waitcnt lgkmcnt(5)
	v_mfma_f32_16x16x32_bf16 v[10:13], v[204:207], v[58:61], v[10:13]
	ds_read_b128 v[200:203], v163 offset:6976
	s_waitcnt lgkmcnt(5)
	v_pk_mul_f32 v[8:9], v[8:9], v[210:211]
	ds_read_b128 v[204:207], v151
	v_pk_mul_f32 v[6:7], v[6:7], v[208:209]
	s_nop 0
	s_waitcnt lgkmcnt(5)
	v_mfma_f32_16x16x32_bf16 v[6:9], v[184:187], v[62:65], v[6:9]
	ds_read_b128 v[184:187], v163 offset:9216
	s_waitcnt lgkmcnt(5)
	v_mfma_f32_16x16x32_bf16 v[6:9], v[188:191], v[58:61], v[6:9]
	ds_read_b128 v[188:191], v163 offset:9280
	s_waitcnt lgkmcnt(5)
	v_pk_mul_f32 v[16:17], v[16:17], v[194:195]
	ds_read_b128 v[208:211], v152
	v_pk_mul_f32 v[14:15], v[14:15], v[192:193]
	s_nop 0
	s_waitcnt lgkmcnt(5)
	v_mfma_f32_16x16x32_bf16 v[14:17], v[196:199], v[62:65], v[14:17]
	ds_read_b128 v[192:195], v163 offset:11520
	s_waitcnt lgkmcnt(5)
	v_mfma_f32_16x16x32_bf16 v[14:17], v[200:203], v[58:61], v[14:17]
	ds_read_b128 v[196:199], v163 offset:11584
	s_waitcnt lgkmcnt(5)
	v_pk_mul_f32 v[20:21], v[20:21], v[206:207]
	ds_read_b128 v[200:203], v153
	v_pk_mul_f32 v[18:19], v[18:19], v[204:205]
	s_nop 0
	s_waitcnt lgkmcnt(5)
	v_mfma_f32_16x16x32_bf16 v[18:21], v[184:187], v[62:65], v[18:21]
	ds_read_b128 v[184:187], v163 offset:13824
	s_waitcnt lgkmcnt(5)
	v_mfma_f32_16x16x32_bf16 v[18:21], v[188:191], v[58:61], v[18:21]
	ds_read_b128 v[188:191], v163 offset:13888
	s_waitcnt lgkmcnt(5)
	v_pk_mul_f32 v[24:25], v[24:25], v[210:211]
	ds_read_b128 v[204:207], v154
	v_pk_mul_f32 v[22:23], v[22:23], v[208:209]
	s_nop 0
	s_waitcnt lgkmcnt(5)
	v_mfma_f32_16x16x32_bf16 v[22:25], v[192:195], v[62:65], v[22:25]
	s_waitcnt lgkmcnt(4)
	v_mfma_f32_16x16x32_bf16 v[22:25], v[196:199], v[58:61], v[22:25]
	s_waitcnt lgkmcnt(3)
	v_pk_mul_f32 v[28:29], v[28:29], v[202:203]
	v_pk_mul_f32 v[26:27], v[26:27], v[200:201]
	s_nop 0
	s_waitcnt lgkmcnt(2)
	v_mfma_f32_16x16x32_bf16 v[26:29], v[184:187], v[62:65], v[26:29]
	s_waitcnt lgkmcnt(1)
	v_mfma_f32_16x16x32_bf16 v[26:29], v[188:191], v[58:61], v[26:29]
	s_waitcnt lgkmcnt(0)
	v_pk_mul_f32 v[32:33], v[32:33], v[206:207]
	v_pk_mul_f32 v[30:31], v[30:31], v[204:205]
	ds_read_b128 v[178:181], v163 offset:16128
	s_waitcnt lgkmcnt(0)
	v_mfma_f32_16x16x32_bf16 v[30:33], v[178:181], v[62:65], v[30:33]
	ds_read_b128 v[62:65], v163 offset:16192
	s_waitcnt lgkmcnt(0)
	s_barrier
	v_mfma_f32_16x16x32_bf16 v[30:33], v[62:65], v[58:61], v[30:33]
	s_and_saveexec_b64 s[20:21], s[68:69]
	s_cbranch_execz .LBB0_875
	v_add_u32_e32 v1, 0, v142
	v_add_u32_e32 v1, 0x14400, v1
	ds_read_b128 v[58:61], v1
	ds_read_b128 v[62:65], v1 offset:16
	s_mov_b32 s0, 0xf800000
	s_waitcnt lgkmcnt(0)
	v_mov_b32_e32 v178, v58
	v_mov_b32_e32 v179, v62
	v_mov_b32_e32 v62, v59
	v_pk_add_f32 v[58:59], v[178:179], v[62:63]
	v_mov_b32_e32 v62, v60
	v_mov_b32_e32 v63, v64
	v_mov_b32_e32 v64, v61
	v_pk_add_f32 v[60:61], v[62:63], v[64:65]
	s_waitcnt vmcnt(0)
	v_lshlrev_b32_e32 v62, 16, v37
	v_pk_add_f32 v[58:59], v[58:59], v[60:61]
	v_and_b32_e32 v63, 0xffff0000, v37
	v_add_f32_e32 v1, v58, v59
	v_fmamk_f32 v1, v1, 0x3c000000, v222
	v_cmp_gt_f32_e32 vcc, s0, v1
	v_mul_f32_e32 v35, 0x4f800000, v1
	s_nop 0
	v_cndmask_b32_e32 v1, v1, v35, vcc
	v_sqrt_f32_e32 v35, v1
	s_nop 0
	v_add_u32_e32 v58, -1, v35
	v_fma_f32 v59, -v58, v35, v1
	v_cmp_ge_f32_e64 s[0:1], 0, v59
	v_add_u32_e32 v59, 1, v35
	s_nop 0
	v_cndmask_b32_e64 v58, v35, v58, s[0:1]
	v_fma_f32 v35, -v59, v35, v1
	v_cmp_lt_f32_e64 s[0:1], 0, v35
	s_nop 1
	v_cndmask_b32_e64 v35, v58, v59, s[0:1]
	v_mul_f32_e32 v58, 0x37800000, v35
	v_cndmask_b32_e32 v35, v35, v58, vcc
	v_cmp_class_f32_e32 vcc, v1, v223
	s_nop 1
	v_cndmask_b32_e32 v1, v35, v1, vcc
	v_div_scale_f32 v35, s[0:1], v1, v1, 1.0
	v_rcp_f32_e32 v58, v35
	s_movk_i32 s0, 0x3000
	v_fma_f32 v59, -v35, v58, 1.0
	v_fmac_f32_e32 v58, v59, v58
	v_div_scale_f32 v59, vcc, 1.0, v1, 1.0
	v_mul_f32_e32 v60, v59, v58
	v_fma_f32 v61, -v35, v60, v59
	v_fmac_f32_e32 v60, v61, v58
	v_fma_f32 v35, -v35, v60, v59
	v_div_fmas_f32 v35, v35, v58, v60
	v_div_fixup_f32 v58, v35, v1, 1.0
	v_pk_mul_f32 v[60:61], v[80:81], v[58:59] op_sel_hi:[1,0]
	v_pk_mul_f32 v[58:59], v[78:79], v[58:59] op_sel_hi:[1,0]
	v_pk_mul_f32 v[60:61], v[40:41], v[60:61]
	v_pk_mul_f32 v[58:59], v[38:39], v[58:59]
	v_pk_mul_f32 v[60:61], v[60:61], v[62:63]
	s_nop 0
	v_cvt_pk_bf16_f32 v37, v60, v61
	v_lshlrev_b32_e32 v60, 16, v36
	v_and_b32_e32 v61, 0xffff0000, v36
	v_pk_mul_f32 v[58:59], v[58:59], v[60:61]
	s_nop 0
	v_cvt_pk_bf16_f32 v36, v58, v59
	v_mad_u64_u32 v[58:59], s[0:1], v116, s0, v[100:101]
	v_mad_i32_i24 v59, s19, v230, v59
	global_store_dwordx2 v[58:59], v[36:37], off

.LBB0_1286:
	ds_read_b128 v[184:187], v144
	ds_read_b128 v[188:191], v144 offset:64
	ds_read_b128 v[192:195], v144 offset:128
	ds_read_b128 v[196:199], v144 offset:192
	ds_read_b32 v200, v128 offset:17408
	ds_read_b32 v204, v129 offset:17408
	ds_read_b32 v208, v130 offset:17408
	ds_read_b32 v212, v131 offset:17408
	s_lshl_b32 s59, s59, 6
	s_sub_i32 s6, s15, s59
	s_min_i32 s70, s6, 64
	s_waitcnt lgkmcnt(8)
	s_waitcnt lgkmcnt(7)
	v_mfma_f32_16x16x32_bf16 v[40:43], v[184:187], v[2:5], 0
	v_mfma_f32_16x16x32_bf16 v[36:39], v[184:187], v[6:9], 0
	ds_read_b128 v[184:187], v144 offset:4352
	s_waitcnt lgkmcnt(7)
	v_mfma_f32_16x16x32_bf16 v[40:43], v[188:191], v[10:13], v[40:43]
	v_mfma_f32_16x16x32_bf16 v[36:39], v[188:191], v[14:17], v[36:39]
	ds_read_b128 v[188:191], v144 offset:4416
	s_waitcnt lgkmcnt(7)
	v_mfma_f32_16x16x32_bf16 v[40:43], v[192:195], v[18:21], v[40:43]
	v_mfma_f32_16x16x32_bf16 v[36:39], v[192:195], v[22:25], v[36:39]
	ds_read_b128 v[192:195], v144 offset:4480
	s_nop 0
	s_waitcnt lgkmcnt(7)
	v_mfma_f32_16x16x32_bf16 v[40:43], v[196:199], v[26:29], v[40:43]
	s_nop 7
	v_add_f32_e32 v1, v52, v40
	v_mul_f32_e32 v1, 0xbfb8aa3b, v1
	v_exp_f32_e32 v1, v1
	v_mfma_f32_16x16x32_bf16 v[36:39], v[196:199], v[30:33], v[36:39]
	ds_read_b128 v[196:199], v144 offset:4544
	v_add_f32_e32 v1, 1.0, v1
	v_rcp_f32_e32 v1, v1
	s_nop 0
	v_mul_f32_e32 v1, v89, v1
	v_mul_f32_e32 v40, 0x3fb8aa3b, v1
	v_exp_f32_e32 v40, v40
	v_add_f32_e32 v174, v1, v1
	v_cmp_nlt_f32_e32 vcc, s33, v174
	s_and_saveexec_b64 s[6:7], vcc
	s_xor_b64 s[6:7], exec, s[6:7]
	v_fma_f32 v173, -v40, v40, 1.0
	s_andn2_saveexec_b64 s[6:7], s[6:7]
	v_fmamk_f32 v1, v174, 0x3d2aaaab, v225
	v_fma_f32 v1, v174, v1, 0.5
	v_fma_f32 v1, v174, v1, 1.0
	v_mul_f32_e64 v173, v1, -v174
	s_or_b64 exec, exec, s[6:7]
	v_add_f32_e32 v1, v53, v36
	v_mul_f32_e32 v1, 0xbfb8aa3b, v1
	v_exp_f32_e32 v1, v1
	v_max_f32_e32 v36, v173, v173
	v_max_f32_e32 v36, 0, v36
	v_sqrt_f32_e32 v36, v36
	v_add_f32_e32 v1, 1.0, v1
	v_rcp_f32_e32 v1, v1
	v_cmp_gt_i32_e32 vcc, s70, v92
	v_mul_f32_e32 v1, v1, v36
	s_waitcnt lgkmcnt(7)
	v_mul_f32_e32 v1, v200, v1
	ds_read_b32 v200, v132 offset:17408
	v_cndmask_b32_e32 v36, 1.0, v40, vcc
	v_cndmask_b32_e32 v1, 0, v1, vcc
	ds_write_b32 v128, v36 offset:50176
	v_add_u32_e32 v36, 0x14400, v128
	ds_write_b32 v36, v1
	v_add_f32_e32 v1, v52, v41
	v_mul_f32_e32 v1, 0xbfb8aa3b, v1
	v_exp_f32_e32 v1, v1
	s_nop 0
	v_add_f32_e32 v1, 1.0, v1
	v_rcp_f32_e32 v1, v1
	s_nop 0
	v_mul_f32_e32 v1, v89, v1
	v_mul_f32_e32 v36, 0x3fb8aa3b, v1
	v_exp_f32_e32 v36, v36
	v_add_f32_e32 v41, v1, v1
	v_cmp_nlt_f32_e32 vcc, s33, v41
	s_and_saveexec_b64 s[6:7], vcc
	s_xor_b64 s[6:7], exec, s[6:7]
	v_fma_f32 v40, -v36, v36, 1.0
	s_andn2_saveexec_b64 s[6:7], s[6:7]
	v_fmamk_f32 v1, v41, 0x3d2aaaab, v225
	v_fma_f32 v1, v41, v1, 0.5
	v_fma_f32 v1, v41, v1, 1.0
	v_mul_f32_e64 v40, v1, -v41
	s_or_b64 exec, exec, s[6:7]
	v_add_f32_e32 v1, v53, v37
	v_mul_f32_e32 v1, 0xbfb8aa3b, v1
	v_exp_f32_e32 v1, v1
	v_max_f32_e32 v37, v40, v40
	v_max_f32_e32 v37, 0, v37
	v_sqrt_f32_e32 v37, v37
	v_add_f32_e32 v1, 1.0, v1
	v_rcp_f32_e32 v1, v1
	v_cmp_gt_i32_e32 vcc, s70, v94
	v_mul_f32_e32 v1, v1, v37
	s_nop 0
	v_cndmask_b32_e32 v36, 1.0, v36, vcc
	ds_write_b32 v129, v36 offset:50176
	v_add_u32_e32 v36, 0x14400, v129
	s_waitcnt lgkmcnt(10)
	v_mul_f32_e32 v1, v204, v1
	ds_read_b32 v204, v133 offset:17408
	v_cndmask_b32_e32 v1, 0, v1, vcc
	ds_write_b32 v36, v1
	v_add_f32_e32 v1, v52, v42
	v_mul_f32_e32 v1, 0xbfb8aa3b, v1
	v_exp_f32_e32 v1, v1
	s_nop 0
	v_add_f32_e32 v1, 1.0, v1
	v_rcp_f32_e32 v1, v1
	s_nop 0
	v_mul_f32_e32 v1, v89, v1
	v_mul_f32_e32 v36, 0x3fb8aa3b, v1
	v_exp_f32_e32 v36, v36
	v_add_f32_e32 v40, v1, v1
	v_cmp_nlt_f32_e32 vcc, s33, v40
	s_and_saveexec_b64 s[6:7], vcc
	s_xor_b64 s[6:7], exec, s[6:7]
	v_fma_f32 v37, -v36, v36, 1.0
	s_andn2_saveexec_b64 s[6:7], s[6:7]
	v_fmamk_f32 v1, v40, 0x3d2aaaab, v225
	v_fma_f32 v1, v40, v1, 0.5
	v_fma_f32 v1, v40, v1, 1.0
	v_mul_f32_e64 v37, v1, -v40
	s_or_b64 exec, exec, s[6:7]
	v_add_f32_e32 v1, v53, v38
	v_mul_f32_e32 v1, 0xbfb8aa3b, v1
	v_exp_f32_e32 v1, v1
	v_max_f32_e32 v37, v37, v37
	v_max_f32_e32 v37, 0, v37
	v_sqrt_f32_e32 v37, v37
	v_add_f32_e32 v1, 1.0, v1
	v_rcp_f32_e32 v1, v1
	v_cmp_gt_i32_e32 vcc, s70, v95
	v_mul_f32_e32 v1, v1, v37
	s_nop 0
	v_cndmask_b32_e32 v36, 1.0, v36, vcc
	ds_write_b32 v130, v36 offset:50176
	v_add_u32_e32 v36, 0x14400, v130
	s_waitcnt lgkmcnt(12)
	v_mul_f32_e32 v1, v208, v1
	ds_read_b32 v208, v134 offset:17408
	v_cndmask_b32_e32 v1, 0, v1, vcc
	ds_write_b32 v36, v1
	v_add_f32_e32 v1, v52, v43
	v_mul_f32_e32 v1, 0xbfb8aa3b, v1
	v_exp_f32_e32 v1, v1
	s_nop 0
	v_add_f32_e32 v1, 1.0, v1
	v_rcp_f32_e32 v1, v1
	s_nop 0
	v_mul_f32_e32 v1, v89, v1
	v_mul_f32_e32 v36, 0x3fb8aa3b, v1
	v_exp_f32_e32 v36, v36
	v_add_f32_e32 v38, v1, v1
	v_cmp_nlt_f32_e32 vcc, s33, v38
	s_and_saveexec_b64 s[6:7], vcc
	s_xor_b64 s[6:7], exec, s[6:7]
	v_fma_f32 v37, -v36, v36, 1.0
	s_andn2_saveexec_b64 s[6:7], s[6:7]
	v_fmamk_f32 v1, v38, 0x3d2aaaab, v225
	v_fma_f32 v1, v38, v1, 0.5
	v_fma_f32 v1, v38, v1, 1.0
	v_mul_f32_e64 v37, v1, -v38
	s_or_b64 exec, exec, s[6:7]
	v_add_f32_e32 v1, v53, v39
	v_mul_f32_e32 v1, 0xbfb8aa3b, v1
	v_exp_f32_e32 v1, v1
	v_max_f32_e32 v37, v37, v37
	v_max_f32_e32 v37, 0, v37
	v_sqrt_f32_e32 v37, v37
	v_add_f32_e32 v1, 1.0, v1
	v_rcp_f32_e32 v1, v1
	v_cmp_gt_i32_e32 vcc, s70, v96
	v_mul_f32_e32 v1, v1, v37
	s_nop 0
	v_cndmask_b32_e32 v36, 1.0, v36, vcc
	ds_write_b32 v131, v36 offset:50176
	v_add_u32_e32 v36, 0x14400, v131
	s_waitcnt lgkmcnt(14)
	v_mul_f32_e32 v1, v212, v1
	ds_read_b32 v212, v135 offset:17408
	v_cndmask_b32_e32 v1, 0, v1, vcc
	ds_write_b32 v36, v1
	s_waitcnt lgkmcnt(15)
	v_mfma_f32_16x16x32_bf16 v[40:43], v[184:187], v[2:5], 0
	v_mfma_f32_16x16x32_bf16 v[36:39], v[184:187], v[6:9], 0
	ds_read_b128 v[184:187], v144 offset:8704
	s_waitcnt lgkmcnt(15)
	v_mfma_f32_16x16x32_bf16 v[40:43], v[188:191], v[10:13], v[40:43]
	v_mfma_f32_16x16x32_bf16 v[36:39], v[188:191], v[14:17], v[36:39]
	ds_read_b128 v[188:191], v144 offset:8768
	s_waitcnt lgkmcnt(15)
	v_mfma_f32_16x16x32_bf16 v[40:43], v[192:195], v[18:21], v[40:43]
	v_mfma_f32_16x16x32_bf16 v[36:39], v[192:195], v[22:25], v[36:39]
	ds_read_b128 v[192:195], v144 offset:8832
	s_nop 0
	s_waitcnt lgkmcnt(15)
	v_mfma_f32_16x16x32_bf16 v[40:43], v[196:199], v[26:29], v[40:43]
	s_nop 7
	v_add_f32_e32 v1, v52, v40
	v_mul_f32_e32 v1, 0xbfb8aa3b, v1
	v_exp_f32_e32 v1, v1
	v_mfma_f32_16x16x32_bf16 v[36:39], v[196:199], v[30:33], v[36:39]
	ds_read_b128 v[196:199], v144 offset:8896
	v_add_f32_e32 v1, 1.0, v1
	v_rcp_f32_e32 v1, v1
	s_nop 0
	v_mul_f32_e32 v1, v89, v1
	v_mul_f32_e32 v40, 0x3fb8aa3b, v1
	v_exp_f32_e32 v40, v40
	v_add_f32_e32 v174, v1, v1
	v_cmp_nlt_f32_e32 vcc, s33, v174
	s_and_saveexec_b64 s[6:7], vcc
	s_xor_b64 s[6:7], exec, s[6:7]
	v_fma_f32 v173, -v40, v40, 1.0
	s_andn2_saveexec_b64 s[6:7], s[6:7]
	v_fmamk_f32 v1, v174, 0x3d2aaaab, v225
	v_fma_f32 v1, v174, v1, 0.5
	v_fma_f32 v1, v174, v1, 1.0
	v_mul_f32_e64 v173, v1, -v174
	s_or_b64 exec, exec, s[6:7]
	v_add_f32_e32 v1, v53, v36
	v_mul_f32_e32 v1, 0xbfb8aa3b, v1
	v_exp_f32_e32 v1, v1
	v_max_f32_e32 v36, v173, v173
	v_max_f32_e32 v36, 0, v36
	v_sqrt_f32_e32 v36, v36
	v_add_f32_e32 v1, 1.0, v1
	v_rcp_f32_e32 v1, v1
	v_cmp_gt_i32_e32 vcc, s70, v97
	v_mul_f32_e32 v1, v1, v36
	s_waitcnt lgkmcnt(15)
	v_mul_f32_e32 v1, v200, v1
	ds_read_b32 v200, v136 offset:17408
	v_cndmask_b32_e32 v36, 1.0, v40, vcc
	v_cndmask_b32_e32 v1, 0, v1, vcc
	ds_write_b32 v132, v36 offset:50176
	v_add_u32_e32 v36, 0x14400, v132
	ds_write_b32 v36, v1
	v_add_f32_e32 v1, v52, v41
	v_mul_f32_e32 v1, 0xbfb8aa3b, v1
	v_exp_f32_e32 v1, v1
	s_nop 0
	v_add_f32_e32 v1, 1.0, v1
	v_rcp_f32_e32 v1, v1
	s_nop 0
	v_mul_f32_e32 v1, v89, v1
	v_mul_f32_e32 v36, 0x3fb8aa3b, v1
	v_exp_f32_e32 v36, v36
	v_add_f32_e32 v41, v1, v1
	v_cmp_nlt_f32_e32 vcc, s33, v41
	s_and_saveexec_b64 s[6:7], vcc
	s_xor_b64 s[6:7], exec, s[6:7]
	v_fma_f32 v40, -v36, v36, 1.0
	s_andn2_saveexec_b64 s[6:7], s[6:7]
	v_fmamk_f32 v1, v41, 0x3d2aaaab, v225
	v_fma_f32 v1, v41, v1, 0.5
	v_fma_f32 v1, v41, v1, 1.0
	v_mul_f32_e64 v40, v1, -v41
	s_or_b64 exec, exec, s[6:7]
	v_add_f32_e32 v1, v53, v37
	v_mul_f32_e32 v1, 0xbfb8aa3b, v1
	v_exp_f32_e32 v1, v1
	v_max_f32_e32 v37, v40, v40
	v_max_f32_e32 v37, 0, v37
	v_sqrt_f32_e32 v37, v37
	v_add_f32_e32 v1, 1.0, v1
	v_rcp_f32_e32 v1, v1
	v_cmp_gt_i32_e32 vcc, s70, v99
	v_mul_f32_e32 v1, v1, v37
	s_nop 0
	v_cndmask_b32_e32 v36, 1.0, v36, vcc
	ds_write_b32 v133, v36 offset:50176
	v_add_u32_e32 v36, 0x14400, v133
	s_waitcnt lgkmcnt(15)
	v_mul_f32_e32 v1, v204, v1
	ds_read_b32 v204, v137 offset:17408
	v_cndmask_b32_e32 v1, 0, v1, vcc
	ds_write_b32 v36, v1
	v_add_f32_e32 v1, v52, v42
	v_mul_f32_e32 v1, 0xbfb8aa3b, v1
	v_exp_f32_e32 v1, v1
	s_nop 0
	v_add_f32_e32 v1, 1.0, v1
	v_rcp_f32_e32 v1, v1
	s_nop 0
	v_mul_f32_e32 v1, v89, v1
	v_mul_f32_e32 v36, 0x3fb8aa3b, v1
	v_exp_f32_e32 v36, v36
	v_add_f32_e32 v40, v1, v1
	v_cmp_nlt_f32_e32 vcc, s33, v40
	s_and_saveexec_b64 s[6:7], vcc
	s_xor_b64 s[6:7], exec, s[6:7]
	v_fma_f32 v37, -v36, v36, 1.0
	s_andn2_saveexec_b64 s[6:7], s[6:7]
	v_fmamk_f32 v1, v40, 0x3d2aaaab, v225
	v_fma_f32 v1, v40, v1, 0.5
	v_fma_f32 v1, v40, v1, 1.0
	v_mul_f32_e64 v37, v1, -v40
	s_or_b64 exec, exec, s[6:7]
	v_add_f32_e32 v1, v53, v38
	v_mul_f32_e32 v1, 0xbfb8aa3b, v1
	v_exp_f32_e32 v1, v1
	v_max_f32_e32 v37, v37, v37
	v_max_f32_e32 v37, 0, v37
	v_sqrt_f32_e32 v37, v37
	v_add_f32_e32 v1, 1.0, v1
	v_rcp_f32_e32 v1, v1
	v_cmp_gt_i32_e32 vcc, s70, v100
	v_mul_f32_e32 v1, v1, v37
	s_nop 0
	v_cndmask_b32_e32 v36, 1.0, v36, vcc
	ds_write_b32 v134, v36 offset:50176
	v_add_u32_e32 v36, 0x14400, v134
	s_waitcnt lgkmcnt(15)
	v_mul_f32_e32 v1, v208, v1
	ds_read_b32 v208, v138 offset:17408
	v_cndmask_b32_e32 v1, 0, v1, vcc
	ds_write_b32 v36, v1
	v_add_f32_e32 v1, v52, v43
	v_mul_f32_e32 v1, 0xbfb8aa3b, v1
	v_exp_f32_e32 v1, v1
	s_nop 0
	v_add_f32_e32 v1, 1.0, v1
	v_rcp_f32_e32 v1, v1
	s_nop 0
	v_mul_f32_e32 v1, v89, v1
	v_mul_f32_e32 v36, 0x3fb8aa3b, v1
	v_exp_f32_e32 v36, v36
	v_add_f32_e32 v38, v1, v1
	v_cmp_nlt_f32_e32 vcc, s33, v38
	s_and_saveexec_b64 s[6:7], vcc
	s_xor_b64 s[6:7], exec, s[6:7]
	v_fma_f32 v37, -v36, v36, 1.0
	s_andn2_saveexec_b64 s[6:7], s[6:7]
	v_fmamk_f32 v1, v38, 0x3d2aaaab, v225
	v_fma_f32 v1, v38, v1, 0.5
	v_fma_f32 v1, v38, v1, 1.0
	v_mul_f32_e64 v37, v1, -v38
	s_or_b64 exec, exec, s[6:7]
	v_add_f32_e32 v1, v53, v39
	v_mul_f32_e32 v1, 0xbfb8aa3b, v1
	v_exp_f32_e32 v1, v1
	v_max_f32_e32 v37, v37, v37
	v_max_f32_e32 v37, 0, v37
	v_sqrt_f32_e32 v37, v37
	v_add_f32_e32 v1, 1.0, v1
	v_rcp_f32_e32 v1, v1
	v_cmp_gt_i32_e32 vcc, s70, v101
	v_mul_f32_e32 v1, v1, v37
	s_nop 0
	v_cndmask_b32_e32 v36, 1.0, v36, vcc
	ds_write_b32 v135, v36 offset:50176
	v_add_u32_e32 v36, 0x14400, v135
	s_waitcnt lgkmcnt(15)
	v_mul_f32_e32 v1, v212, v1
	ds_read_b32 v212, v139 offset:17408
	v_cndmask_b32_e32 v1, 0, v1, vcc
	ds_write_b32 v36, v1
	s_waitcnt lgkmcnt(15)
	v_mfma_f32_16x16x32_bf16 v[40:43], v[184:187], v[2:5], 0
	v_mfma_f32_16x16x32_bf16 v[36:39], v[184:187], v[6:9], 0
	ds_read_b128 v[184:187], v144 offset:13056
	s_waitcnt lgkmcnt(15)
	v_mfma_f32_16x16x32_bf16 v[40:43], v[188:191], v[10:13], v[40:43]
	v_mfma_f32_16x16x32_bf16 v[36:39], v[188:191], v[14:17], v[36:39]
	ds_read_b128 v[188:191], v144 offset:13120
	s_waitcnt lgkmcnt(15)
	v_mfma_f32_16x16x32_bf16 v[40:43], v[192:195], v[18:21], v[40:43]
	v_mfma_f32_16x16x32_bf16 v[36:39], v[192:195], v[22:25], v[36:39]
	ds_read_b128 v[192:195], v144 offset:13184
	s_nop 0
	s_waitcnt lgkmcnt(15)
	v_mfma_f32_16x16x32_bf16 v[40:43], v[196:199], v[26:29], v[40:43]
	s_nop 7
	v_add_f32_e32 v1, v52, v40
	v_mul_f32_e32 v1, 0xbfb8aa3b, v1
	v_exp_f32_e32 v1, v1
	v_mfma_f32_16x16x32_bf16 v[36:39], v[196:199], v[30:33], v[36:39]
	v_add_f32_e32 v1, 1.0, v1
	v_rcp_f32_e32 v1, v1
	s_nop 0
	v_mul_f32_e32 v1, v89, v1
	v_mul_f32_e32 v40, 0x3fb8aa3b, v1
	v_exp_f32_e32 v40, v40
	v_add_f32_e32 v174, v1, v1
	v_cmp_nlt_f32_e32 vcc, s33, v174
	s_and_saveexec_b64 s[6:7], vcc
	s_xor_b64 s[6:7], exec, s[6:7]
	v_fma_f32 v173, -v40, v40, 1.0
	s_andn2_saveexec_b64 s[6:7], s[6:7]
	v_fmamk_f32 v1, v174, 0x3d2aaaab, v225
	v_fma_f32 v1, v174, v1, 0.5
	v_fma_f32 v1, v174, v1, 1.0
	v_mul_f32_e64 v173, v1, -v174
	s_or_b64 exec, exec, s[6:7]
	v_add_f32_e32 v1, v53, v36
	v_mul_f32_e32 v1, 0xbfb8aa3b, v1
	v_exp_f32_e32 v1, v1
	v_max_f32_e32 v36, v173, v173
	v_max_f32_e32 v36, 0, v36
	v_sqrt_f32_e32 v36, v36
	v_add_f32_e32 v1, 1.0, v1
	v_rcp_f32_e32 v1, v1
	v_cmp_gt_i32_e32 vcc, s70, v102
	v_mul_f32_e32 v1, v1, v36
	s_waitcnt lgkmcnt(14)
	v_mul_f32_e32 v1, v200, v1
	v_cndmask_b32_e32 v36, 1.0, v40, vcc
	v_cndmask_b32_e32 v1, 0, v1, vcc
	ds_write_b32 v136, v36 offset:50176
	v_add_u32_e32 v36, 0x14400, v136
	ds_write_b32 v36, v1
	v_add_f32_e32 v1, v52, v41
	v_mul_f32_e32 v1, 0xbfb8aa3b, v1
	v_exp_f32_e32 v1, v1
	s_nop 0
	v_add_f32_e32 v1, 1.0, v1
	v_rcp_f32_e32 v1, v1
	s_nop 0
	v_mul_f32_e32 v1, v89, v1
	v_mul_f32_e32 v36, 0x3fb8aa3b, v1
	v_exp_f32_e32 v36, v36
	v_add_f32_e32 v41, v1, v1
	v_cmp_nlt_f32_e32 vcc, s33, v41
	s_and_saveexec_b64 s[6:7], vcc
	s_xor_b64 s[6:7], exec, s[6:7]
	v_fma_f32 v40, -v36, v36, 1.0
	s_andn2_saveexec_b64 s[6:7], s[6:7]
	v_fmamk_f32 v1, v41, 0x3d2aaaab, v225
	v_fma_f32 v1, v41, v1, 0.5
	v_fma_f32 v1, v41, v1, 1.0
	v_mul_f32_e64 v40, v1, -v41
	s_or_b64 exec, exec, s[6:7]
	v_add_f32_e32 v1, v53, v37
	v_mul_f32_e32 v1, 0xbfb8aa3b, v1
	v_exp_f32_e32 v1, v1
	v_max_f32_e32 v37, v40, v40
	v_max_f32_e32 v37, 0, v37
	v_sqrt_f32_e32 v37, v37
	v_add_f32_e32 v1, 1.0, v1
	v_rcp_f32_e32 v1, v1
	v_cmp_gt_i32_e32 vcc, s70, v103
	v_mul_f32_e32 v1, v1, v37
	s_nop 0
	v_cndmask_b32_e32 v36, 1.0, v36, vcc
	ds_write_b32 v137, v36 offset:50176
	v_add_u32_e32 v36, 0x14400, v137
	s_waitcnt lgkmcnt(13)
	v_mul_f32_e32 v1, v204, v1
	v_cndmask_b32_e32 v1, 0, v1, vcc
	ds_write_b32 v36, v1
	v_add_f32_e32 v1, v52, v42
	v_mul_f32_e32 v1, 0xbfb8aa3b, v1
	v_exp_f32_e32 v1, v1
	s_nop 0
	v_add_f32_e32 v1, 1.0, v1
	v_rcp_f32_e32 v1, v1
	s_nop 0
	v_mul_f32_e32 v1, v89, v1
	v_mul_f32_e32 v36, 0x3fb8aa3b, v1
	v_exp_f32_e32 v36, v36
	v_add_f32_e32 v40, v1, v1
	v_cmp_nlt_f32_e32 vcc, s33, v40
	s_and_saveexec_b64 s[6:7], vcc
	s_xor_b64 s[6:7], exec, s[6:7]
	v_fma_f32 v37, -v36, v36, 1.0
	s_andn2_saveexec_b64 s[6:7], s[6:7]
	v_fmamk_f32 v1, v40, 0x3d2aaaab, v225
	v_fma_f32 v1, v40, v1, 0.5
	v_fma_f32 v1, v40, v1, 1.0
	v_mul_f32_e64 v37, v1, -v40
	s_or_b64 exec, exec, s[6:7]
	v_add_f32_e32 v1, v53, v38
	v_mul_f32_e32 v1, 0xbfb8aa3b, v1
	v_exp_f32_e32 v1, v1
	v_max_f32_e32 v37, v37, v37
	v_max_f32_e32 v37, 0, v37
	v_sqrt_f32_e32 v37, v37
	v_add_f32_e32 v1, 1.0, v1
	v_rcp_f32_e32 v1, v1
	v_cmp_gt_i32_e32 vcc, s70, v104
	v_mul_f32_e32 v1, v1, v37
	s_nop 0
	v_cndmask_b32_e32 v36, 1.0, v36, vcc
	ds_write_b32 v138, v36 offset:50176
	v_add_u32_e32 v36, 0x14400, v138
	s_waitcnt lgkmcnt(12)
	v_mul_f32_e32 v1, v208, v1
	v_cndmask_b32_e32 v1, 0, v1, vcc
	ds_write_b32 v36, v1
	v_add_f32_e32 v1, v52, v43
	v_mul_f32_e32 v1, 0xbfb8aa3b, v1
	v_exp_f32_e32 v1, v1
	s_nop 0
	v_add_f32_e32 v1, 1.0, v1
	v_rcp_f32_e32 v1, v1
	s_nop 0
	v_mul_f32_e32 v1, v89, v1
	v_mul_f32_e32 v36, 0x3fb8aa3b, v1
	v_exp_f32_e32 v36, v36
	v_add_f32_e32 v38, v1, v1
	v_cmp_nlt_f32_e32 vcc, s33, v38
	s_and_saveexec_b64 s[6:7], vcc
	s_xor_b64 s[6:7], exec, s[6:7]
	v_fma_f32 v37, -v36, v36, 1.0
	s_andn2_saveexec_b64 s[6:7], s[6:7]
	v_fmamk_f32 v1, v38, 0x3d2aaaab, v225
	v_fma_f32 v1, v38, v1, 0.5
	v_fma_f32 v1, v38, v1, 1.0
	v_mul_f32_e64 v37, v1, -v38
	s_or_b64 exec, exec, s[6:7]
	v_add_f32_e32 v1, v53, v39
	v_mul_f32_e32 v1, 0xbfb8aa3b, v1
	v_exp_f32_e32 v1, v1
	v_max_f32_e32 v37, v37, v37
	v_max_f32_e32 v37, 0, v37
	v_sqrt_f32_e32 v37, v37
	v_add_f32_e32 v1, 1.0, v1
	v_rcp_f32_e32 v1, v1
	v_cmp_gt_i32_e32 vcc, s70, v105
	v_mul_f32_e32 v1, v1, v37
	s_nop 0
	v_cndmask_b32_e32 v36, 1.0, v36, vcc
	ds_write_b32 v139, v36 offset:50176
	v_add_u32_e32 v36, 0x14400, v139
	s_waitcnt lgkmcnt(11)
	v_mul_f32_e32 v1, v212, v1
	v_cndmask_b32_e32 v1, 0, v1, vcc
	ds_write_b32 v36, v1
	s_waitcnt lgkmcnt(10)
	v_mfma_f32_16x16x32_bf16 v[40:43], v[184:187], v[2:5], 0
	v_mfma_f32_16x16x32_bf16 v[36:39], v[184:187], v[6:9], 0
	s_waitcnt lgkmcnt(9)
	v_mfma_f32_16x16x32_bf16 v[40:43], v[188:191], v[10:13], v[40:43]
	v_mfma_f32_16x16x32_bf16 v[36:39], v[188:191], v[14:17], v[36:39]
	s_waitcnt lgkmcnt(8)
	v_mfma_f32_16x16x32_bf16 v[40:43], v[192:195], v[18:21], v[40:43]
	v_mfma_f32_16x16x32_bf16 v[36:39], v[192:195], v[22:25], v[36:39]
	ds_read_b32 v184, v140 offset:17408
	ds_read_b32 v188, v141 offset:17408
	ds_read_b32 v192, v142 offset:17408
	ds_read_b128 v[174:177], v144 offset:13248
	s_waitcnt lgkmcnt(0)
	v_mfma_f32_16x16x32_bf16 v[40:43], v[174:177], v[26:29], v[40:43]
	s_nop 7
	v_add_f32_e32 v1, v52, v40
	v_mul_f32_e32 v1, 0xbfb8aa3b, v1
	v_exp_f32_e32 v1, v1
	v_mfma_f32_16x16x32_bf16 v[36:39], v[174:177], v[30:33], v[36:39]
	v_add_f32_e32 v1, 1.0, v1
	v_rcp_f32_e32 v1, v1
	s_nop 0
	v_mul_f32_e32 v1, v89, v1
	v_mul_f32_e32 v40, 0x3fb8aa3b, v1
	v_exp_f32_e32 v40, v40
	v_add_f32_e32 v174, v1, v1
	v_cmp_nlt_f32_e32 vcc, s33, v174
	s_and_saveexec_b64 s[6:7], vcc
	s_xor_b64 s[6:7], exec, s[6:7]
	v_fma_f32 v173, -v40, v40, 1.0
	s_andn2_saveexec_b64 s[6:7], s[6:7]
	v_fmamk_f32 v1, v174, 0x3d2aaaab, v225
	v_fma_f32 v1, v174, v1, 0.5
	v_fma_f32 v1, v174, v1, 1.0
	v_mul_f32_e64 v173, v1, -v174
	s_or_b64 exec, exec, s[6:7]
	v_add_f32_e32 v1, v53, v36
	v_mul_f32_e32 v1, 0xbfb8aa3b, v1
	v_exp_f32_e32 v1, v1
	v_max_f32_e32 v36, v173, v173
	v_max_f32_e32 v36, 0, v36
	v_sqrt_f32_e32 v36, v36
	v_add_f32_e32 v1, 1.0, v1
	v_rcp_f32_e32 v1, v1
	v_cmp_gt_i32_e32 vcc, s70, v106
	v_mul_f32_e32 v1, v1, v36
	v_mul_f32_e32 v1, v184, v1
	v_cndmask_b32_e32 v36, 1.0, v40, vcc
	v_cndmask_b32_e32 v1, 0, v1, vcc
	ds_write_b32 v140, v36 offset:50176
	v_add_u32_e32 v36, 0x14400, v140
	ds_write_b32 v36, v1
	v_add_f32_e32 v1, v52, v41
	v_mul_f32_e32 v1, 0xbfb8aa3b, v1
	v_exp_f32_e32 v1, v1
	s_nop 0
	v_add_f32_e32 v1, 1.0, v1
	v_rcp_f32_e32 v1, v1
	s_nop 0
	v_mul_f32_e32 v1, v89, v1
	v_mul_f32_e32 v36, 0x3fb8aa3b, v1
	v_exp_f32_e32 v36, v36
	v_add_f32_e32 v41, v1, v1
	v_cmp_nlt_f32_e32 vcc, s33, v41
	s_and_saveexec_b64 s[6:7], vcc
	s_xor_b64 s[6:7], exec, s[6:7]
	v_fma_f32 v40, -v36, v36, 1.0
	s_andn2_saveexec_b64 s[6:7], s[6:7]
	v_fmamk_f32 v1, v41, 0x3d2aaaab, v225
	v_fma_f32 v1, v41, v1, 0.5
	v_fma_f32 v1, v41, v1, 1.0
	v_mul_f32_e64 v40, v1, -v41
	s_or_b64 exec, exec, s[6:7]
	v_add_f32_e32 v1, v53, v37
	v_mul_f32_e32 v1, 0xbfb8aa3b, v1
	v_exp_f32_e32 v1, v1
	v_max_f32_e32 v37, v40, v40
	v_max_f32_e32 v37, 0, v37
	v_sqrt_f32_e32 v37, v37
	v_add_f32_e32 v1, 1.0, v1
	v_rcp_f32_e32 v1, v1
	v_cmp_gt_i32_e32 vcc, s70, v107
	v_mul_f32_e32 v1, v1, v37
	s_nop 0
	v_cndmask_b32_e32 v36, 1.0, v36, vcc
	ds_write_b32 v141, v36 offset:50176
	v_add_u32_e32 v36, 0x14400, v141
	v_mul_f32_e32 v1, v188, v1
	v_cndmask_b32_e32 v1, 0, v1, vcc
	ds_write_b32 v36, v1
	v_add_f32_e32 v1, v52, v42
	v_mul_f32_e32 v1, 0xbfb8aa3b, v1
	v_exp_f32_e32 v1, v1
	s_nop 0
	v_add_f32_e32 v1, 1.0, v1
	v_rcp_f32_e32 v1, v1
	s_nop 0
	v_mul_f32_e32 v1, v89, v1
	v_mul_f32_e32 v36, 0x3fb8aa3b, v1
	v_exp_f32_e32 v36, v36
	v_add_f32_e32 v40, v1, v1
	v_cmp_nlt_f32_e32 vcc, s33, v40
	s_and_saveexec_b64 s[6:7], vcc
	s_xor_b64 s[6:7], exec, s[6:7]
	v_fma_f32 v37, -v36, v36, 1.0
	s_andn2_saveexec_b64 s[6:7], s[6:7]
	v_fmamk_f32 v1, v40, 0x3d2aaaab, v225
	v_fma_f32 v1, v40, v1, 0.5
	v_fma_f32 v1, v40, v1, 1.0
	v_mul_f32_e64 v37, v1, -v40
	s_or_b64 exec, exec, s[6:7]
	v_add_f32_e32 v1, v53, v38
	v_mul_f32_e32 v1, 0xbfb8aa3b, v1
	v_exp_f32_e32 v1, v1
	v_max_f32_e32 v37, v37, v37
	v_max_f32_e32 v37, 0, v37
	v_sqrt_f32_e32 v37, v37
	v_add_f32_e32 v1, 1.0, v1
	v_rcp_f32_e32 v1, v1
	v_cmp_gt_i32_e32 vcc, s70, v108
	v_mul_f32_e32 v1, v1, v37
	s_nop 0
	v_cndmask_b32_e32 v36, 1.0, v36, vcc
	ds_write_b32 v142, v36 offset:50176
	v_add_u32_e32 v36, 0x14400, v142
	v_mul_f32_e32 v1, v192, v1
	v_cndmask_b32_e32 v1, 0, v1, vcc
	ds_write_b32 v36, v1
	v_add_f32_e32 v1, v52, v43
	v_mul_f32_e32 v1, 0xbfb8aa3b, v1
	v_exp_f32_e32 v1, v1
	s_nop 0
	v_add_f32_e32 v1, 1.0, v1
	v_rcp_f32_e32 v1, v1
	s_nop 0
	v_mul_f32_e32 v1, v89, v1
	v_mul_f32_e32 v36, 0x3fb8aa3b, v1
	v_exp_f32_e32 v36, v36
	v_add_f32_e32 v38, v1, v1
	v_cmp_nlt_f32_e32 vcc, s33, v38
	s_and_saveexec_b64 s[6:7], vcc
	s_xor_b64 s[6:7], exec, s[6:7]
	v_fma_f32 v37, -v36, v36, 1.0
	s_andn2_saveexec_b64 s[6:7], s[6:7]
	v_fmamk_f32 v1, v38, 0x3d2aaaab, v225
	v_fma_f32 v1, v38, v1, 0.5
	v_fma_f32 v1, v38, v1, 1.0
	v_mul_f32_e64 v37, v1, -v38
	s_or_b64 exec, exec, s[6:7]
	v_add_f32_e32 v1, v53, v39
	v_mul_f32_e32 v1, 0xbfb8aa3b, v1
	v_exp_f32_e32 v1, v1
	v_max_f32_e32 v37, v37, v37
	v_max_f32_e32 v37, 0, v37
	v_sqrt_f32_e32 v37, v37
	v_add_f32_e32 v1, 1.0, v1
	v_rcp_f32_e32 v1, v1
	v_cmp_gt_i32_e32 vcc, s70, v109
	v_mul_f32_e32 v1, v1, v37
	ds_read_b32 v37, v143 offset:17408
	v_cndmask_b32_e32 v36, 1.0, v36, vcc
	ds_write_b32 v143, v36 offset:50176
	v_add_u32_e32 v36, 0x14400, v143
	s_waitcnt lgkmcnt(1)
	v_mul_f32_e32 v1, v37, v1
	v_cndmask_b32_e32 v1, 0, v1, vcc
	ds_write_b32 v36, v1
	s_waitcnt lgkmcnt(0)
	s_barrier
	s_and_saveexec_b64 s[6:7], s[36:37]
	s_cbranch_execz .LBB0_1353
	s_mov_b32 s43, 0
